# v11 + LN reductions xor1/2/4/8 via DPP instead of ds_bpermute; memattn q-prefetch waits moved off the MFMA head; EpiGate sigmoids issued in pairs
# baseline (speedup 1.0000x reference)
; __device__ __forceinline__ unsigned cvt_pk_bf16(float lo, float hi) { unsigned r; asm volatile("v_cvt_pk_bf16_f32 %0, %1, %2" : "=v"(r) : "v"(lo), "v"(hi)); return r; }
; __device__ __forceinline__ float fsigmoid(float x) { return __builtin_amdgcn_rcpf(1.f + __expf(-x)); }
;     __device__ __forceinline__ void operator()(const f32x4 (&acc)[2][2][4][2], const Unit& u, int wr, int wc, int fr, int fq) const {
;         const int br = u.pn >> 2, row0 = u.pm * BM + wr * 64 + fr, col0 = (u.pn & 3) * BM + wc * 32 + 8 * fq;
; #pragma unroll
;         for (int bj = 0; bj < 2; ++bj) { const f32x4 b0 = *(const f32x4*)(bg + br * 1024 + col0 + bj * HALF), b1 = *(const f32x4*)(bg + br * 1024 + col0 + bj * HALF + 4);
; #pragma unroll
;             for (int ai = 0; ai < 2; ++ai)
; #pragma unroll
;                 for (int m = 0; m < 4; ++m) { bf16_t* pm_ = G + (size_t)(row0 + ai * HALF + m * 16) * 3072 + col0 + bj * HALF;
;                     const u32x4 pv = *(const u32x4*)(pm_ + br * 1024); u32x4 mv = (u32x4){0u, 0u, 0u, 0u}; if (br) mv = *(const u32x4*)pm_;
;                     const f32x4 v0 = acc[ai][bj][m][0] + b0, v1 = acc[ai][bj][m][1] + b1;
;                     u32x4 w;
;                     w.x = cvt_pk_bf16(bf_lo(mv.x) + fsigmoid(v0[0]) * bf_lo(pv.x), bf_hi(mv.x) + fsigmoid(v0[1]) * bf_hi(pv.x));
;                     w.y = cvt_pk_bf16(bf_lo(mv.y) + fsigmoid(v0[2]) * bf_lo(pv.y), bf_hi(mv.y) + fsigmoid(v0[3]) * bf_hi(pv.y));
;                     w.z = cvt_pk_bf16(bf_lo(mv.z) + fsigmoid(v1[0]) * bf_lo(pv.z), bf_hi(mv.z) + fsigmoid(v1[1]) * bf_hi(pv.z));
;                     w.w = cvt_pk_bf16(bf_lo(mv.w) + fsigmoid(v1[2]) * bf_lo(pv.w), bf_hi(mv.w) + fsigmoid(v1[3]) * bf_hi(pv.w));
;                     *(u32x4*)pm_ = w; } }
.LBB0_278:
	s_lshl_b32 s9, s38, 8
	s_and_b32 s48, s9, 0xfffffc00
	s_and_b32 s13, s9, 0x300
	s_cmp_gt_u32 s38, 3
	s_cselect_b32 s50, -1, 0
	v_lshl_add_u32 v246, s46, 8, v1
	s_ashr_i32 s49, s48, 31
	s_lshl_b64 s[46:47], s[48:49], 2
	s_add_u32 s46, s61, s46
	s_addc_u32 s47, s62, s47
	v_or_b32_e32 v247, s13, v165
	v_mul_lo_u32 v248, v246, s96
	v_lshl_add_u32 v248, v247, 1, v248
	s_lshl_b32 s51, s48, 1
	v_add_u32_e32 v249, s51, v248
	v_lshlrev_b32_e32 v247, 2, v247
	global_load_dwordx4 v[90:93], v247, s[46:47]
	global_load_dwordx4 v[94:97], v247, s[46:47] offset:16
	global_load_dwordx4 v[138:141], v247, s[46:47] offset:512
	global_load_dwordx4 v[142:145], v247, s[46:47] offset:528
	global_load_dwordx4 v[182:185], v249, s[90:91]
	global_load_dwordx4 v[214:217], v248, s[90:91]
	v_add_u32_e32 v147, 0x18000, v249
	global_load_dwordx4 v[198:201], v147, s[90:91]
	v_add_u32_e32 v147, 0x18000, v248
	global_load_dwordx4 v[218:221], v147, s[90:91]
	v_add_u32_e32 v147, 0x30000, v249
	global_load_dwordx4 v[202:205], v147, s[90:91]
	v_add_u32_e32 v147, 0x30000, v248
	global_load_dwordx4 v[222:225], v147, s[90:91]
	v_add_u32_e32 v147, 0x48000, v249
	global_load_dwordx4 v[206:209], v147, s[90:91]
	v_add_u32_e32 v147, 0x48000, v248
	global_load_dwordx4 v[226:229], v147, s[90:91]
	v_add_u32_e32 v147, 0xc0000, v249
	global_load_dwordx4 v[210:213], v147, s[90:91]
	v_add_u32_e32 v147, 0xc0000, v248
	global_load_dwordx4 v[236:239], v147, s[90:91]
	s_waitcnt vmcnt(8)
	v_pk_add_f32 v[134:135], v[134:135], v[90:91]
	v_pk_add_f32 v[136:137], v[136:137], v[92:93]
	v_pk_add_f32 v[130:131], v[130:131], v[94:95]
	v_pk_add_f32 v[132:133], v[132:133], v[96:97]
	v_mul_f32_e32 v134, 0xbfb8aa3b, v134
	v_mul_f32_e32 v135, 0xbfb8aa3b, v135
	v_exp_f32_e32 v134, v134
	v_exp_f32_e32 v135, v135
	v_add_f32_e32 v134, 1.0, v134
	v_add_f32_e32 v135, 1.0, v135
	v_rcp_f32_e32 v134, v134
	v_rcp_f32_e32 v135, v135
	v_mul_f32_e32 v136, 0xbfb8aa3b, v136
	v_mul_f32_e32 v137, 0xbfb8aa3b, v137
	v_exp_f32_e32 v136, v136
	v_exp_f32_e32 v137, v137
	v_add_f32_e32 v136, 1.0, v136
	v_add_f32_e32 v137, 1.0, v137
	v_rcp_f32_e32 v136, v136
	v_rcp_f32_e32 v137, v137
	v_mul_f32_e32 v130, 0xbfb8aa3b, v130
	v_mul_f32_e32 v131, 0xbfb8aa3b, v131
	v_exp_f32_e32 v130, v130
	v_exp_f32_e32 v131, v131
	v_add_f32_e32 v130, 1.0, v130
	v_add_f32_e32 v131, 1.0, v131
	v_rcp_f32_e32 v130, v130
	v_rcp_f32_e32 v131, v131
	v_mul_f32_e32 v132, 0xbfb8aa3b, v132
	v_mul_f32_e32 v133, 0xbfb8aa3b, v133
	v_exp_f32_e32 v132, v132
	v_exp_f32_e32 v133, v133
	v_add_f32_e32 v132, 1.0, v132
	v_add_f32_e32 v133, 1.0, v133
	v_rcp_f32_e32 v132, v132
	v_rcp_f32_e32 v133, v133
	v_and_b32_e32 v214, s50, v214
	v_and_b32_e32 v215, s50, v215
	v_and_b32_e32 v216, s50, v216
	v_and_b32_e32 v217, s50, v217
	v_lshlrev_b32_e32 v150, 16, v182
	v_and_b32_e32 v182, 0xffff0000, v182
	v_lshlrev_b32_e32 v151, 16, v214
	v_and_b32_e32 v214, 0xffff0000, v214
	v_lshlrev_b32_e32 v152, 16, v183
	v_and_b32_e32 v183, 0xffff0000, v183
	v_lshlrev_b32_e32 v153, 16, v215
	v_and_b32_e32 v215, 0xffff0000, v215
	v_lshlrev_b32_e32 v178, 16, v184
	v_and_b32_e32 v184, 0xffff0000, v184
	v_lshlrev_b32_e32 v179, 16, v216
	v_and_b32_e32 v216, 0xffff0000, v216
	v_lshlrev_b32_e32 v180, 16, v185
	v_and_b32_e32 v185, 0xffff0000, v185
	v_lshlrev_b32_e32 v181, 16, v217
	v_and_b32_e32 v217, 0xffff0000, v217
	v_fmac_f32_e32 v151, v134, v150
	v_fmac_f32_e32 v214, v135, v182
	v_fmac_f32_e32 v153, v136, v152
	v_fmac_f32_e32 v215, v137, v183
	v_fmac_f32_e32 v179, v130, v178
	v_fmac_f32_e32 v216, v131, v184
	v_fmac_f32_e32 v181, v132, v180
	v_fmac_f32_e32 v217, v133, v185
	v_cvt_pk_bf16_f32 v214, v151, v214
	v_cvt_pk_bf16_f32 v215, v153, v215
	v_cvt_pk_bf16_f32 v216, v179, v216
	v_cvt_pk_bf16_f32 v217, v181, v217
	global_store_dwordx4 v248, v[214:217], s[90:91]
	v_add_u32_e32 v147, 0xd8000, v249
	global_load_dwordx4 v[134:137], v147, s[90:91]
	v_add_u32_e32 v147, 0xd8000, v248
	global_load_dwordx4 v[130:133], v147, s[90:91]
	s_waitcnt vmcnt(9)
	v_pk_add_f32 v[126:127], v[126:127], v[90:91]
	v_pk_add_f32 v[128:129], v[128:129], v[92:93]
	v_pk_add_f32 v[122:123], v[122:123], v[94:95]
	v_pk_add_f32 v[124:125], v[124:125], v[96:97]
	v_mul_f32_e32 v126, 0xbfb8aa3b, v126
	v_mul_f32_e32 v127, 0xbfb8aa3b, v127
	v_exp_f32_e32 v126, v126
	v_exp_f32_e32 v127, v127
	v_add_f32_e32 v126, 1.0, v126
	v_add_f32_e32 v127, 1.0, v127
	v_rcp_f32_e32 v126, v126
	v_rcp_f32_e32 v127, v127
	v_mul_f32_e32 v128, 0xbfb8aa3b, v128
	v_mul_f32_e32 v129, 0xbfb8aa3b, v129
	v_exp_f32_e32 v128, v128
	v_exp_f32_e32 v129, v129
	v_add_f32_e32 v128, 1.0, v128
	v_add_f32_e32 v129, 1.0, v129
	v_rcp_f32_e32 v128, v128
	v_rcp_f32_e32 v129, v129
	v_mul_f32_e32 v122, 0xbfb8aa3b, v122
	v_mul_f32_e32 v123, 0xbfb8aa3b, v123
	v_exp_f32_e32 v122, v122
	v_exp_f32_e32 v123, v123
	v_add_f32_e32 v122, 1.0, v122
	v_add_f32_e32 v123, 1.0, v123
	v_rcp_f32_e32 v122, v122
	v_rcp_f32_e32 v123, v123
	v_mul_f32_e32 v124, 0xbfb8aa3b, v124
	v_mul_f32_e32 v125, 0xbfb8aa3b, v125
	v_exp_f32_e32 v124, v124
	v_exp_f32_e32 v125, v125
	v_add_f32_e32 v124, 1.0, v124
	v_add_f32_e32 v125, 1.0, v125
	v_rcp_f32_e32 v124, v124
	v_rcp_f32_e32 v125, v125
	v_and_b32_e32 v218, s50, v218
	v_and_b32_e32 v219, s50, v219
	v_and_b32_e32 v220, s50, v220
	v_and_b32_e32 v221, s50, v221
	v_lshlrev_b32_e32 v150, 16, v198
	v_and_b32_e32 v198, 0xffff0000, v198
	v_lshlrev_b32_e32 v151, 16, v218
	v_and_b32_e32 v218, 0xffff0000, v218
	v_lshlrev_b32_e32 v152, 16, v199
	v_and_b32_e32 v199, 0xffff0000, v199
	v_lshlrev_b32_e32 v153, 16, v219
	v_and_b32_e32 v219, 0xffff0000, v219
	v_lshlrev_b32_e32 v178, 16, v200
	v_and_b32_e32 v200, 0xffff0000, v200
	v_lshlrev_b32_e32 v179, 16, v220
	v_and_b32_e32 v220, 0xffff0000, v220
	v_lshlrev_b32_e32 v180, 16, v201
	v_and_b32_e32 v201, 0xffff0000, v201
	v_lshlrev_b32_e32 v181, 16, v221
	v_and_b32_e32 v221, 0xffff0000, v221
	v_fmac_f32_e32 v151, v126, v150
	v_fmac_f32_e32 v218, v127, v198
	v_fmac_f32_e32 v153, v128, v152
	v_fmac_f32_e32 v219, v129, v199
	v_fmac_f32_e32 v179, v122, v178
	v_fmac_f32_e32 v220, v123, v200
	v_fmac_f32_e32 v181, v124, v180
	v_fmac_f32_e32 v221, v125, v201
	v_cvt_pk_bf16_f32 v218, v151, v218
	v_cvt_pk_bf16_f32 v219, v153, v219
	v_cvt_pk_bf16_f32 v220, v179, v220
	v_cvt_pk_bf16_f32 v221, v181, v221
	v_add_u32_e32 v146, 0x18000, v248
	global_store_dwordx4 v146, v[218:221], s[90:91]
	v_add_u32_e32 v147, 0xf0000, v249
	global_load_dwordx4 v[126:129], v147, s[90:91]
	v_add_u32_e32 v147, 0xf0000, v248
	global_load_dwordx4 v[122:125], v147, s[90:91]
	s_waitcnt vmcnt(10)
; __device__ __forceinline__ unsigned cvt_pk_bf16(float lo, float hi) { unsigned r; asm volatile("v_cvt_pk_bf16_f32 %0, %1, %2" : "=v"(r) : "v"(lo), "v"(hi)); return r; }
; __device__ __forceinline__ float fsigmoid(float x) { return __builtin_amdgcn_rcpf(1.f + __expf(-x)); }
;     __device__ __forceinline__ void operator()(const f32x4 (&acc)[2][2][4][2], const Unit& u, int wr, int wc, int fr, int fq) const {
;     ...
;         for (int bj = 0; bj < 2; ++bj) { const f32x4 b0 = *(const f32x4*)(bg + br * 1024 + col0 + bj * HALF), b1 = *(const f32x4*)(bg + br * 1024 + col0 + bj * HALF + 4);
; #pragma unroll
;             for (int ai = 0; ai < 2; ++ai)
; #pragma unroll
;                 for (int m = 0; m < 4; ++m) { bf16_t* pm_ = G + (size_t)(row0 + ai * HALF + m * 16) * 3072 + col0 + bj * HALF;
;                     const u32x4 pv = *(const u32x4*)(pm_ + br * 1024); u32x4 mv = (u32x4){0u, 0u, 0u, 0u}; if (br) mv = *(const u32x4*)pm_;
;                     const f32x4 v0 = acc[ai][bj][m][0] + b0, v1 = acc[ai][bj][m][1] + b1;
;                     u32x4 w;
;                     w.x = cvt_pk_bf16(bf_lo(mv.x) + fsigmoid(v0[0]) * bf_lo(pv.x), bf_hi(mv.x) + fsigmoid(v0[1]) * bf_hi(pv.x));
;                     w.y = cvt_pk_bf16(bf_lo(mv.y) + fsigmoid(v0[2]) * bf_lo(pv.y), bf_hi(mv.y) + fsigmoid(v0[3]) * bf_hi(pv.y));
;                     w.z = cvt_pk_bf16(bf_lo(mv.z) + fsigmoid(v1[0]) * bf_lo(pv.z), bf_hi(mv.z) + fsigmoid(v1[1]) * bf_hi(pv.z));
;                     w.w = cvt_pk_bf16(bf_lo(mv.w) + fsigmoid(v1[2]) * bf_lo(pv.w), bf_hi(mv.w) + fsigmoid(v1[3]) * bf_hi(pv.w));
;                     *(u32x4*)pm_ = w; } }
	v_pk_add_f32 v[118:119], v[118:119], v[90:91]
	v_pk_add_f32 v[120:121], v[120:121], v[92:93]
	v_pk_add_f32 v[114:115], v[114:115], v[94:95]
	v_pk_add_f32 v[116:117], v[116:117], v[96:97]
	v_mul_f32_e32 v118, 0xbfb8aa3b, v118
	v_mul_f32_e32 v119, 0xbfb8aa3b, v119
	v_exp_f32_e32 v118, v118
	v_exp_f32_e32 v119, v119
	v_add_f32_e32 v118, 1.0, v118
	v_add_f32_e32 v119, 1.0, v119
	v_rcp_f32_e32 v118, v118
	v_rcp_f32_e32 v119, v119
	v_mul_f32_e32 v120, 0xbfb8aa3b, v120
	v_mul_f32_e32 v121, 0xbfb8aa3b, v121
	v_exp_f32_e32 v120, v120
	v_exp_f32_e32 v121, v121
	v_add_f32_e32 v120, 1.0, v120
	v_add_f32_e32 v121, 1.0, v121
	v_rcp_f32_e32 v120, v120
	v_rcp_f32_e32 v121, v121
	v_mul_f32_e32 v114, 0xbfb8aa3b, v114
	v_mul_f32_e32 v115, 0xbfb8aa3b, v115
	v_exp_f32_e32 v114, v114
	v_exp_f32_e32 v115, v115
	v_add_f32_e32 v114, 1.0, v114
	v_add_f32_e32 v115, 1.0, v115
	v_rcp_f32_e32 v114, v114
	v_rcp_f32_e32 v115, v115
	v_mul_f32_e32 v116, 0xbfb8aa3b, v116
	v_mul_f32_e32 v117, 0xbfb8aa3b, v117
	v_exp_f32_e32 v116, v116
	v_exp_f32_e32 v117, v117
	v_add_f32_e32 v116, 1.0, v116
	v_add_f32_e32 v117, 1.0, v117
	v_rcp_f32_e32 v116, v116
	v_rcp_f32_e32 v117, v117
	v_and_b32_e32 v222, s50, v222
	v_and_b32_e32 v223, s50, v223
	v_and_b32_e32 v224, s50, v224
	v_and_b32_e32 v225, s50, v225
	v_lshlrev_b32_e32 v150, 16, v202
	v_and_b32_e32 v202, 0xffff0000, v202
	v_lshlrev_b32_e32 v151, 16, v222
	v_and_b32_e32 v222, 0xffff0000, v222
	v_lshlrev_b32_e32 v152, 16, v203
	v_and_b32_e32 v203, 0xffff0000, v203
	v_lshlrev_b32_e32 v153, 16, v223
	v_and_b32_e32 v223, 0xffff0000, v223
	v_lshlrev_b32_e32 v178, 16, v204
	v_and_b32_e32 v204, 0xffff0000, v204
	v_lshlrev_b32_e32 v179, 16, v224
	v_and_b32_e32 v224, 0xffff0000, v224
	v_lshlrev_b32_e32 v180, 16, v205
	v_and_b32_e32 v205, 0xffff0000, v205
	v_lshlrev_b32_e32 v181, 16, v225
	v_and_b32_e32 v225, 0xffff0000, v225
	v_fmac_f32_e32 v151, v118, v150
	v_fmac_f32_e32 v222, v119, v202
	v_fmac_f32_e32 v153, v120, v152
	v_fmac_f32_e32 v223, v121, v203
	v_fmac_f32_e32 v179, v114, v178
	v_fmac_f32_e32 v224, v115, v204
	v_fmac_f32_e32 v181, v116, v180
	v_fmac_f32_e32 v225, v117, v205
	v_cvt_pk_bf16_f32 v222, v151, v222
	v_cvt_pk_bf16_f32 v223, v153, v223
	v_cvt_pk_bf16_f32 v224, v179, v224
	v_cvt_pk_bf16_f32 v225, v181, v225
	v_add_u32_e32 v146, 0x30000, v248
	global_store_dwordx4 v146, v[222:225], s[90:91]
	v_add_u32_e32 v147, 0x108000, v249
	global_load_dwordx4 v[118:121], v147, s[90:91]
	v_add_u32_e32 v147, 0x108000, v248
	global_load_dwordx4 v[114:117], v147, s[90:91]
	s_waitcnt vmcnt(11)
	v_pk_add_f32 v[110:111], v[110:111], v[90:91]
	v_pk_add_f32 v[112:113], v[112:113], v[92:93]
	v_pk_add_f32 v[106:107], v[106:107], v[94:95]
	v_pk_add_f32 v[108:109], v[108:109], v[96:97]
	v_mul_f32_e32 v110, 0xbfb8aa3b, v110
	v_mul_f32_e32 v111, 0xbfb8aa3b, v111
	v_exp_f32_e32 v110, v110
	v_exp_f32_e32 v111, v111
	v_add_f32_e32 v110, 1.0, v110
	v_add_f32_e32 v111, 1.0, v111
	v_rcp_f32_e32 v110, v110
	v_rcp_f32_e32 v111, v111
	v_mul_f32_e32 v112, 0xbfb8aa3b, v112
	v_mul_f32_e32 v113, 0xbfb8aa3b, v113
	v_exp_f32_e32 v112, v112
	v_exp_f32_e32 v113, v113
	v_add_f32_e32 v112, 1.0, v112
	v_add_f32_e32 v113, 1.0, v113
	v_rcp_f32_e32 v112, v112
	v_rcp_f32_e32 v113, v113
	v_mul_f32_e32 v106, 0xbfb8aa3b, v106
	v_mul_f32_e32 v107, 0xbfb8aa3b, v107
	v_exp_f32_e32 v106, v106
	v_exp_f32_e32 v107, v107
	v_add_f32_e32 v106, 1.0, v106
	v_add_f32_e32 v107, 1.0, v107
	v_rcp_f32_e32 v106, v106
	v_rcp_f32_e32 v107, v107
	v_mul_f32_e32 v108, 0xbfb8aa3b, v108
	v_mul_f32_e32 v109, 0xbfb8aa3b, v109
	v_exp_f32_e32 v108, v108
	v_exp_f32_e32 v109, v109
	v_add_f32_e32 v108, 1.0, v108
	v_add_f32_e32 v109, 1.0, v109
	v_rcp_f32_e32 v108, v108
	v_rcp_f32_e32 v109, v109
	v_and_b32_e32 v226, s50, v226
	v_and_b32_e32 v227, s50, v227
	v_and_b32_e32 v228, s50, v228
	v_and_b32_e32 v229, s50, v229
	v_lshlrev_b32_e32 v150, 16, v206
	v_and_b32_e32 v206, 0xffff0000, v206
	v_lshlrev_b32_e32 v151, 16, v226
	v_and_b32_e32 v226, 0xffff0000, v226
	v_lshlrev_b32_e32 v152, 16, v207
	v_and_b32_e32 v207, 0xffff0000, v207
	v_lshlrev_b32_e32 v153, 16, v227
	v_and_b32_e32 v227, 0xffff0000, v227
	v_lshlrev_b32_e32 v178, 16, v208
	v_and_b32_e32 v208, 0xffff0000, v208
	v_lshlrev_b32_e32 v179, 16, v228
	v_and_b32_e32 v228, 0xffff0000, v228
	v_lshlrev_b32_e32 v180, 16, v209
	v_and_b32_e32 v209, 0xffff0000, v209
	v_lshlrev_b32_e32 v181, 16, v229
	v_and_b32_e32 v229, 0xffff0000, v229
	v_fmac_f32_e32 v151, v110, v150
	v_fmac_f32_e32 v226, v111, v206
	v_fmac_f32_e32 v153, v112, v152
	v_fmac_f32_e32 v227, v113, v207
	v_fmac_f32_e32 v179, v106, v178
	v_fmac_f32_e32 v228, v107, v208
	v_fmac_f32_e32 v181, v108, v180
	v_fmac_f32_e32 v229, v109, v209
	v_cvt_pk_bf16_f32 v226, v151, v226
	v_cvt_pk_bf16_f32 v227, v153, v227
	v_cvt_pk_bf16_f32 v228, v179, v228
	v_cvt_pk_bf16_f32 v229, v181, v229
	v_add_u32_e32 v146, 0x48000, v248
	global_store_dwordx4 v146, v[226:229], s[90:91]
	global_load_dwordx4 v[110:113], v249, s[90:91] offset:256
	global_load_dwordx4 v[106:109], v248, s[90:91] offset:256
	s_waitcnt vmcnt(12)
; __device__ __forceinline__ unsigned cvt_pk_bf16(float lo, float hi) { unsigned r; asm volatile("v_cvt_pk_bf16_f32 %0, %1, %2" : "=v"(r) : "v"(lo), "v"(hi)); return r; }
; __device__ __forceinline__ float fsigmoid(float x) { return __builtin_amdgcn_rcpf(1.f + __expf(-x)); }
;     __device__ __forceinline__ void operator()(const f32x4 (&acc)[2][2][4][2], const Unit& u, int wr, int wc, int fr, int fq) const {
;     ...
;         for (int bj = 0; bj < 2; ++bj) { const f32x4 b0 = *(const f32x4*)(bg + br * 1024 + col0 + bj * HALF), b1 = *(const f32x4*)(bg + br * 1024 + col0 + bj * HALF + 4);
; #pragma unroll
;             for (int ai = 0; ai < 2; ++ai)
; #pragma unroll
;                 for (int m = 0; m < 4; ++m) { bf16_t* pm_ = G + (size_t)(row0 + ai * HALF + m * 16) * 3072 + col0 + bj * HALF;
;                     const u32x4 pv = *(const u32x4*)(pm_ + br * 1024); u32x4 mv = (u32x4){0u, 0u, 0u, 0u}; if (br) mv = *(const u32x4*)pm_;
;                     const f32x4 v0 = acc[ai][bj][m][0] + b0, v1 = acc[ai][bj][m][1] + b1;
;                     u32x4 w;
;                     w.x = cvt_pk_bf16(bf_lo(mv.x) + fsigmoid(v0[0]) * bf_lo(pv.x), bf_hi(mv.x) + fsigmoid(v0[1]) * bf_hi(pv.x));
;                     w.y = cvt_pk_bf16(bf_lo(mv.y) + fsigmoid(v0[2]) * bf_lo(pv.y), bf_hi(mv.y) + fsigmoid(v0[3]) * bf_hi(pv.y));
;                     w.z = cvt_pk_bf16(bf_lo(mv.z) + fsigmoid(v1[0]) * bf_lo(pv.z), bf_hi(mv.z) + fsigmoid(v1[1]) * bf_hi(pv.z));
;                     w.w = cvt_pk_bf16(bf_lo(mv.w) + fsigmoid(v1[2]) * bf_lo(pv.w), bf_hi(mv.w) + fsigmoid(v1[3]) * bf_hi(pv.w));
;                     *(u32x4*)pm_ = w; } }
	v_pk_add_f32 v[102:103], v[102:103], v[90:91]
	v_pk_add_f32 v[104:105], v[104:105], v[92:93]
	v_pk_add_f32 v[98:99], v[98:99], v[94:95]
	v_pk_add_f32 v[100:101], v[100:101], v[96:97]
	v_mul_f32_e32 v102, 0xbfb8aa3b, v102
	v_mul_f32_e32 v103, 0xbfb8aa3b, v103
	v_exp_f32_e32 v102, v102
	v_exp_f32_e32 v103, v103
	v_add_f32_e32 v102, 1.0, v102
	v_add_f32_e32 v103, 1.0, v103
	v_rcp_f32_e32 v102, v102
	v_rcp_f32_e32 v103, v103
	v_mul_f32_e32 v104, 0xbfb8aa3b, v104
	v_mul_f32_e32 v105, 0xbfb8aa3b, v105
	v_exp_f32_e32 v104, v104
	v_exp_f32_e32 v105, v105
	v_add_f32_e32 v104, 1.0, v104
	v_add_f32_e32 v105, 1.0, v105
	v_rcp_f32_e32 v104, v104
	v_rcp_f32_e32 v105, v105
	v_mul_f32_e32 v98, 0xbfb8aa3b, v98
	v_mul_f32_e32 v99, 0xbfb8aa3b, v99
	v_exp_f32_e32 v98, v98
	v_exp_f32_e32 v99, v99
	v_add_f32_e32 v98, 1.0, v98
	v_add_f32_e32 v99, 1.0, v99
	v_rcp_f32_e32 v98, v98
	v_rcp_f32_e32 v99, v99
	v_mul_f32_e32 v100, 0xbfb8aa3b, v100
	v_mul_f32_e32 v101, 0xbfb8aa3b, v101
	v_exp_f32_e32 v100, v100
	v_exp_f32_e32 v101, v101
	v_add_f32_e32 v100, 1.0, v100
	v_add_f32_e32 v101, 1.0, v101
	v_rcp_f32_e32 v100, v100
	v_rcp_f32_e32 v101, v101
	v_and_b32_e32 v236, s50, v236
	v_and_b32_e32 v237, s50, v237
	v_and_b32_e32 v238, s50, v238
	v_and_b32_e32 v239, s50, v239
	v_lshlrev_b32_e32 v150, 16, v210
	v_and_b32_e32 v210, 0xffff0000, v210
	v_lshlrev_b32_e32 v151, 16, v236
	v_and_b32_e32 v236, 0xffff0000, v236
	v_lshlrev_b32_e32 v152, 16, v211
	v_and_b32_e32 v211, 0xffff0000, v211
	v_lshlrev_b32_e32 v153, 16, v237
	v_and_b32_e32 v237, 0xffff0000, v237
	v_lshlrev_b32_e32 v178, 16, v212
	v_and_b32_e32 v212, 0xffff0000, v212
	v_lshlrev_b32_e32 v179, 16, v238
	v_and_b32_e32 v238, 0xffff0000, v238
	v_lshlrev_b32_e32 v180, 16, v213
	v_and_b32_e32 v213, 0xffff0000, v213
	v_lshlrev_b32_e32 v181, 16, v239
	v_and_b32_e32 v239, 0xffff0000, v239
	v_fmac_f32_e32 v151, v102, v150
	v_fmac_f32_e32 v236, v103, v210
	v_fmac_f32_e32 v153, v104, v152
	v_fmac_f32_e32 v237, v105, v211
	v_fmac_f32_e32 v179, v98, v178
	v_fmac_f32_e32 v238, v99, v212
	v_fmac_f32_e32 v181, v100, v180
	v_fmac_f32_e32 v239, v101, v213
	v_cvt_pk_bf16_f32 v236, v151, v236
	v_cvt_pk_bf16_f32 v237, v153, v237
	v_cvt_pk_bf16_f32 v238, v179, v238
	v_cvt_pk_bf16_f32 v239, v181, v239
	v_add_u32_e32 v146, 0xc0000, v248
	global_store_dwordx4 v146, v[236:239], s[90:91]
	v_add_u32_e32 v147, 0x18000, v249
	global_load_dwordx4 v[102:105], v147, s[90:91] offset:256
	v_add_u32_e32 v147, 0x18000, v248
	global_load_dwordx4 v[98:101], v147, s[90:91] offset:256
	s_waitcnt vmcnt(12)
	v_pk_add_f32 v[86:87], v[86:87], v[90:91]
	v_pk_add_f32 v[88:89], v[88:89], v[92:93]
	v_pk_add_f32 v[82:83], v[82:83], v[94:95]
	v_pk_add_f32 v[84:85], v[84:85], v[96:97]
	v_mul_f32_e32 v86, 0xbfb8aa3b, v86
	v_mul_f32_e32 v87, 0xbfb8aa3b, v87
	v_exp_f32_e32 v86, v86
	v_exp_f32_e32 v87, v87
	v_add_f32_e32 v86, 1.0, v86
	v_add_f32_e32 v87, 1.0, v87
	v_rcp_f32_e32 v86, v86
	v_rcp_f32_e32 v87, v87
	v_mul_f32_e32 v88, 0xbfb8aa3b, v88
	v_mul_f32_e32 v89, 0xbfb8aa3b, v89
	v_exp_f32_e32 v88, v88
	v_exp_f32_e32 v89, v89
	v_add_f32_e32 v88, 1.0, v88
	v_add_f32_e32 v89, 1.0, v89
	v_rcp_f32_e32 v88, v88
	v_rcp_f32_e32 v89, v89
	v_mul_f32_e32 v82, 0xbfb8aa3b, v82
	v_mul_f32_e32 v83, 0xbfb8aa3b, v83
	v_exp_f32_e32 v82, v82
	v_exp_f32_e32 v83, v83
	v_add_f32_e32 v82, 1.0, v82
	v_add_f32_e32 v83, 1.0, v83
	v_rcp_f32_e32 v82, v82
	v_rcp_f32_e32 v83, v83
	v_mul_f32_e32 v84, 0xbfb8aa3b, v84
	v_mul_f32_e32 v85, 0xbfb8aa3b, v85
	v_exp_f32_e32 v84, v84
	v_exp_f32_e32 v85, v85
	v_add_f32_e32 v84, 1.0, v84
	v_add_f32_e32 v85, 1.0, v85
	v_rcp_f32_e32 v84, v84
	v_rcp_f32_e32 v85, v85
	v_and_b32_e32 v130, s50, v130
	v_and_b32_e32 v131, s50, v131
	v_and_b32_e32 v132, s50, v132
	v_and_b32_e32 v133, s50, v133
	v_lshlrev_b32_e32 v150, 16, v134
	v_and_b32_e32 v134, 0xffff0000, v134
	v_lshlrev_b32_e32 v151, 16, v130
	v_and_b32_e32 v130, 0xffff0000, v130
	v_lshlrev_b32_e32 v152, 16, v135
	v_and_b32_e32 v135, 0xffff0000, v135
	v_lshlrev_b32_e32 v153, 16, v131
	v_and_b32_e32 v131, 0xffff0000, v131
	v_lshlrev_b32_e32 v178, 16, v136
	v_and_b32_e32 v136, 0xffff0000, v136
	v_lshlrev_b32_e32 v179, 16, v132
	v_and_b32_e32 v132, 0xffff0000, v132
	v_lshlrev_b32_e32 v180, 16, v137
	v_and_b32_e32 v137, 0xffff0000, v137
	v_lshlrev_b32_e32 v181, 16, v133
	v_and_b32_e32 v133, 0xffff0000, v133
	v_fmac_f32_e32 v151, v86, v150
	v_fmac_f32_e32 v130, v87, v134
	v_fmac_f32_e32 v153, v88, v152
	v_fmac_f32_e32 v131, v89, v135
	v_fmac_f32_e32 v179, v82, v178
	v_fmac_f32_e32 v132, v83, v136
	v_fmac_f32_e32 v181, v84, v180
	v_fmac_f32_e32 v133, v85, v137
	v_cvt_pk_bf16_f32 v130, v151, v130
	v_cvt_pk_bf16_f32 v131, v153, v131
	v_cvt_pk_bf16_f32 v132, v179, v132
	v_cvt_pk_bf16_f32 v133, v181, v133
	v_add_u32_e32 v146, 0xd8000, v248
	global_store_dwordx4 v146, v[130:133], s[90:91]
	v_add_u32_e32 v147, 0x30000, v249
	global_load_dwordx4 v[86:89], v147, s[90:91] offset:256
	v_add_u32_e32 v147, 0x30000, v248
	global_load_dwordx4 v[82:85], v147, s[90:91] offset:256
	s_waitcnt vmcnt(12)
; __device__ __forceinline__ unsigned cvt_pk_bf16(float lo, float hi) { unsigned r; asm volatile("v_cvt_pk_bf16_f32 %0, %1, %2" : "=v"(r) : "v"(lo), "v"(hi)); return r; }
; __device__ __forceinline__ float fsigmoid(float x) { return __builtin_amdgcn_rcpf(1.f + __expf(-x)); }
;     __device__ __forceinline__ void operator()(const f32x4 (&acc)[2][2][4][2], const Unit& u, int wr, int wc, int fr, int fq) const {
;     ...
;         for (int bj = 0; bj < 2; ++bj) { const f32x4 b0 = *(const f32x4*)(bg + br * 1024 + col0 + bj * HALF), b1 = *(const f32x4*)(bg + br * 1024 + col0 + bj * HALF + 4);
; #pragma unroll
;             for (int ai = 0; ai < 2; ++ai)
; #pragma unroll
;                 for (int m = 0; m < 4; ++m) { bf16_t* pm_ = G + (size_t)(row0 + ai * HALF + m * 16) * 3072 + col0 + bj * HALF;
;                     const u32x4 pv = *(const u32x4*)(pm_ + br * 1024); u32x4 mv = (u32x4){0u, 0u, 0u, 0u}; if (br) mv = *(const u32x4*)pm_;
;                     const f32x4 v0 = acc[ai][bj][m][0] + b0, v1 = acc[ai][bj][m][1] + b1;
;                     u32x4 w;
;                     w.x = cvt_pk_bf16(bf_lo(mv.x) + fsigmoid(v0[0]) * bf_lo(pv.x), bf_hi(mv.x) + fsigmoid(v0[1]) * bf_hi(pv.x));
;                     w.y = cvt_pk_bf16(bf_lo(mv.y) + fsigmoid(v0[2]) * bf_lo(pv.y), bf_hi(mv.y) + fsigmoid(v0[3]) * bf_hi(pv.y));
;                     w.z = cvt_pk_bf16(bf_lo(mv.z) + fsigmoid(v1[0]) * bf_lo(pv.z), bf_hi(mv.z) + fsigmoid(v1[1]) * bf_hi(pv.z));
;                     w.w = cvt_pk_bf16(bf_lo(mv.w) + fsigmoid(v1[2]) * bf_lo(pv.w), bf_hi(mv.w) + fsigmoid(v1[3]) * bf_hi(pv.w));
;                     *(u32x4*)pm_ = w; } }
	v_pk_add_f32 v[78:79], v[78:79], v[90:91]
	v_pk_add_f32 v[80:81], v[80:81], v[92:93]
	v_pk_add_f32 v[74:75], v[74:75], v[94:95]
	v_pk_add_f32 v[76:77], v[76:77], v[96:97]
	v_mul_f32_e32 v78, 0xbfb8aa3b, v78
	v_mul_f32_e32 v79, 0xbfb8aa3b, v79
	v_exp_f32_e32 v78, v78
	v_exp_f32_e32 v79, v79
	v_add_f32_e32 v78, 1.0, v78
	v_add_f32_e32 v79, 1.0, v79
	v_rcp_f32_e32 v78, v78
	v_rcp_f32_e32 v79, v79
	v_mul_f32_e32 v80, 0xbfb8aa3b, v80
	v_mul_f32_e32 v81, 0xbfb8aa3b, v81
	v_exp_f32_e32 v80, v80
	v_exp_f32_e32 v81, v81
	v_add_f32_e32 v80, 1.0, v80
	v_add_f32_e32 v81, 1.0, v81
	v_rcp_f32_e32 v80, v80
	v_rcp_f32_e32 v81, v81
	v_mul_f32_e32 v74, 0xbfb8aa3b, v74
	v_mul_f32_e32 v75, 0xbfb8aa3b, v75
	v_exp_f32_e32 v74, v74
	v_exp_f32_e32 v75, v75
	v_add_f32_e32 v74, 1.0, v74
	v_add_f32_e32 v75, 1.0, v75
	v_rcp_f32_e32 v74, v74
	v_rcp_f32_e32 v75, v75
	v_mul_f32_e32 v76, 0xbfb8aa3b, v76
	v_mul_f32_e32 v77, 0xbfb8aa3b, v77
	v_exp_f32_e32 v76, v76
	v_exp_f32_e32 v77, v77
	v_add_f32_e32 v76, 1.0, v76
	v_add_f32_e32 v77, 1.0, v77
	v_rcp_f32_e32 v76, v76
	v_rcp_f32_e32 v77, v77
	v_and_b32_e32 v122, s50, v122
	v_and_b32_e32 v123, s50, v123
	v_and_b32_e32 v124, s50, v124
	v_and_b32_e32 v125, s50, v125
	v_lshlrev_b32_e32 v150, 16, v126
	v_and_b32_e32 v126, 0xffff0000, v126
	v_lshlrev_b32_e32 v151, 16, v122
	v_and_b32_e32 v122, 0xffff0000, v122
	v_lshlrev_b32_e32 v152, 16, v127
	v_and_b32_e32 v127, 0xffff0000, v127
	v_lshlrev_b32_e32 v153, 16, v123
	v_and_b32_e32 v123, 0xffff0000, v123
	v_lshlrev_b32_e32 v178, 16, v128
	v_and_b32_e32 v128, 0xffff0000, v128
	v_lshlrev_b32_e32 v179, 16, v124
	v_and_b32_e32 v124, 0xffff0000, v124
	v_lshlrev_b32_e32 v180, 16, v129
	v_and_b32_e32 v129, 0xffff0000, v129
	v_lshlrev_b32_e32 v181, 16, v125
	v_and_b32_e32 v125, 0xffff0000, v125
	v_fmac_f32_e32 v151, v78, v150
	v_fmac_f32_e32 v122, v79, v126
	v_fmac_f32_e32 v153, v80, v152
	v_fmac_f32_e32 v123, v81, v127
	v_fmac_f32_e32 v179, v74, v178
	v_fmac_f32_e32 v124, v75, v128
	v_fmac_f32_e32 v181, v76, v180
	v_fmac_f32_e32 v125, v77, v129
	v_cvt_pk_bf16_f32 v122, v151, v122
	v_cvt_pk_bf16_f32 v123, v153, v123
	v_cvt_pk_bf16_f32 v124, v179, v124
	v_cvt_pk_bf16_f32 v125, v181, v125
	v_add_u32_e32 v146, 0xf0000, v248
	global_store_dwordx4 v146, v[122:125], s[90:91]
	v_add_u32_e32 v147, 0x48000, v249
	global_load_dwordx4 v[78:81], v147, s[90:91] offset:256
	v_add_u32_e32 v147, 0x48000, v248
	global_load_dwordx4 v[74:77], v147, s[90:91] offset:256
	s_waitcnt vmcnt(12)
	v_pk_add_f32 v[70:71], v[70:71], v[90:91]
	v_pk_add_f32 v[72:73], v[72:73], v[92:93]
	v_pk_add_f32 v[66:67], v[66:67], v[94:95]
	v_pk_add_f32 v[68:69], v[68:69], v[96:97]
	v_mul_f32_e32 v70, 0xbfb8aa3b, v70
	v_mul_f32_e32 v71, 0xbfb8aa3b, v71
	v_exp_f32_e32 v70, v70
	v_exp_f32_e32 v71, v71
	v_add_f32_e32 v70, 1.0, v70
	v_add_f32_e32 v71, 1.0, v71
	v_rcp_f32_e32 v70, v70
	v_rcp_f32_e32 v71, v71
	v_mul_f32_e32 v72, 0xbfb8aa3b, v72
	v_mul_f32_e32 v73, 0xbfb8aa3b, v73
	v_exp_f32_e32 v72, v72
	v_exp_f32_e32 v73, v73
	v_add_f32_e32 v72, 1.0, v72
	v_add_f32_e32 v73, 1.0, v73
	v_rcp_f32_e32 v72, v72
	v_rcp_f32_e32 v73, v73
	v_mul_f32_e32 v66, 0xbfb8aa3b, v66
	v_mul_f32_e32 v67, 0xbfb8aa3b, v67
	v_exp_f32_e32 v66, v66
	v_exp_f32_e32 v67, v67
	v_add_f32_e32 v66, 1.0, v66
	v_add_f32_e32 v67, 1.0, v67
	v_rcp_f32_e32 v66, v66
	v_rcp_f32_e32 v67, v67
	v_mul_f32_e32 v68, 0xbfb8aa3b, v68
	v_mul_f32_e32 v69, 0xbfb8aa3b, v69
	v_exp_f32_e32 v68, v68
	v_exp_f32_e32 v69, v69
	v_add_f32_e32 v68, 1.0, v68
	v_add_f32_e32 v69, 1.0, v69
	v_rcp_f32_e32 v68, v68
	v_rcp_f32_e32 v69, v69
	v_and_b32_e32 v114, s50, v114
	v_and_b32_e32 v115, s50, v115
	v_and_b32_e32 v116, s50, v116
	v_and_b32_e32 v117, s50, v117
	v_lshlrev_b32_e32 v150, 16, v118
	v_and_b32_e32 v118, 0xffff0000, v118
	v_lshlrev_b32_e32 v151, 16, v114
	v_and_b32_e32 v114, 0xffff0000, v114
	v_lshlrev_b32_e32 v152, 16, v119
	v_and_b32_e32 v119, 0xffff0000, v119
	v_lshlrev_b32_e32 v153, 16, v115
	v_and_b32_e32 v115, 0xffff0000, v115
	v_lshlrev_b32_e32 v178, 16, v120
	v_and_b32_e32 v120, 0xffff0000, v120
	v_lshlrev_b32_e32 v179, 16, v116
	v_and_b32_e32 v116, 0xffff0000, v116
	v_lshlrev_b32_e32 v180, 16, v121
	v_and_b32_e32 v121, 0xffff0000, v121
	v_lshlrev_b32_e32 v181, 16, v117
	v_and_b32_e32 v117, 0xffff0000, v117
	v_fmac_f32_e32 v151, v70, v150
	v_fmac_f32_e32 v114, v71, v118
	v_fmac_f32_e32 v153, v72, v152
	v_fmac_f32_e32 v115, v73, v119
	v_fmac_f32_e32 v179, v66, v178
	v_fmac_f32_e32 v116, v67, v120
	v_fmac_f32_e32 v181, v68, v180
	v_fmac_f32_e32 v117, v69, v121
	v_cvt_pk_bf16_f32 v114, v151, v114
	v_cvt_pk_bf16_f32 v115, v153, v115
	v_cvt_pk_bf16_f32 v116, v179, v116
	v_cvt_pk_bf16_f32 v117, v181, v117
	v_add_u32_e32 v146, 0x108000, v248
	global_store_dwordx4 v146, v[114:117], s[90:91]
	v_add_u32_e32 v147, 0xc0000, v249
	global_load_dwordx4 v[70:73], v147, s[90:91] offset:256
	v_add_u32_e32 v147, 0xc0000, v248
	global_load_dwordx4 v[66:69], v147, s[90:91] offset:256
	s_waitcnt vmcnt(12)
; __device__ __forceinline__ unsigned cvt_pk_bf16(float lo, float hi) { unsigned r; asm volatile("v_cvt_pk_bf16_f32 %0, %1, %2" : "=v"(r) : "v"(lo), "v"(hi)); return r; }
; __device__ __forceinline__ float fsigmoid(float x) { return __builtin_amdgcn_rcpf(1.f + __expf(-x)); }
;     __device__ __forceinline__ void operator()(const f32x4 (&acc)[2][2][4][2], const Unit& u, int wr, int wc, int fr, int fq) const {
;     ...
;         for (int bj = 0; bj < 2; ++bj) { const f32x4 b0 = *(const f32x4*)(bg + br * 1024 + col0 + bj * HALF), b1 = *(const f32x4*)(bg + br * 1024 + col0 + bj * HALF + 4);
; #pragma unroll
;             for (int ai = 0; ai < 2; ++ai)
; #pragma unroll
;                 for (int m = 0; m < 4; ++m) { bf16_t* pm_ = G + (size_t)(row0 + ai * HALF + m * 16) * 3072 + col0 + bj * HALF;
;                     const u32x4 pv = *(const u32x4*)(pm_ + br * 1024); u32x4 mv = (u32x4){0u, 0u, 0u, 0u}; if (br) mv = *(const u32x4*)pm_;
;                     const f32x4 v0 = acc[ai][bj][m][0] + b0, v1 = acc[ai][bj][m][1] + b1;
;                     u32x4 w;
;                     w.x = cvt_pk_bf16(bf_lo(mv.x) + fsigmoid(v0[0]) * bf_lo(pv.x), bf_hi(mv.x) + fsigmoid(v0[1]) * bf_hi(pv.x));
;                     w.y = cvt_pk_bf16(bf_lo(mv.y) + fsigmoid(v0[2]) * bf_lo(pv.y), bf_hi(mv.y) + fsigmoid(v0[3]) * bf_hi(pv.y));
;                     w.z = cvt_pk_bf16(bf_lo(mv.z) + fsigmoid(v1[0]) * bf_lo(pv.z), bf_hi(mv.z) + fsigmoid(v1[1]) * bf_hi(pv.z));
;                     w.w = cvt_pk_bf16(bf_lo(mv.w) + fsigmoid(v1[2]) * bf_lo(pv.w), bf_hi(mv.w) + fsigmoid(v1[3]) * bf_hi(pv.w));
;                     *(u32x4*)pm_ = w; } }
	v_pk_add_f32 v[62:63], v[62:63], v[138:139]
	v_pk_add_f32 v[64:65], v[64:65], v[140:141]
	v_pk_add_f32 v[58:59], v[58:59], v[142:143]
	v_pk_add_f32 v[60:61], v[60:61], v[144:145]
	v_mul_f32_e32 v62, 0xbfb8aa3b, v62
	v_mul_f32_e32 v63, 0xbfb8aa3b, v63
	v_exp_f32_e32 v62, v62
	v_exp_f32_e32 v63, v63
	v_add_f32_e32 v62, 1.0, v62
	v_add_f32_e32 v63, 1.0, v63
	v_rcp_f32_e32 v62, v62
	v_rcp_f32_e32 v63, v63
	v_mul_f32_e32 v64, 0xbfb8aa3b, v64
	v_mul_f32_e32 v65, 0xbfb8aa3b, v65
	v_exp_f32_e32 v64, v64
	v_exp_f32_e32 v65, v65
	v_add_f32_e32 v64, 1.0, v64
	v_add_f32_e32 v65, 1.0, v65
	v_rcp_f32_e32 v64, v64
	v_rcp_f32_e32 v65, v65
	v_mul_f32_e32 v58, 0xbfb8aa3b, v58
	v_mul_f32_e32 v59, 0xbfb8aa3b, v59
	v_exp_f32_e32 v58, v58
	v_exp_f32_e32 v59, v59
	v_add_f32_e32 v58, 1.0, v58
	v_add_f32_e32 v59, 1.0, v59
	v_rcp_f32_e32 v58, v58
	v_rcp_f32_e32 v59, v59
	v_mul_f32_e32 v60, 0xbfb8aa3b, v60
	v_mul_f32_e32 v61, 0xbfb8aa3b, v61
	v_exp_f32_e32 v60, v60
	v_exp_f32_e32 v61, v61
	v_add_f32_e32 v60, 1.0, v60
	v_add_f32_e32 v61, 1.0, v61
	v_rcp_f32_e32 v60, v60
	v_rcp_f32_e32 v61, v61
	v_and_b32_e32 v106, s50, v106
	v_and_b32_e32 v107, s50, v107
	v_and_b32_e32 v108, s50, v108
	v_and_b32_e32 v109, s50, v109
	v_lshlrev_b32_e32 v150, 16, v110
	v_and_b32_e32 v110, 0xffff0000, v110
	v_lshlrev_b32_e32 v151, 16, v106
	v_and_b32_e32 v106, 0xffff0000, v106
	v_lshlrev_b32_e32 v152, 16, v111
	v_and_b32_e32 v111, 0xffff0000, v111
	v_lshlrev_b32_e32 v153, 16, v107
	v_and_b32_e32 v107, 0xffff0000, v107
	v_lshlrev_b32_e32 v178, 16, v112
	v_and_b32_e32 v112, 0xffff0000, v112
	v_lshlrev_b32_e32 v179, 16, v108
	v_and_b32_e32 v108, 0xffff0000, v108
	v_lshlrev_b32_e32 v180, 16, v113
	v_and_b32_e32 v113, 0xffff0000, v113
	v_lshlrev_b32_e32 v181, 16, v109
	v_and_b32_e32 v109, 0xffff0000, v109
	v_fmac_f32_e32 v151, v62, v150
	v_fmac_f32_e32 v106, v63, v110
	v_fmac_f32_e32 v153, v64, v152
	v_fmac_f32_e32 v107, v65, v111
	v_fmac_f32_e32 v179, v58, v178
	v_fmac_f32_e32 v108, v59, v112
	v_fmac_f32_e32 v181, v60, v180
	v_fmac_f32_e32 v109, v61, v113
	v_cvt_pk_bf16_f32 v106, v151, v106
	v_cvt_pk_bf16_f32 v107, v153, v107
	v_cvt_pk_bf16_f32 v108, v179, v108
	v_cvt_pk_bf16_f32 v109, v181, v109
	global_store_dwordx4 v248, v[106:109], s[90:91] offset:256
	v_add_u32_e32 v147, 0xd8000, v249
	global_load_dwordx4 v[62:65], v147, s[90:91] offset:256
	v_add_u32_e32 v147, 0xd8000, v248
	global_load_dwordx4 v[58:61], v147, s[90:91] offset:256
	s_waitcnt vmcnt(12)
	v_pk_add_f32 v[54:55], v[54:55], v[138:139]
	v_pk_add_f32 v[56:57], v[56:57], v[140:141]
	v_pk_add_f32 v[50:51], v[50:51], v[142:143]
	v_pk_add_f32 v[52:53], v[52:53], v[144:145]
	v_mul_f32_e32 v54, 0xbfb8aa3b, v54
	v_mul_f32_e32 v55, 0xbfb8aa3b, v55
	v_exp_f32_e32 v54, v54
	v_exp_f32_e32 v55, v55
	v_add_f32_e32 v54, 1.0, v54
	v_add_f32_e32 v55, 1.0, v55
	v_rcp_f32_e32 v54, v54
	v_rcp_f32_e32 v55, v55
	v_mul_f32_e32 v56, 0xbfb8aa3b, v56
	v_mul_f32_e32 v57, 0xbfb8aa3b, v57
	v_exp_f32_e32 v56, v56
	v_exp_f32_e32 v57, v57
	v_add_f32_e32 v56, 1.0, v56
	v_add_f32_e32 v57, 1.0, v57
	v_rcp_f32_e32 v56, v56
	v_rcp_f32_e32 v57, v57
	v_mul_f32_e32 v50, 0xbfb8aa3b, v50
	v_mul_f32_e32 v51, 0xbfb8aa3b, v51
	v_exp_f32_e32 v50, v50
	v_exp_f32_e32 v51, v51
	v_add_f32_e32 v50, 1.0, v50
	v_add_f32_e32 v51, 1.0, v51
	v_rcp_f32_e32 v50, v50
	v_rcp_f32_e32 v51, v51
	v_mul_f32_e32 v52, 0xbfb8aa3b, v52
	v_mul_f32_e32 v53, 0xbfb8aa3b, v53
	v_exp_f32_e32 v52, v52
	v_exp_f32_e32 v53, v53
	v_add_f32_e32 v52, 1.0, v52
	v_add_f32_e32 v53, 1.0, v53
	v_rcp_f32_e32 v52, v52
	v_rcp_f32_e32 v53, v53
	v_and_b32_e32 v98, s50, v98
	v_and_b32_e32 v99, s50, v99
	v_and_b32_e32 v100, s50, v100
	v_and_b32_e32 v101, s50, v101
	v_lshlrev_b32_e32 v150, 16, v102
	v_and_b32_e32 v102, 0xffff0000, v102
	v_lshlrev_b32_e32 v151, 16, v98
	v_and_b32_e32 v98, 0xffff0000, v98
	v_lshlrev_b32_e32 v152, 16, v103
	v_and_b32_e32 v103, 0xffff0000, v103
	v_lshlrev_b32_e32 v153, 16, v99
	v_and_b32_e32 v99, 0xffff0000, v99
	v_lshlrev_b32_e32 v178, 16, v104
	v_and_b32_e32 v104, 0xffff0000, v104
	v_lshlrev_b32_e32 v179, 16, v100
	v_and_b32_e32 v100, 0xffff0000, v100
	v_lshlrev_b32_e32 v180, 16, v105
	v_and_b32_e32 v105, 0xffff0000, v105
	v_lshlrev_b32_e32 v181, 16, v101
	v_and_b32_e32 v101, 0xffff0000, v101
	v_fmac_f32_e32 v151, v54, v150
	v_fmac_f32_e32 v98, v55, v102
	v_fmac_f32_e32 v153, v56, v152
	v_fmac_f32_e32 v99, v57, v103
	v_fmac_f32_e32 v179, v50, v178
	v_fmac_f32_e32 v100, v51, v104
	v_fmac_f32_e32 v181, v52, v180
	v_fmac_f32_e32 v101, v53, v105
	v_cvt_pk_bf16_f32 v98, v151, v98
	v_cvt_pk_bf16_f32 v99, v153, v99
	v_cvt_pk_bf16_f32 v100, v179, v100
	v_cvt_pk_bf16_f32 v101, v181, v101
	v_add_u32_e32 v146, 0x18000, v248
	global_store_dwordx4 v146, v[98:101], s[90:91] offset:256
	v_add_u32_e32 v147, 0xf0000, v249
	global_load_dwordx4 v[54:57], v147, s[90:91] offset:256
	v_add_u32_e32 v147, 0xf0000, v248
	global_load_dwordx4 v[50:53], v147, s[90:91] offset:256
	s_waitcnt vmcnt(12)
; __device__ __forceinline__ unsigned cvt_pk_bf16(float lo, float hi) { unsigned r; asm volatile("v_cvt_pk_bf16_f32 %0, %1, %2" : "=v"(r) : "v"(lo), "v"(hi)); return r; }
; __device__ __forceinline__ float fsigmoid(float x) { return __builtin_amdgcn_rcpf(1.f + __expf(-x)); }
;     __device__ __forceinline__ void operator()(const f32x4 (&acc)[2][2][4][2], const Unit& u, int wr, int wc, int fr, int fq) const {
;     ...
;         for (int bj = 0; bj < 2; ++bj) { const f32x4 b0 = *(const f32x4*)(bg + br * 1024 + col0 + bj * HALF), b1 = *(const f32x4*)(bg + br * 1024 + col0 + bj * HALF + 4);
; #pragma unroll
;             for (int ai = 0; ai < 2; ++ai)
; #pragma unroll
;                 for (int m = 0; m < 4; ++m) { bf16_t* pm_ = G + (size_t)(row0 + ai * HALF + m * 16) * 3072 + col0 + bj * HALF;
;                     const u32x4 pv = *(const u32x4*)(pm_ + br * 1024); u32x4 mv = (u32x4){0u, 0u, 0u, 0u}; if (br) mv = *(const u32x4*)pm_;
;                     const f32x4 v0 = acc[ai][bj][m][0] + b0, v1 = acc[ai][bj][m][1] + b1;
;                     u32x4 w;
;                     w.x = cvt_pk_bf16(bf_lo(mv.x) + fsigmoid(v0[0]) * bf_lo(pv.x), bf_hi(mv.x) + fsigmoid(v0[1]) * bf_hi(pv.x));
;                     w.y = cvt_pk_bf16(bf_lo(mv.y) + fsigmoid(v0[2]) * bf_lo(pv.y), bf_hi(mv.y) + fsigmoid(v0[3]) * bf_hi(pv.y));
;                     w.z = cvt_pk_bf16(bf_lo(mv.z) + fsigmoid(v1[0]) * bf_lo(pv.z), bf_hi(mv.z) + fsigmoid(v1[1]) * bf_hi(pv.z));
;                     w.w = cvt_pk_bf16(bf_lo(mv.w) + fsigmoid(v1[2]) * bf_lo(pv.w), bf_hi(mv.w) + fsigmoid(v1[3]) * bf_hi(pv.w));
;                     *(u32x4*)pm_ = w; } }
	v_pk_add_f32 v[46:47], v[46:47], v[138:139]
	v_pk_add_f32 v[48:49], v[48:49], v[140:141]
	v_pk_add_f32 v[42:43], v[42:43], v[142:143]
	v_pk_add_f32 v[44:45], v[44:45], v[144:145]
	v_mul_f32_e32 v46, 0xbfb8aa3b, v46
	v_mul_f32_e32 v47, 0xbfb8aa3b, v47
	v_exp_f32_e32 v46, v46
	v_exp_f32_e32 v47, v47
	v_add_f32_e32 v46, 1.0, v46
	v_add_f32_e32 v47, 1.0, v47
	v_rcp_f32_e32 v46, v46
	v_rcp_f32_e32 v47, v47
	v_mul_f32_e32 v48, 0xbfb8aa3b, v48
	v_mul_f32_e32 v49, 0xbfb8aa3b, v49
	v_exp_f32_e32 v48, v48
	v_exp_f32_e32 v49, v49
	v_add_f32_e32 v48, 1.0, v48
	v_add_f32_e32 v49, 1.0, v49
	v_rcp_f32_e32 v48, v48
	v_rcp_f32_e32 v49, v49
	v_mul_f32_e32 v42, 0xbfb8aa3b, v42
	v_mul_f32_e32 v43, 0xbfb8aa3b, v43
	v_exp_f32_e32 v42, v42
	v_exp_f32_e32 v43, v43
	v_add_f32_e32 v42, 1.0, v42
	v_add_f32_e32 v43, 1.0, v43
	v_rcp_f32_e32 v42, v42
	v_rcp_f32_e32 v43, v43
	v_mul_f32_e32 v44, 0xbfb8aa3b, v44
	v_mul_f32_e32 v45, 0xbfb8aa3b, v45
	v_exp_f32_e32 v44, v44
	v_exp_f32_e32 v45, v45
	v_add_f32_e32 v44, 1.0, v44
	v_add_f32_e32 v45, 1.0, v45
	v_rcp_f32_e32 v44, v44
	v_rcp_f32_e32 v45, v45
	v_and_b32_e32 v82, s50, v82
	v_and_b32_e32 v83, s50, v83
	v_and_b32_e32 v84, s50, v84
	v_and_b32_e32 v85, s50, v85
	v_lshlrev_b32_e32 v150, 16, v86
	v_and_b32_e32 v86, 0xffff0000, v86
	v_lshlrev_b32_e32 v151, 16, v82
	v_and_b32_e32 v82, 0xffff0000, v82
	v_lshlrev_b32_e32 v152, 16, v87
	v_and_b32_e32 v87, 0xffff0000, v87
	v_lshlrev_b32_e32 v153, 16, v83
	v_and_b32_e32 v83, 0xffff0000, v83
	v_lshlrev_b32_e32 v178, 16, v88
	v_and_b32_e32 v88, 0xffff0000, v88
	v_lshlrev_b32_e32 v179, 16, v84
	v_and_b32_e32 v84, 0xffff0000, v84
	v_lshlrev_b32_e32 v180, 16, v89
	v_and_b32_e32 v89, 0xffff0000, v89
	v_lshlrev_b32_e32 v181, 16, v85
	v_and_b32_e32 v85, 0xffff0000, v85
	v_fmac_f32_e32 v151, v46, v150
	v_fmac_f32_e32 v82, v47, v86
	v_fmac_f32_e32 v153, v48, v152
	v_fmac_f32_e32 v83, v49, v87
	v_fmac_f32_e32 v179, v42, v178
	v_fmac_f32_e32 v84, v43, v88
	v_fmac_f32_e32 v181, v44, v180
	v_fmac_f32_e32 v85, v45, v89
	v_cvt_pk_bf16_f32 v82, v151, v82
	v_cvt_pk_bf16_f32 v83, v153, v83
	v_cvt_pk_bf16_f32 v84, v179, v84
	v_cvt_pk_bf16_f32 v85, v181, v85
	v_add_u32_e32 v146, 0x30000, v248
	global_store_dwordx4 v146, v[82:85], s[90:91] offset:256
	v_add_u32_e32 v147, 0x108000, v249
	global_load_dwordx4 v[46:49], v147, s[90:91] offset:256
	v_add_u32_e32 v147, 0x108000, v248
	global_load_dwordx4 v[42:45], v147, s[90:91] offset:256
	s_waitcnt vmcnt(12)
	v_pk_add_f32 v[38:39], v[38:39], v[138:139]
	v_pk_add_f32 v[40:41], v[40:41], v[140:141]
	v_pk_add_f32 v[34:35], v[34:35], v[142:143]
	v_pk_add_f32 v[36:37], v[36:37], v[144:145]
	v_mul_f32_e32 v38, 0xbfb8aa3b, v38
	v_mul_f32_e32 v39, 0xbfb8aa3b, v39
	v_exp_f32_e32 v38, v38
	v_exp_f32_e32 v39, v39
	v_add_f32_e32 v38, 1.0, v38
	v_add_f32_e32 v39, 1.0, v39
	v_rcp_f32_e32 v38, v38
	v_rcp_f32_e32 v39, v39
	v_mul_f32_e32 v40, 0xbfb8aa3b, v40
	v_mul_f32_e32 v41, 0xbfb8aa3b, v41
	v_exp_f32_e32 v40, v40
	v_exp_f32_e32 v41, v41
	v_add_f32_e32 v40, 1.0, v40
	v_add_f32_e32 v41, 1.0, v41
	v_rcp_f32_e32 v40, v40
	v_rcp_f32_e32 v41, v41
	v_mul_f32_e32 v34, 0xbfb8aa3b, v34
	v_mul_f32_e32 v35, 0xbfb8aa3b, v35
	v_exp_f32_e32 v34, v34
	v_exp_f32_e32 v35, v35
	v_add_f32_e32 v34, 1.0, v34
	v_add_f32_e32 v35, 1.0, v35
	v_rcp_f32_e32 v34, v34
	v_rcp_f32_e32 v35, v35
	v_mul_f32_e32 v36, 0xbfb8aa3b, v36
	v_mul_f32_e32 v37, 0xbfb8aa3b, v37
	v_exp_f32_e32 v36, v36
	v_exp_f32_e32 v37, v37
	v_add_f32_e32 v36, 1.0, v36
	v_add_f32_e32 v37, 1.0, v37
	v_rcp_f32_e32 v36, v36
	v_rcp_f32_e32 v37, v37
	v_and_b32_e32 v74, s50, v74
	v_and_b32_e32 v75, s50, v75
	v_and_b32_e32 v76, s50, v76
	v_and_b32_e32 v77, s50, v77
	v_lshlrev_b32_e32 v150, 16, v78
	v_and_b32_e32 v78, 0xffff0000, v78
	v_lshlrev_b32_e32 v151, 16, v74
	v_and_b32_e32 v74, 0xffff0000, v74
	v_lshlrev_b32_e32 v152, 16, v79
	v_and_b32_e32 v79, 0xffff0000, v79
	v_lshlrev_b32_e32 v153, 16, v75
	v_and_b32_e32 v75, 0xffff0000, v75
	v_lshlrev_b32_e32 v178, 16, v80
	v_and_b32_e32 v80, 0xffff0000, v80
	v_lshlrev_b32_e32 v179, 16, v76
	v_and_b32_e32 v76, 0xffff0000, v76
	v_lshlrev_b32_e32 v180, 16, v81
	v_and_b32_e32 v81, 0xffff0000, v81
	v_lshlrev_b32_e32 v181, 16, v77
	v_and_b32_e32 v77, 0xffff0000, v77
	v_fmac_f32_e32 v151, v38, v150
	v_fmac_f32_e32 v74, v39, v78
	v_fmac_f32_e32 v153, v40, v152
	v_fmac_f32_e32 v75, v41, v79
	v_fmac_f32_e32 v179, v34, v178
	v_fmac_f32_e32 v76, v35, v80
	v_fmac_f32_e32 v181, v36, v180
	v_fmac_f32_e32 v77, v37, v81
	v_cvt_pk_bf16_f32 v74, v151, v74
	v_cvt_pk_bf16_f32 v75, v153, v75
	v_cvt_pk_bf16_f32 v76, v179, v76
	v_cvt_pk_bf16_f32 v77, v181, v77
	v_add_u32_e32 v146, 0x48000, v248
	global_store_dwordx4 v146, v[74:77], s[90:91] offset:256
	s_waitcnt vmcnt(10)
; __device__ __forceinline__ unsigned cvt_pk_bf16(float lo, float hi) { unsigned r; asm volatile("v_cvt_pk_bf16_f32 %0, %1, %2" : "=v"(r) : "v"(lo), "v"(hi)); return r; }
; __device__ __forceinline__ float fsigmoid(float x) { return __builtin_amdgcn_rcpf(1.f + __expf(-x)); }
;     __device__ __forceinline__ void operator()(const f32x4 (&acc)[2][2][4][2], const Unit& u, int wr, int wc, int fr, int fq) const {
;     ...
;         for (int bj = 0; bj < 2; ++bj) { const f32x4 b0 = *(const f32x4*)(bg + br * 1024 + col0 + bj * HALF), b1 = *(const f32x4*)(bg + br * 1024 + col0 + bj * HALF + 4);
; #pragma unroll
;             for (int ai = 0; ai < 2; ++ai)
; #pragma unroll
;                 for (int m = 0; m < 4; ++m) { bf16_t* pm_ = G + (size_t)(row0 + ai * HALF + m * 16) * 3072 + col0 + bj * HALF;
;                     const u32x4 pv = *(const u32x4*)(pm_ + br * 1024); u32x4 mv = (u32x4){0u, 0u, 0u, 0u}; if (br) mv = *(const u32x4*)pm_;
;                     const f32x4 v0 = acc[ai][bj][m][0] + b0, v1 = acc[ai][bj][m][1] + b1;
;                     u32x4 w;
;                     w.x = cvt_pk_bf16(bf_lo(mv.x) + fsigmoid(v0[0]) * bf_lo(pv.x), bf_hi(mv.x) + fsigmoid(v0[1]) * bf_hi(pv.x));
;                     w.y = cvt_pk_bf16(bf_lo(mv.y) + fsigmoid(v0[2]) * bf_lo(pv.y), bf_hi(mv.y) + fsigmoid(v0[3]) * bf_hi(pv.y));
;                     w.z = cvt_pk_bf16(bf_lo(mv.z) + fsigmoid(v1[0]) * bf_lo(pv.z), bf_hi(mv.z) + fsigmoid(v1[1]) * bf_hi(pv.z));
;                     w.w = cvt_pk_bf16(bf_lo(mv.w) + fsigmoid(v1[2]) * bf_lo(pv.w), bf_hi(mv.w) + fsigmoid(v1[3]) * bf_hi(pv.w));
;                     *(u32x4*)pm_ = w; } }
	v_pk_add_f32 v[30:31], v[30:31], v[138:139]
	v_pk_add_f32 v[32:33], v[32:33], v[140:141]
	v_pk_add_f32 v[26:27], v[26:27], v[142:143]
	v_pk_add_f32 v[28:29], v[28:29], v[144:145]
	v_mul_f32_e32 v30, 0xbfb8aa3b, v30
	v_mul_f32_e32 v31, 0xbfb8aa3b, v31
	v_exp_f32_e32 v30, v30
	v_exp_f32_e32 v31, v31
	v_add_f32_e32 v30, 1.0, v30
	v_add_f32_e32 v31, 1.0, v31
	v_rcp_f32_e32 v30, v30
	v_rcp_f32_e32 v31, v31
	v_mul_f32_e32 v32, 0xbfb8aa3b, v32
	v_mul_f32_e32 v33, 0xbfb8aa3b, v33
	v_exp_f32_e32 v32, v32
	v_exp_f32_e32 v33, v33
	v_add_f32_e32 v32, 1.0, v32
	v_add_f32_e32 v33, 1.0, v33
	v_rcp_f32_e32 v32, v32
	v_rcp_f32_e32 v33, v33
	v_mul_f32_e32 v26, 0xbfb8aa3b, v26
	v_mul_f32_e32 v27, 0xbfb8aa3b, v27
	v_exp_f32_e32 v26, v26
	v_exp_f32_e32 v27, v27
	v_add_f32_e32 v26, 1.0, v26
	v_add_f32_e32 v27, 1.0, v27
	v_rcp_f32_e32 v26, v26
	v_rcp_f32_e32 v27, v27
	v_mul_f32_e32 v28, 0xbfb8aa3b, v28
	v_mul_f32_e32 v29, 0xbfb8aa3b, v29
	v_exp_f32_e32 v28, v28
	v_exp_f32_e32 v29, v29
	v_add_f32_e32 v28, 1.0, v28
	v_add_f32_e32 v29, 1.0, v29
	v_rcp_f32_e32 v28, v28
	v_rcp_f32_e32 v29, v29
	v_and_b32_e32 v66, s50, v66
	v_and_b32_e32 v67, s50, v67
	v_and_b32_e32 v68, s50, v68
	v_and_b32_e32 v69, s50, v69
	v_lshlrev_b32_e32 v150, 16, v70
	v_and_b32_e32 v70, 0xffff0000, v70
	v_lshlrev_b32_e32 v151, 16, v66
	v_and_b32_e32 v66, 0xffff0000, v66
	v_lshlrev_b32_e32 v152, 16, v71
	v_and_b32_e32 v71, 0xffff0000, v71
	v_lshlrev_b32_e32 v153, 16, v67
	v_and_b32_e32 v67, 0xffff0000, v67
	v_lshlrev_b32_e32 v178, 16, v72
	v_and_b32_e32 v72, 0xffff0000, v72
	v_lshlrev_b32_e32 v179, 16, v68
	v_and_b32_e32 v68, 0xffff0000, v68
	v_lshlrev_b32_e32 v180, 16, v73
	v_and_b32_e32 v73, 0xffff0000, v73
	v_lshlrev_b32_e32 v181, 16, v69
	v_and_b32_e32 v69, 0xffff0000, v69
	v_fmac_f32_e32 v151, v30, v150
	v_fmac_f32_e32 v66, v31, v70
	v_fmac_f32_e32 v153, v32, v152
	v_fmac_f32_e32 v67, v33, v71
	v_fmac_f32_e32 v179, v26, v178
	v_fmac_f32_e32 v68, v27, v72
	v_fmac_f32_e32 v181, v28, v180
	v_fmac_f32_e32 v69, v29, v73
	v_cvt_pk_bf16_f32 v66, v151, v66
	v_cvt_pk_bf16_f32 v67, v153, v67
	v_cvt_pk_bf16_f32 v68, v179, v68
	v_cvt_pk_bf16_f32 v69, v181, v69
	v_add_u32_e32 v146, 0xc0000, v248
	global_store_dwordx4 v146, v[66:69], s[90:91] offset:256
	s_waitcnt vmcnt(8)
	v_pk_add_f32 v[22:23], v[22:23], v[138:139]
	v_pk_add_f32 v[24:25], v[24:25], v[140:141]
	v_pk_add_f32 v[18:19], v[18:19], v[142:143]
	v_pk_add_f32 v[20:21], v[20:21], v[144:145]
	v_mul_f32_e32 v22, 0xbfb8aa3b, v22
	v_mul_f32_e32 v23, 0xbfb8aa3b, v23
	v_exp_f32_e32 v22, v22
	v_exp_f32_e32 v23, v23
	v_add_f32_e32 v22, 1.0, v22
	v_add_f32_e32 v23, 1.0, v23
	v_rcp_f32_e32 v22, v22
	v_rcp_f32_e32 v23, v23
	v_mul_f32_e32 v24, 0xbfb8aa3b, v24
	v_mul_f32_e32 v25, 0xbfb8aa3b, v25
	v_exp_f32_e32 v24, v24
	v_exp_f32_e32 v25, v25
	v_add_f32_e32 v24, 1.0, v24
	v_add_f32_e32 v25, 1.0, v25
	v_rcp_f32_e32 v24, v24
	v_rcp_f32_e32 v25, v25
	v_mul_f32_e32 v18, 0xbfb8aa3b, v18
	v_mul_f32_e32 v19, 0xbfb8aa3b, v19
	v_exp_f32_e32 v18, v18
	v_exp_f32_e32 v19, v19
	v_add_f32_e32 v18, 1.0, v18
	v_add_f32_e32 v19, 1.0, v19
	v_rcp_f32_e32 v18, v18
	v_rcp_f32_e32 v19, v19
	v_mul_f32_e32 v20, 0xbfb8aa3b, v20
	v_mul_f32_e32 v21, 0xbfb8aa3b, v21
	v_exp_f32_e32 v20, v20
	v_exp_f32_e32 v21, v21
	v_add_f32_e32 v20, 1.0, v20
	v_add_f32_e32 v21, 1.0, v21
	v_rcp_f32_e32 v20, v20
	v_rcp_f32_e32 v21, v21
	v_and_b32_e32 v58, s50, v58
	v_and_b32_e32 v59, s50, v59
	v_and_b32_e32 v60, s50, v60
	v_and_b32_e32 v61, s50, v61
	v_lshlrev_b32_e32 v150, 16, v62
	v_and_b32_e32 v62, 0xffff0000, v62
	v_lshlrev_b32_e32 v151, 16, v58
	v_and_b32_e32 v58, 0xffff0000, v58
	v_lshlrev_b32_e32 v152, 16, v63
	v_and_b32_e32 v63, 0xffff0000, v63
	v_lshlrev_b32_e32 v153, 16, v59
	v_and_b32_e32 v59, 0xffff0000, v59
	v_lshlrev_b32_e32 v178, 16, v64
	v_and_b32_e32 v64, 0xffff0000, v64
	v_lshlrev_b32_e32 v179, 16, v60
	v_and_b32_e32 v60, 0xffff0000, v60
	v_lshlrev_b32_e32 v180, 16, v65
	v_and_b32_e32 v65, 0xffff0000, v65
	v_lshlrev_b32_e32 v181, 16, v61
	v_and_b32_e32 v61, 0xffff0000, v61
	v_fmac_f32_e32 v151, v22, v150
	v_fmac_f32_e32 v58, v23, v62
	v_fmac_f32_e32 v153, v24, v152
	v_fmac_f32_e32 v59, v25, v63
	v_fmac_f32_e32 v179, v18, v178
	v_fmac_f32_e32 v60, v19, v64
	v_fmac_f32_e32 v181, v20, v180
	v_fmac_f32_e32 v61, v21, v65
	v_cvt_pk_bf16_f32 v58, v151, v58
	v_cvt_pk_bf16_f32 v59, v153, v59
	v_cvt_pk_bf16_f32 v60, v179, v60
	v_cvt_pk_bf16_f32 v61, v181, v61
	v_add_u32_e32 v146, 0xd8000, v248
	global_store_dwordx4 v146, v[58:61], s[90:91] offset:256
	s_waitcnt vmcnt(6)
; #define PG8_SCHED __builtin_amdgcn_sched_barrier(0)
;     __device__ __forceinline__ void operator()(const f32x4 (&acc)[2][2][4][2], const Unit& u, int wr, int wc, int fr, int fq) const {
;     ...
;         for (int bj = 0; bj < 2; ++bj) { const f32x4 b0 = *(const f32x4*)(bg + br * 1024 + col0 + bj * HALF), b1 = *(const f32x4*)(bg + br * 1024 + col0 + bj * HALF + 4);
; #pragma unroll
;             for (int ai = 0; ai < 2; ++ai)
; #pragma unroll
;                 for (int m = 0; m < 4; ++m) { bf16_t* pm_ = G + (size_t)(row0 + ai * HALF + m * 16) * 3072 + col0 + bj * HALF;
;                     const u32x4 pv = *(const u32x4*)(pm_ + br * 1024); u32x4 mv = (u32x4){0u, 0u, 0u, 0u}; if (br) mv = *(const u32x4*)pm_;
;                     const f32x4 v0 = acc[ai][bj][m][0] + b0, v1 = acc[ai][bj][m][1] + b1;
;                     u32x4 w;
;                     w.x = cvt_pk_bf16(bf_lo(mv.x) + fsigmoid(v0[0]) * bf_lo(pv.x), bf_hi(mv.x) + fsigmoid(v0[1]) * bf_hi(pv.x));
;                     w.y = cvt_pk_bf16(bf_lo(mv.y) + fsigmoid(v0[2]) * bf_lo(pv.y), bf_hi(mv.y) + fsigmoid(v0[3]) * bf_hi(pv.y));
;                     w.z = cvt_pk_bf16(bf_lo(mv.z) + fsigmoid(v1[0]) * bf_lo(pv.z), bf_hi(mv.z) + fsigmoid(v1[1]) * bf_hi(pv.z));
;                     w.w = cvt_pk_bf16(bf_lo(mv.w) + fsigmoid(v1[2]) * bf_lo(pv.w), bf_hi(mv.w) + fsigmoid(v1[3]) * bf_hi(pv.w));
;                     *(u32x4*)pm_ = w; } }
; template <class Epi, class Sched, bool ALIGN_EPI = false, bool SP2 = false>
; __device__ __forceinline__ void gemm_phase(PG8_LAS unsigned char* lds, const Gemm g, const Sched& S, const Epi& E) {
;     ...
;         const bool has_next = S.next(ui + 1, nxt);
;         const char* nA = has_next ? (const char*)g.A + (size_t)nxt.pm * tstepA : cA; const char* nB = has_next ? (const char*)g.Bt + (size_t)nxt.pn * tstep : cB;
;         for (int t = 0; t < nt; t += 2) {
;             const bool last = (t == nt - 2);
;             const char* a1 = cA + (size_t)(t + 1) * kstep;
;             const char* a2 = last ? nA : cA + (size_t)(t + 2) * kstep; const char* b2 = last ? nB : cB + (size_t)(t + 2) * kstep;
;             const char* a3 = a2 + kstep; const char* b3 = b2 + kstep;
;             if (last && has_next) S.a_ready(nxt);
;             if constexpr (SP2) {
;             PG8_LDB(B0, 0, 0); PG8_LDB(B1, 0, 1); PG8_SCHED; PG8_LDA(At, 0, 0); PG8_STAGE(PG8_SA(1, 1), a1 + hstepA, voffA);
	v_pk_add_f32 v[14:15], v[14:15], v[138:139]
	v_pk_add_f32 v[16:17], v[16:17], v[140:141]
	v_pk_add_f32 v[10:11], v[10:11], v[142:143]
	v_pk_add_f32 v[12:13], v[12:13], v[144:145]
	v_mul_f32_e32 v14, 0xbfb8aa3b, v14
	v_mul_f32_e32 v15, 0xbfb8aa3b, v15
	v_exp_f32_e32 v14, v14
	v_exp_f32_e32 v15, v15
	v_add_f32_e32 v14, 1.0, v14
	v_add_f32_e32 v15, 1.0, v15
	v_rcp_f32_e32 v14, v14
	v_rcp_f32_e32 v15, v15
	v_mul_f32_e32 v16, 0xbfb8aa3b, v16
	v_mul_f32_e32 v17, 0xbfb8aa3b, v17
	v_exp_f32_e32 v16, v16
	v_exp_f32_e32 v17, v17
	v_add_f32_e32 v16, 1.0, v16
	v_add_f32_e32 v17, 1.0, v17
	v_rcp_f32_e32 v16, v16
	v_rcp_f32_e32 v17, v17
	v_mul_f32_e32 v10, 0xbfb8aa3b, v10
	v_mul_f32_e32 v11, 0xbfb8aa3b, v11
	v_exp_f32_e32 v10, v10
	v_exp_f32_e32 v11, v11
	v_add_f32_e32 v10, 1.0, v10
	v_add_f32_e32 v11, 1.0, v11
	v_rcp_f32_e32 v10, v10
	v_rcp_f32_e32 v11, v11
	v_mul_f32_e32 v12, 0xbfb8aa3b, v12
	v_mul_f32_e32 v13, 0xbfb8aa3b, v13
	v_exp_f32_e32 v12, v12
	v_exp_f32_e32 v13, v13
	v_add_f32_e32 v12, 1.0, v12
	v_add_f32_e32 v13, 1.0, v13
	v_rcp_f32_e32 v12, v12
	v_rcp_f32_e32 v13, v13
	v_and_b32_e32 v50, s50, v50
	v_and_b32_e32 v51, s50, v51
	v_and_b32_e32 v52, s50, v52
	v_and_b32_e32 v53, s50, v53
	v_lshlrev_b32_e32 v150, 16, v54
	v_and_b32_e32 v54, 0xffff0000, v54
	v_lshlrev_b32_e32 v151, 16, v50
	v_and_b32_e32 v50, 0xffff0000, v50
	v_lshlrev_b32_e32 v152, 16, v55
	v_and_b32_e32 v55, 0xffff0000, v55
	v_lshlrev_b32_e32 v153, 16, v51
	v_and_b32_e32 v51, 0xffff0000, v51
	v_lshlrev_b32_e32 v178, 16, v56
	v_and_b32_e32 v56, 0xffff0000, v56
	v_lshlrev_b32_e32 v179, 16, v52
	v_and_b32_e32 v52, 0xffff0000, v52
	v_lshlrev_b32_e32 v180, 16, v57
	v_and_b32_e32 v57, 0xffff0000, v57
	v_lshlrev_b32_e32 v181, 16, v53
	v_and_b32_e32 v53, 0xffff0000, v53
	v_fmac_f32_e32 v151, v14, v150
	v_fmac_f32_e32 v50, v15, v54
	v_fmac_f32_e32 v153, v16, v152
	v_fmac_f32_e32 v51, v17, v55
	v_fmac_f32_e32 v179, v10, v178
	v_fmac_f32_e32 v52, v11, v56
	v_fmac_f32_e32 v181, v12, v180
	v_fmac_f32_e32 v53, v13, v57
	v_cvt_pk_bf16_f32 v50, v151, v50
	v_cvt_pk_bf16_f32 v51, v153, v51
	v_cvt_pk_bf16_f32 v52, v179, v52
	v_cvt_pk_bf16_f32 v53, v181, v53
	v_add_u32_e32 v146, 0xf0000, v248
	global_store_dwordx4 v146, v[50:53], s[90:91] offset:256
	s_waitcnt vmcnt(4)
	v_pk_add_f32 v[6:7], v[6:7], v[138:139]
	v_pk_add_f32 v[8:9], v[8:9], v[140:141]
	v_pk_add_f32 v[2:3], v[2:3], v[142:143]
	v_pk_add_f32 v[4:5], v[4:5], v[144:145]
	v_mul_f32_e32 v6, 0xbfb8aa3b, v6
	v_mul_f32_e32 v7, 0xbfb8aa3b, v7
	v_exp_f32_e32 v6, v6
	v_exp_f32_e32 v7, v7
	v_add_f32_e32 v6, 1.0, v6
	v_add_f32_e32 v7, 1.0, v7
	v_rcp_f32_e32 v6, v6
	v_rcp_f32_e32 v7, v7
	v_mul_f32_e32 v8, 0xbfb8aa3b, v8
	v_mul_f32_e32 v9, 0xbfb8aa3b, v9
	v_exp_f32_e32 v8, v8
	v_exp_f32_e32 v9, v9
	v_add_f32_e32 v8, 1.0, v8
	v_add_f32_e32 v9, 1.0, v9
	v_rcp_f32_e32 v8, v8
	v_rcp_f32_e32 v9, v9
	v_mul_f32_e32 v2, 0xbfb8aa3b, v2
	v_mul_f32_e32 v3, 0xbfb8aa3b, v3
	v_exp_f32_e32 v2, v2
	v_exp_f32_e32 v3, v3
	v_add_f32_e32 v2, 1.0, v2
	v_add_f32_e32 v3, 1.0, v3
	v_rcp_f32_e32 v2, v2
	v_rcp_f32_e32 v3, v3
	v_mul_f32_e32 v4, 0xbfb8aa3b, v4
	v_mul_f32_e32 v5, 0xbfb8aa3b, v5
	v_exp_f32_e32 v4, v4
	v_exp_f32_e32 v5, v5
	v_add_f32_e32 v4, 1.0, v4
	v_add_f32_e32 v5, 1.0, v5
	v_rcp_f32_e32 v4, v4
	v_rcp_f32_e32 v5, v5
	v_and_b32_e32 v42, s50, v42
	v_and_b32_e32 v43, s50, v43
	v_and_b32_e32 v44, s50, v44
	v_and_b32_e32 v45, s50, v45
	v_lshlrev_b32_e32 v150, 16, v46
	v_and_b32_e32 v46, 0xffff0000, v46
	v_lshlrev_b32_e32 v151, 16, v42
	v_and_b32_e32 v42, 0xffff0000, v42
	v_lshlrev_b32_e32 v152, 16, v47
	v_and_b32_e32 v47, 0xffff0000, v47
	v_lshlrev_b32_e32 v153, 16, v43
	v_and_b32_e32 v43, 0xffff0000, v43
	v_lshlrev_b32_e32 v178, 16, v48
	v_and_b32_e32 v48, 0xffff0000, v48
	v_lshlrev_b32_e32 v179, 16, v44
	v_and_b32_e32 v44, 0xffff0000, v44
	v_lshlrev_b32_e32 v180, 16, v49
	v_and_b32_e32 v49, 0xffff0000, v49
	v_lshlrev_b32_e32 v181, 16, v45
	v_and_b32_e32 v45, 0xffff0000, v45
	v_fmac_f32_e32 v151, v6, v150
	v_fmac_f32_e32 v42, v7, v46
	v_fmac_f32_e32 v153, v8, v152
	v_fmac_f32_e32 v43, v9, v47
	v_fmac_f32_e32 v179, v2, v178
	v_fmac_f32_e32 v44, v3, v48
	v_fmac_f32_e32 v181, v4, v180
	v_fmac_f32_e32 v45, v5, v49
	v_cvt_pk_bf16_f32 v42, v151, v42
	v_cvt_pk_bf16_f32 v43, v153, v43
	v_cvt_pk_bf16_f32 v44, v179, v44
	v_cvt_pk_bf16_f32 v45, v181, v45
	v_add_u32_e32 v146, 0x108000, v248
	global_store_dwordx4 v146, v[42:45], s[90:91] offset:256
	s_andn2_b64 vcc, exec, s[42:43]
	s_mov_b64 s[38:39], -1
	s_cbranch_vccnz .LBB0_265
	s_andn2_b64 vcc, exec, s[0:1]
	s_cbranch_vccnz .LBB0_264
	s_barrier
	s_branch .LBB0_264

; #define LAS __attribute__((address_space(3)))
; #define MFMA16(a, b, c) __builtin_amdgcn_mfma_f32_16x16x32_bf16(a, b, c, 0, 0, 0)
; __device__ __forceinline__ void memattn_group(const Params& p, LAS unsigned char* lds, int grp, const int tid) {
;     ...
;     const bf16* kbase = MKV + (size_t)(bi * 256) * 1024 + h * 128; const bf16* vbase = kbase + 512;
;     { v4u kr[8], vr8[8];
; #pragma unroll
;       for (int k = 0; k < 8; ++k) { const int c = k * 512 + tid; kr[k] = *(const v4u*)(kbase + (size_t)(c >> 4) * 1024 + (c & 15) * 8); vr8[k] = *(const v4u*)(vbase + (size_t)(c >> 4) * 1024 + (c & 15) * 8); }
; #pragma unroll
;       for (int k = 0; k < 8; ++k) { const int c = k * 512 + tid; *(LAS v4u*)(lds + MA_KS + (c >> 4) * 272 + (c & 15) * 16) = kr[k];
;           *(LAS v4u*)(lds + MA_VT + (c >> 4) * 288 + (c & 15) * 16) = vr8[k]; } }
;     bf16x8 qn[4];
;     { const bf16* qp = QM + (size_t)(mg + 16 * w + fr) * 512 + h * 128 + 8 * fq;
; #pragma unroll
;       for (int ks = 0; ks < 4; ++ks) qn[ks] = *(const bf16x8*)(qp + 32 * ks); }
;     __syncthreads();
; #pragma nounroll
;     for (int j = 0; j < 4; ++j) {
;         asm volatile("" ::: "memory");
;         const int m0 = mg + j * 128;
;         bf16x8 qa[4];
; #pragma unroll
;         for (int ks = 0; ks < 4; ++ks) qa[ks] = qn[ks];
;         if (j < 3) { const bf16* qp = QM + (size_t)(m0 + 128 + 16 * w + fr) * 512 + h * 128 + 8 * fq;
; #pragma unroll
;             for (int ks = 0; ks < 4; ++ks) qn[ks] = *(const bf16x8*)(qp + 32 * ks); }
;         f32x4 st[16]; float mx = -3e38f;
; #pragma unroll
;         for (int ct = 0; ct < 16; ++ct) { st[ct] = (f32x4){0.f, 0.f, 0.f, 0.f};
; #pragma unroll
;             for (int ks = 0; ks < 4; ++ks) { const bf16x8 kb = *(const LAS bf16x8*)(lds + MA_KS + (16 * ct + fr) * 272 + (32 * ks + 8 * fq) * 2); st[ct] = MFMA16(kb, qa[ks], st[ct]); }
;             mx = fmaxf(fmaxf(mx, fmaxf(st[ct][0], st[ct][1])), fmaxf(st[ct][2], st[ct][3])); }
.LBB0_499:
	s_lshl_b32 s1, s4, 9
	s_and_b32 s8, s0, s1
	s_lshl_b32 s0, s7, 8
	s_ashr_i32 s1, s0, 31
	s_or_b32 s9, s5, s8
	s_lshl_b64 s[0:1], s[0:1], 11
	s_add_u32 s0, s70, s0
	s_addc_u32 s1, s71, s1
	s_lshl_b32 s6, s6, 8
	s_and_b32 s86, s6, 0x300
	s_add_u32 s0, s0, s86
	s_addc_u32 s1, s1, 0
	v_mov_b32_e32 v113, v0
	v_lshl_add_u64 v[58:59], s[0:1], 0, v[112:113]
	v_lshl_add_u64 v[6:7], v[94:95], 1, v[58:59]
	v_lshl_add_u64 v[14:15], v[96:97], 1, v[58:59]
	v_lshl_add_u64 v[22:23], v[98:99], 1, v[58:59]
	v_lshl_add_u64 v[30:31], v[102:103], 1, v[58:59]
	v_lshl_add_u64 v[38:39], v[104:105], 1, v[58:59]
	v_lshl_add_u64 v[46:47], v[106:107], 1, v[58:59]
	v_lshl_add_u64 v[54:55], v[108:109], 1, v[58:59]
	v_lshl_add_u64 v[62:63], v[110:111], 1, v[58:59]
	global_load_dwordx4 v[2:5], v[6:7], off
	s_nop 0
	global_load_dwordx4 v[6:9], v[6:7], off offset:1024
	s_nop 0
	global_load_dwordx4 v[10:13], v[14:15], off
	s_nop 0
	global_load_dwordx4 v[14:17], v[14:15], off offset:1024
	s_nop 0
	global_load_dwordx4 v[18:21], v[22:23], off
	s_nop 0
	global_load_dwordx4 v[22:25], v[22:23], off offset:1024
	s_nop 0
	global_load_dwordx4 v[26:29], v[30:31], off
	s_nop 0
	global_load_dwordx4 v[30:33], v[30:31], off offset:1024
	s_nop 0
	global_load_dwordx4 v[34:37], v[38:39], off
	s_nop 0
	global_load_dwordx4 v[38:41], v[38:39], off offset:1024
	s_nop 0
	global_load_dwordx4 v[42:45], v[46:47], off
	s_nop 0
	global_load_dwordx4 v[46:49], v[46:47], off offset:1024
	s_nop 0
	global_load_dwordx4 v[50:53], v[54:55], off
	s_nop 0
	global_load_dwordx4 v[54:57], v[54:55], off offset:1024
	s_nop 0
	global_load_dwordx4 v[58:61], v[62:63], off
	s_nop 0
	global_load_dwordx4 v[62:65], v[62:63], off offset:1024
	v_readlane_b32 s0, v252, 61
	v_readlane_b32 s1, v252, 62
	v_mov_b32_e32 v115, v0
	v_mov_b32_e32 v117, v0
	s_waitcnt vmcnt(0)
	ds_write_b128 v137, v[2:5]
	ds_write_b128 v138, v[6:9]
	ds_write_b128 v139, v[10:13]
	ds_write_b128 v140, v[14:17]
	ds_write_b128 v141, v[18:21]
	ds_write_b128 v142, v[22:25]
	ds_write_b128 v143, v[26:29]
	ds_write_b128 v144, v[30:33]
	ds_write_b128 v145, v[34:37]
	ds_write_b128 v146, v[38:41]
	ds_write_b128 v147, v[42:45]
	ds_write_b128 v157, v[46:49]
	ds_write_b128 v165, v[50:53]
	ds_write_b128 v166, v[54:57]
	ds_write_b128 v167, v[58:61]
	ds_write_b128 v168, v[62:65]
	v_add_u32_e32 v2, s9, v127
	v_ashrrev_i32_e32 v3, 31, v2
	v_lshlrev_b64 v[2:3], 10, v[2:3]
	v_lshl_add_u64 v[2:3], s[0:1], 0, v[2:3]
	v_lshl_add_u64 v[2:3], v[2:3], 0, s[86:87]
	v_lshl_add_u64 v[2:3], v[2:3], 0, v[114:115]
	global_load_dwordx4 v[30:33], v[2:3], off
	global_load_dwordx4 v[26:29], v[2:3], off offset:64
	global_load_dwordx4 v[22:25], v[2:3], off offset:128
	global_load_dwordx4 v[18:21], v[2:3], off offset:192
	s_add_u32 s0, s0, s86
	s_addc_u32 s1, s1, 0
	s_add_i32 s8, s8, s5
	v_lshl_add_u64 v[118:119], s[0:1], 0, v[114:115]
	v_lshl_add_u64 v[120:121], s[0:1], 0, v[116:117]
	v_add_u32_e32 v113, s8, v127
	s_mov_b32 s5, 0
	s_waitcnt lgkmcnt(0)
	s_waitcnt vmcnt(0)
	s_barrier
	s_branch .LBB0_501
.LBB0_500:
	ds_read_b128 v[34:37], v169
	ds_read_b128 v[38:41], v169 offset:64
	s_addk_i32 s5, 0x80
	s_cmpk_lg_i32 s5, 0x200
	s_waitcnt lgkmcnt(1)
	v_mfma_f32_16x16x32_bf16 v[34:37], v[34:37], v[30:33], 0
	ds_read_b128 v[42:45], v169 offset:4416
	ds_read_b128 v[150:153], v169 offset:60992
	s_waitcnt lgkmcnt(2)
	v_mfma_f32_16x16x32_bf16 v[34:37], v[38:41], v[26:29], v[34:37]
	ds_read_b128 v[38:41], v169 offset:128
	s_waitcnt lgkmcnt(0)
	v_mfma_f32_16x16x32_bf16 v[34:37], v[38:41], v[22:25], v[34:37]
	ds_read_b128 v[38:41], v169 offset:192
	s_waitcnt lgkmcnt(0)
	v_mfma_f32_16x16x32_bf16 v[34:37], v[38:41], v[18:21], v[34:37]
	s_nop 7
	v_max_f32_e32 v38, v35, v35
	v_max_f32_e32 v39, v34, v34
	v_max_f32_e32 v38, v39, v38
	v_max_f32_e32 v39, v37, v37
	v_max_f32_e32 v40, v36, v36
	v_max_f32_e32 v39, v40, v39
	v_max3_f32 v46, v38, s12, v39
	ds_read_b128 v[38:41], v169 offset:4352
	s_waitcnt lgkmcnt(0)
	v_mfma_f32_16x16x32_bf16 v[38:41], v[38:41], v[30:33], 0
	v_mfma_f32_16x16x32_bf16 v[38:41], v[42:45], v[26:29], v[38:41]
	ds_read_b128 v[42:45], v169 offset:4480
	s_waitcnt lgkmcnt(0)
	v_mfma_f32_16x16x32_bf16 v[38:41], v[42:45], v[22:25], v[38:41]
	ds_read_b128 v[42:45], v169 offset:4544
	s_waitcnt lgkmcnt(0)
	v_mfma_f32_16x16x32_bf16 v[38:41], v[42:45], v[18:21], v[38:41]
	s_nop 7
	v_max_f32_e32 v42, v39, v39
	v_max_f32_e32 v43, v38, v38
	v_max_f32_e32 v42, v43, v42
	v_max_f32_e32 v43, v41, v41
	v_max_f32_e32 v44, v40, v40
	v_max_f32_e32 v43, v44, v43
	v_max3_f32 v50, v46, v42, v43
	ds_read_b128 v[42:45], v169 offset:8704
	ds_read_b128 v[46:49], v169 offset:8768
	s_waitcnt lgkmcnt(1)
	v_mfma_f32_16x16x32_bf16 v[42:45], v[42:45], v[30:33], 0
	s_waitcnt lgkmcnt(0)
	v_mfma_f32_16x16x32_bf16 v[42:45], v[46:49], v[26:29], v[42:45]
	ds_read_b128 v[46:49], v169 offset:8832
	s_waitcnt lgkmcnt(0)
	v_mfma_f32_16x16x32_bf16 v[42:45], v[46:49], v[22:25], v[42:45]
	ds_read_b128 v[46:49], v169 offset:8896
	s_waitcnt lgkmcnt(0)
	v_mfma_f32_16x16x32_bf16 v[42:45], v[46:49], v[18:21], v[42:45]
	s_nop 7
	v_max_f32_e32 v46, v43, v43
	v_max_f32_e32 v47, v42, v42
	v_max_f32_e32 v46, v47, v46
	v_max_f32_e32 v47, v45, v45
	v_max_f32_e32 v48, v44, v44
	v_max_f32_e32 v47, v48, v47
	v_max3_f32 v54, v50, v46, v47
	ds_read_b128 v[46:49], v169 offset:13056
	ds_read_b128 v[50:53], v169 offset:13120
	s_waitcnt lgkmcnt(1)
	v_mfma_f32_16x16x32_bf16 v[46:49], v[46:49], v[30:33], 0
	s_waitcnt lgkmcnt(0)
	v_mfma_f32_16x16x32_bf16 v[46:49], v[50:53], v[26:29], v[46:49]
	ds_read_b128 v[50:53], v169 offset:13184
	s_waitcnt lgkmcnt(0)
	v_mfma_f32_16x16x32_bf16 v[46:49], v[50:53], v[22:25], v[46:49]
	ds_read_b128 v[50:53], v169 offset:13248
	s_waitcnt lgkmcnt(0)
; #define LAS __attribute__((address_space(3)))
; #define MFMA16(a, b, c) __builtin_amdgcn_mfma_f32_16x16x32_bf16(a, b, c, 0, 0, 0)
; __device__ __forceinline__ void memattn_group(const Params& p, LAS unsigned char* lds, int grp, const int tid) {
;     ...
;         f32x4 st[16]; float mx = -3e38f;
; #pragma unroll
;         for (int ct = 0; ct < 16; ++ct) { st[ct] = (f32x4){0.f, 0.f, 0.f, 0.f};
; #pragma unroll
;             for (int ks = 0; ks < 4; ++ks) { const bf16x8 kb = *(const LAS bf16x8*)(lds + MA_KS + (16 * ct + fr) * 272 + (32 * ks + 8 * fq) * 2); st[ct] = MFMA16(kb, qa[ks], st[ct]); }
;             mx = fmaxf(fmaxf(mx, fmaxf(st[ct][0], st[ct][1])), fmaxf(st[ct][2], st[ct][3])); }
	v_mfma_f32_16x16x32_bf16 v[46:49], v[50:53], v[18:21], v[46:49]
	s_nop 7
	v_max_f32_e32 v50, v47, v47
	v_max_f32_e32 v51, v46, v46
	v_max_f32_e32 v50, v51, v50
	v_max_f32_e32 v51, v49, v49
	v_max_f32_e32 v52, v48, v48
	v_max_f32_e32 v51, v52, v51
	v_max3_f32 v58, v54, v50, v51
	ds_read_b128 v[50:53], v169 offset:17408
	ds_read_b128 v[54:57], v169 offset:17472
	s_waitcnt lgkmcnt(1)
	v_mfma_f32_16x16x32_bf16 v[50:53], v[50:53], v[30:33], 0
	s_waitcnt lgkmcnt(0)
	v_mfma_f32_16x16x32_bf16 v[50:53], v[54:57], v[26:29], v[50:53]
	ds_read_b128 v[54:57], v169 offset:17536
	s_waitcnt lgkmcnt(0)
	v_mfma_f32_16x16x32_bf16 v[50:53], v[54:57], v[22:25], v[50:53]
	ds_read_b128 v[54:57], v169 offset:17600
	s_waitcnt lgkmcnt(0)
	v_mfma_f32_16x16x32_bf16 v[50:53], v[54:57], v[18:21], v[50:53]
	s_nop 7
	v_max_f32_e32 v54, v51, v51
	v_max_f32_e32 v55, v50, v50
	v_max_f32_e32 v54, v55, v54
	v_max_f32_e32 v55, v53, v53
	v_max_f32_e32 v56, v52, v52
	v_max_f32_e32 v55, v56, v55
	v_max3_f32 v62, v58, v54, v55
	ds_read_b128 v[54:57], v169 offset:21760
	ds_read_b128 v[58:61], v169 offset:21824
	s_waitcnt lgkmcnt(1)
	v_mfma_f32_16x16x32_bf16 v[54:57], v[54:57], v[30:33], 0
	s_waitcnt lgkmcnt(0)
	v_mfma_f32_16x16x32_bf16 v[54:57], v[58:61], v[26:29], v[54:57]
	ds_read_b128 v[58:61], v169 offset:21888
	s_waitcnt lgkmcnt(0)
	v_mfma_f32_16x16x32_bf16 v[54:57], v[58:61], v[22:25], v[54:57]
	ds_read_b128 v[58:61], v169 offset:21952
	s_waitcnt lgkmcnt(0)
	v_mfma_f32_16x16x32_bf16 v[54:57], v[58:61], v[18:21], v[54:57]
	s_nop 7
	v_max_f32_e32 v58, v55, v55
	v_max_f32_e32 v59, v54, v54
	v_max_f32_e32 v58, v59, v58
	v_max_f32_e32 v59, v57, v57
	v_max_f32_e32 v60, v56, v56
	v_max_f32_e32 v59, v60, v59
	v_max3_f32 v66, v62, v58, v59
	ds_read_b128 v[58:61], v169 offset:26112
	ds_read_b128 v[62:65], v169 offset:26176
	s_waitcnt lgkmcnt(1)
	v_mfma_f32_16x16x32_bf16 v[58:61], v[58:61], v[30:33], 0
	s_waitcnt lgkmcnt(0)
	v_mfma_f32_16x16x32_bf16 v[58:61], v[62:65], v[26:29], v[58:61]
	ds_read_b128 v[62:65], v169 offset:26240
	s_waitcnt lgkmcnt(0)
	v_mfma_f32_16x16x32_bf16 v[58:61], v[62:65], v[22:25], v[58:61]
	ds_read_b128 v[62:65], v169 offset:26304
	s_waitcnt lgkmcnt(0)
	v_mfma_f32_16x16x32_bf16 v[58:61], v[62:65], v[18:21], v[58:61]
	s_nop 7
	v_max_f32_e32 v62, v59, v59
	v_max_f32_e32 v63, v58, v58
	v_max_f32_e32 v62, v63, v62
	v_max_f32_e32 v63, v61, v61
	v_max_f32_e32 v64, v60, v60
	v_max_f32_e32 v63, v64, v63
	v_max3_f32 v70, v66, v62, v63
	ds_read_b128 v[62:65], v169 offset:30464
	ds_read_b128 v[66:69], v169 offset:30528
	s_waitcnt lgkmcnt(1)
	v_mfma_f32_16x16x32_bf16 v[62:65], v[62:65], v[30:33], 0
	s_waitcnt lgkmcnt(0)
	v_mfma_f32_16x16x32_bf16 v[62:65], v[66:69], v[26:29], v[62:65]
	ds_read_b128 v[66:69], v169 offset:30592
	s_waitcnt lgkmcnt(0)
	v_mfma_f32_16x16x32_bf16 v[62:65], v[66:69], v[22:25], v[62:65]
	ds_read_b128 v[66:69], v169 offset:30656
	s_waitcnt lgkmcnt(0)
	v_mfma_f32_16x16x32_bf16 v[62:65], v[66:69], v[18:21], v[62:65]
	s_nop 7
	v_max_f32_e32 v66, v63, v63
	v_max_f32_e32 v67, v62, v62
	v_max_f32_e32 v66, v67, v66
	v_max_f32_e32 v67, v65, v65
	v_max_f32_e32 v68, v64, v64
	v_max_f32_e32 v67, v68, v67
	v_max3_f32 v74, v70, v66, v67
	ds_read_b128 v[66:69], v169 offset:34816
	ds_read_b128 v[70:73], v169 offset:34880
	s_waitcnt lgkmcnt(1)
	v_mfma_f32_16x16x32_bf16 v[66:69], v[66:69], v[30:33], 0
	s_waitcnt lgkmcnt(0)
	v_mfma_f32_16x16x32_bf16 v[66:69], v[70:73], v[26:29], v[66:69]
	ds_read_b128 v[70:73], v169 offset:34944
	s_waitcnt lgkmcnt(0)
	v_mfma_f32_16x16x32_bf16 v[66:69], v[70:73], v[22:25], v[66:69]
	ds_read_b128 v[70:73], v169 offset:35008
	s_waitcnt lgkmcnt(0)
	v_mfma_f32_16x16x32_bf16 v[66:69], v[70:73], v[18:21], v[66:69]
	s_nop 7
	v_max_f32_e32 v70, v67, v67
	v_max_f32_e32 v71, v66, v66
	v_max_f32_e32 v70, v71, v70
	v_max_f32_e32 v71, v69, v69
	v_max_f32_e32 v72, v68, v68
	v_max_f32_e32 v71, v72, v71
	v_max3_f32 v78, v74, v70, v71
	ds_read_b128 v[70:73], v169 offset:39168
	ds_read_b128 v[74:77], v169 offset:39232
	s_waitcnt lgkmcnt(1)
	v_mfma_f32_16x16x32_bf16 v[70:73], v[70:73], v[30:33], 0
	s_waitcnt lgkmcnt(0)
	v_mfma_f32_16x16x32_bf16 v[70:73], v[74:77], v[26:29], v[70:73]
	ds_read_b128 v[74:77], v169 offset:39296
	s_waitcnt lgkmcnt(0)
	v_mfma_f32_16x16x32_bf16 v[70:73], v[74:77], v[22:25], v[70:73]
	ds_read_b128 v[74:77], v169 offset:39360
	s_waitcnt lgkmcnt(0)
	v_mfma_f32_16x16x32_bf16 v[70:73], v[74:77], v[18:21], v[70:73]
	s_nop 7
	v_max_f32_e32 v74, v71, v71
	v_max_f32_e32 v75, v70, v70
	v_max_f32_e32 v74, v75, v74
	v_max_f32_e32 v75, v73, v73
	v_max_f32_e32 v76, v72, v72
	v_max_f32_e32 v75, v76, v75
	v_max3_f32 v82, v78, v74, v75
	ds_read_b128 v[74:77], v169 offset:43520
	ds_read_b128 v[78:81], v169 offset:43584
	s_waitcnt lgkmcnt(1)
	v_mfma_f32_16x16x32_bf16 v[74:77], v[74:77], v[30:33], 0
	s_waitcnt lgkmcnt(0)
	v_mfma_f32_16x16x32_bf16 v[74:77], v[78:81], v[26:29], v[74:77]
	ds_read_b128 v[78:81], v169 offset:43648
	s_waitcnt lgkmcnt(0)
	v_mfma_f32_16x16x32_bf16 v[74:77], v[78:81], v[22:25], v[74:77]
	ds_read_b128 v[78:81], v169 offset:43712
	s_waitcnt lgkmcnt(0)
	v_mfma_f32_16x16x32_bf16 v[74:77], v[78:81], v[18:21], v[74:77]
	s_nop 7
	v_max_f32_e32 v78, v75, v75
	v_max_f32_e32 v79, v74, v74
	v_max_f32_e32 v78, v79, v78
	v_max_f32_e32 v79, v77, v77
	v_max_f32_e32 v80, v76, v76
	v_max_f32_e32 v79, v80, v79
	v_max3_f32 v86, v82, v78, v79
	ds_read_b128 v[78:81], v169 offset:47872
	ds_read_b128 v[82:85], v169 offset:47936
	s_waitcnt lgkmcnt(1)
	v_mfma_f32_16x16x32_bf16 v[78:81], v[78:81], v[30:33], 0
	s_waitcnt lgkmcnt(0)
	v_mfma_f32_16x16x32_bf16 v[78:81], v[82:85], v[26:29], v[78:81]
	ds_read_b128 v[82:85], v169 offset:48000
	s_waitcnt lgkmcnt(0)
; #define LAS __attribute__((address_space(3)))
; #define MFMA16(a, b, c) __builtin_amdgcn_mfma_f32_16x16x32_bf16(a, b, c, 0, 0, 0)
; __device__ __forceinline__ void memattn_group(const Params& p, LAS unsigned char* lds, int grp, const int tid) {
;     ...
;         for (int ct = 0; ct < 16; ++ct) { st[ct] = (f32x4){0.f, 0.f, 0.f, 0.f};
; #pragma unroll
;             for (int ks = 0; ks < 4; ++ks) { const bf16x8 kb = *(const LAS bf16x8*)(lds + MA_KS + (16 * ct + fr) * 272 + (32 * ks + 8 * fq) * 2); st[ct] = MFMA16(kb, qa[ks], st[ct]); }
;             mx = fmaxf(fmaxf(mx, fmaxf(st[ct][0], st[ct][1])), fmaxf(st[ct][2], st[ct][3])); }
;         mx = fmaxf(mx, __shfl_xor(mx, 16)); mx = fmaxf(mx, __shfl_xor(mx, 32));
;         float sm = 0.f;
; #pragma unroll
;         for (int ct = 0; ct < 16; ++ct)
; #pragma unroll
;             for (int e = 0; e < 4; ++e) { const float pv = __expf(st[ct][e] - mx); st[ct][e] = pv; sm += pv; }
	v_mfma_f32_16x16x32_bf16 v[78:81], v[82:85], v[22:25], v[78:81]
	ds_read_b128 v[82:85], v169 offset:48064
	s_waitcnt lgkmcnt(0)
	v_mfma_f32_16x16x32_bf16 v[78:81], v[82:85], v[18:21], v[78:81]
	s_nop 7
	v_max_f32_e32 v82, v79, v79
	v_max_f32_e32 v83, v78, v78
	v_max_f32_e32 v82, v83, v82
	v_max_f32_e32 v83, v81, v81
	v_max_f32_e32 v84, v80, v80
	v_max_f32_e32 v83, v84, v83
	v_max3_f32 v90, v86, v82, v83
	ds_read_b128 v[82:85], v169 offset:52224
	ds_read_b128 v[86:89], v169 offset:52288
	s_waitcnt lgkmcnt(1)
	v_mfma_f32_16x16x32_bf16 v[82:85], v[82:85], v[30:33], 0
	s_waitcnt lgkmcnt(0)
	v_mfma_f32_16x16x32_bf16 v[82:85], v[86:89], v[26:29], v[82:85]
	ds_read_b128 v[86:89], v169 offset:52352
	s_waitcnt lgkmcnt(0)
	v_mfma_f32_16x16x32_bf16 v[82:85], v[86:89], v[22:25], v[82:85]
	ds_read_b128 v[86:89], v169 offset:52416
	s_waitcnt lgkmcnt(0)
	v_mfma_f32_16x16x32_bf16 v[82:85], v[86:89], v[18:21], v[82:85]
	s_nop 7
	v_max_f32_e32 v86, v83, v83
	v_max_f32_e32 v87, v82, v82
	v_max_f32_e32 v86, v87, v86
	v_max_f32_e32 v87, v85, v85
	v_max_f32_e32 v88, v84, v84
	v_max_f32_e32 v87, v88, v87
	v_max3_f32 v115, v90, v86, v87
	ds_read_b128 v[86:89], v169 offset:56576
	ds_read_b128 v[90:93], v169 offset:56640
	s_waitcnt lgkmcnt(1)
	v_mfma_f32_16x16x32_bf16 v[86:89], v[86:89], v[30:33], 0
	s_waitcnt lgkmcnt(0)
	v_mfma_f32_16x16x32_bf16 v[86:89], v[90:93], v[26:29], v[86:89]
	ds_read_b128 v[90:93], v169 offset:56704
	s_waitcnt lgkmcnt(0)
	v_mfma_f32_16x16x32_bf16 v[86:89], v[90:93], v[22:25], v[86:89]
	ds_read_b128 v[90:93], v169 offset:56768
	s_waitcnt lgkmcnt(0)
	v_mfma_f32_16x16x32_bf16 v[86:89], v[90:93], v[18:21], v[86:89]
	s_nop 7
	v_max_f32_e32 v90, v87, v87
	v_max_f32_e32 v91, v86, v86
	v_max_f32_e32 v90, v91, v90
	v_max_f32_e32 v91, v89, v89
	v_max_f32_e32 v92, v88, v88
	v_max_f32_e32 v91, v92, v91
	v_max3_f32 v115, v115, v90, v91
	ds_read_b128 v[90:93], v169 offset:60928
	s_waitcnt lgkmcnt(0)
	v_mfma_f32_16x16x32_bf16 v[90:93], v[90:93], v[30:33], 0
	v_mfma_f32_16x16x32_bf16 v[90:93], v[150:153], v[26:29], v[90:93]
	ds_read_b128 v[150:153], v169 offset:61056
	s_waitcnt lgkmcnt(0)
	v_mfma_f32_16x16x32_bf16 v[90:93], v[150:153], v[22:25], v[90:93]
	ds_read_b128 v[150:153], v169 offset:61120
	s_waitcnt lgkmcnt(0)
	v_mfma_f32_16x16x32_bf16 v[90:93], v[150:153], v[18:21], v[90:93]
	s_nop 7
	v_max_f32_e32 v117, v91, v91
	v_max_f32_e32 v123, v90, v90
	v_max_f32_e32 v117, v123, v117
	v_max_f32_e32 v123, v93, v93
	v_max_f32_e32 v150, v92, v92
	v_max_f32_e32 v123, v150, v123
	ds_read_b128 v[150:153], v169 offset:65280
	s_waitcnt lgkmcnt(0)
	v_mfma_f32_16x16x32_bf16 v[30:33], v[150:153], v[30:33], 0
	ds_read_b128 v[150:153], v169 offset:65344
	v_max3_f32 v115, v115, v117, v123
	s_waitcnt lgkmcnt(0)
	v_mfma_f32_16x16x32_bf16 v[26:29], v[150:153], v[26:29], v[30:33]
	s_nop 3
	ds_read_b128 v[30:33], v169 offset:65408
	s_waitcnt lgkmcnt(0)
	v_mfma_f32_16x16x32_bf16 v[22:25], v[30:33], v[22:25], v[26:29]
	s_nop 2
	ds_read_b128 v[26:29], v169 offset:65472
	s_waitcnt lgkmcnt(0)
	v_mfma_f32_16x16x32_bf16 v[18:21], v[26:29], v[18:21], v[22:25]
	s_nop 7
	v_max_f32_e32 v22, v19, v19
	v_max_f32_e32 v23, v18, v18
	v_max_f32_e32 v22, v23, v22
	v_max_f32_e32 v23, v21, v21
	v_max_f32_e32 v24, v20, v20
	v_max_f32_e32 v23, v24, v23
	v_and_b32_e32 v24, 64, v231
	v_max3_f32 v22, v115, v22, v23
	v_xor_b32_e32 v23, 16, v231
	v_add_u32_e32 v24, 64, v24
	v_cmp_lt_i32_e32 vcc, v23, v24
	s_nop 1
	v_cndmask_b32_e32 v23, v231, v23, vcc
	v_lshlrev_b32_e32 v26, 2, v23
	ds_bpermute_b32 v23, v26, v22
	s_waitcnt lgkmcnt(0)
	v_max_f32_e32 v23, v23, v23
	v_max_f32_e32 v22, v22, v23
	v_xor_b32_e32 v23, 32, v231
	v_cmp_lt_i32_e32 vcc, v23, v24
	s_nop 1
	v_cndmask_b32_e32 v23, v231, v23, vcc
	v_lshlrev_b32_e32 v27, 2, v23
	ds_bpermute_b32 v23, v27, v22
	s_waitcnt lgkmcnt(0)
	v_max_f32_e32 v23, v23, v23
	v_max_f32_e32 v150, v22, v23
	v_sub_f32_e32 v23, v35, v150
	v_mul_f32_e32 v23, 0x3fb8aa3b, v23
	v_exp_f32_e32 v185, v23
	v_sub_f32_e32 v23, v36, v150
	v_mul_f32_e32 v23, 0x3fb8aa3b, v23
	v_exp_f32_e32 v184, v23
	v_sub_f32_e32 v23, v37, v150
	v_mul_f32_e32 v23, 0x3fb8aa3b, v23
	v_exp_f32_e32 v186, v23
	v_sub_f32_e32 v23, v38, v150
	v_mul_f32_e32 v23, 0x3fb8aa3b, v23
	v_exp_f32_e32 v187, v23
	v_sub_f32_e32 v23, v39, v150
	v_mul_f32_e32 v23, 0x3fb8aa3b, v23
	v_exp_f32_e32 v188, v23
	v_sub_f32_e32 v23, v40, v150
	v_mul_f32_e32 v23, 0x3fb8aa3b, v23
	v_exp_f32_e32 v190, v23
	v_sub_f32_e32 v23, v41, v150
	v_mul_f32_e32 v23, 0x3fb8aa3b, v23
	v_exp_f32_e32 v191, v23
	v_sub_f32_e32 v23, v42, v150
	v_mul_f32_e32 v23, 0x3fb8aa3b, v23
	v_exp_f32_e32 v175, v23
	v_sub_f32_e32 v23, v43, v150
	v_mul_f32_e32 v23, 0x3fb8aa3b, v23
	v_exp_f32_e32 v176, v23
	v_sub_f32_e32 v23, v44, v150
	v_mul_f32_e32 v23, 0x3fb8aa3b, v23
	v_exp_f32_e32 v177, v23
	v_sub_f32_e32 v23, v45, v150
	v_mul_f32_e32 v23, 0x3fb8aa3b, v23
	v_exp_f32_e32 v178, v23
	v_sub_f32_e32 v23, v46, v150
	v_mul_f32_e32 v23, 0x3fb8aa3b, v23
	v_exp_f32_e32 v179, v23
	v_sub_f32_e32 v23, v47, v150
	v_mul_f32_e32 v23, 0x3fb8aa3b, v23
	v_exp_f32_e32 v180, v23
	v_sub_f32_e32 v23, v48, v150
	v_mul_f32_e32 v23, 0x3fb8aa3b, v23
	v_exp_f32_e32 v181, v23
	v_sub_f32_e32 v23, v49, v150
	v_mul_f32_e32 v23, 0x3fb8aa3b, v23
	v_exp_f32_e32 v182, v23
	v_sub_f32_e32 v23, v50, v150
	v_mul_f32_e32 v23, 0x3fb8aa3b, v23
	v_exp_f32_e32 v115, v23
	v_sub_f32_e32 v23, v51, v150
	v_mul_f32_e32 v23, 0x3fb8aa3b, v23
	v_exp_f32_e32 v117, v23
	v_sub_f32_e32 v23, v52, v150
	v_mul_f32_e32 v23, 0x3fb8aa3b, v23
	v_exp_f32_e32 v123, v23
	v_sub_f32_e32 v23, v53, v150
	v_mul_f32_e32 v23, 0x3fb8aa3b, v23
	v_exp_f32_e32 v170, v23
	v_sub_f32_e32 v23, v54, v150
	v_mul_f32_e32 v23, 0x3fb8aa3b, v23
; __device__ __forceinline__ unsigned pk2(float lo, float hi) { return f2bf(lo) | (f2bf(hi) << 16); }
; __device__ __forceinline__ void memattn_group(const Params& p, LAS unsigned char* lds, int grp, const int tid) {
;     ...
; #pragma unroll
;         for (int ct = 0; ct < 16; ++ct)
; #pragma unroll
;             for (int e = 0; e < 4; ++e) { const float pv = __expf(st[ct][e] - mx); st[ct][e] = pv; sm += pv; }
;         sm += __shfl_xor(sm, 16); sm += __shfl_xor(sm, 32);
;         f32x4 ot[8];
; #pragma unroll
;         for (int dt = 0; dt < 8; ++dt) ot[dt] = (f32x4){0.f, 0.f, 0.f, 0.f};
; #pragma unroll
;         for (int ks = 0; ks < 8; ++ks) { v4u pw; pw.x = pk2(st[2 * ks][0], st[2 * ks][1]); pw.y = pk2(st[2 * ks][2], st[2 * ks][3]); pw.z = pk2(st[2 * ks + 1][0], st[2 * ks + 1][1]); pw.w = pk2(st[2 * ks + 1][2], st[2 * ks + 1][3]);
	v_exp_f32_e32 v171, v23
	v_sub_f32_e32 v23, v55, v150
	v_mul_f32_e32 v23, 0x3fb8aa3b, v23
	v_exp_f32_e32 v172, v23
	v_sub_f32_e32 v23, v56, v150
	v_mul_f32_e32 v23, 0x3fb8aa3b, v23
	v_exp_f32_e32 v173, v23
	v_sub_f32_e32 v23, v57, v150
	v_sub_f32_e32 v22, v34, v150
	v_mul_f32_e32 v23, 0x3fb8aa3b, v23
	v_mul_f32_e32 v22, 0x3fb8aa3b, v22
	v_exp_f32_e32 v174, v23
	v_sub_f32_e32 v23, v58, v150
	v_exp_f32_e32 v183, v22
	v_mul_f32_e32 v23, 0x3fb8aa3b, v23
	v_exp_f32_e32 v56, v23
	v_sub_f32_e32 v23, v59, v150
	v_mul_f32_e32 v23, 0x3fb8aa3b, v23
	v_exp_f32_e32 v57, v23
	v_sub_f32_e32 v23, v60, v150
	v_add_f32_e32 v22, 0, v183
	v_mul_f32_e32 v23, 0x3fb8aa3b, v23
	v_add_f32_e32 v22, v185, v22
	v_exp_f32_e32 v58, v23
	v_sub_f32_e32 v23, v61, v150
	v_add_f32_e32 v22, v184, v22
	v_mul_f32_e32 v23, 0x3fb8aa3b, v23
	v_add_f32_e32 v22, v186, v22
	v_exp_f32_e32 v59, v23
	v_sub_f32_e32 v23, v62, v150
	v_add_f32_e32 v22, v187, v22
	v_mul_f32_e32 v23, 0x3fb8aa3b, v23
	v_add_f32_e32 v22, v188, v22
	v_exp_f32_e32 v60, v23
	v_sub_f32_e32 v23, v63, v150
	v_add_f32_e32 v22, v190, v22
	v_mul_f32_e32 v23, 0x3fb8aa3b, v23
	v_add_f32_e32 v22, v191, v22
	v_exp_f32_e32 v61, v23
	v_sub_f32_e32 v23, v64, v150
	v_add_f32_e32 v22, v175, v22
	v_mul_f32_e32 v23, 0x3fb8aa3b, v23
	v_add_f32_e32 v22, v176, v22
	v_exp_f32_e32 v62, v23
	v_sub_f32_e32 v23, v65, v150
	v_add_f32_e32 v22, v177, v22
	v_mul_f32_e32 v23, 0x3fb8aa3b, v23
	v_add_f32_e32 v22, v178, v22
	v_exp_f32_e32 v63, v23
	v_sub_f32_e32 v23, v66, v150
	v_add_f32_e32 v22, v179, v22
	v_mul_f32_e32 v23, 0x3fb8aa3b, v23
	v_add_f32_e32 v22, v180, v22
	v_exp_f32_e32 v48, v23
	v_sub_f32_e32 v23, v67, v150
	v_add_f32_e32 v22, v181, v22
	v_mul_f32_e32 v23, 0x3fb8aa3b, v23
	v_add_f32_e32 v22, v182, v22
	v_exp_f32_e32 v49, v23
	v_sub_f32_e32 v23, v68, v150
	v_add_f32_e32 v22, v115, v22
	v_mul_f32_e32 v23, 0x3fb8aa3b, v23
	v_add_f32_e32 v22, v117, v22
	v_exp_f32_e32 v50, v23
	v_sub_f32_e32 v23, v69, v150
	v_add_f32_e32 v22, v123, v22
	v_mul_f32_e32 v23, 0x3fb8aa3b, v23
	v_add_f32_e32 v22, v170, v22
	v_exp_f32_e32 v52, v23
	v_sub_f32_e32 v23, v70, v150
	v_add_f32_e32 v22, v171, v22
	v_mul_f32_e32 v23, 0x3fb8aa3b, v23
	v_add_f32_e32 v22, v172, v22
	v_exp_f32_e32 v51, v23
	v_sub_f32_e32 v23, v71, v150
	v_add_f32_e32 v22, v173, v22
	v_mul_f32_e32 v23, 0x3fb8aa3b, v23
	v_add_f32_e32 v22, v174, v22
	v_exp_f32_e32 v54, v23
	v_sub_f32_e32 v23, v72, v150
	v_add_f32_e32 v22, v56, v22
	v_mul_f32_e32 v23, 0x3fb8aa3b, v23
	v_add_f32_e32 v22, v57, v22
	v_exp_f32_e32 v53, v23
	v_sub_f32_e32 v23, v73, v150
	v_add_f32_e32 v22, v58, v22
	v_mul_f32_e32 v23, 0x3fb8aa3b, v23
	v_add_f32_e32 v22, v59, v22
	v_exp_f32_e32 v55, v23
	v_sub_f32_e32 v23, v74, v150
	v_add_f32_e32 v22, v60, v22
	v_mul_f32_e32 v23, 0x3fb8aa3b, v23
	v_add_f32_e32 v22, v61, v22
	v_exp_f32_e32 v40, v23
	v_sub_f32_e32 v23, v75, v150
	v_add_f32_e32 v22, v62, v22
	v_mul_f32_e32 v23, 0x3fb8aa3b, v23
	v_add_f32_e32 v22, v63, v22
	v_exp_f32_e32 v42, v23
	v_sub_f32_e32 v23, v76, v150
	v_add_f32_e32 v22, v48, v22
	v_mul_f32_e32 v23, 0x3fb8aa3b, v23
	v_add_f32_e32 v22, v49, v22
	v_exp_f32_e32 v41, v23
	v_sub_f32_e32 v23, v77, v150
	v_add_f32_e32 v22, v50, v22
	v_mul_f32_e32 v23, 0x3fb8aa3b, v23
	v_add_f32_e32 v22, v52, v22
	v_exp_f32_e32 v44, v23
	v_sub_f32_e32 v23, v78, v150
	v_add_f32_e32 v22, v51, v22
	v_mul_f32_e32 v23, 0x3fb8aa3b, v23
	v_add_f32_e32 v22, v54, v22
	v_exp_f32_e32 v43, v23
	v_sub_f32_e32 v23, v79, v150
	v_add_f32_e32 v22, v53, v22
	v_mul_f32_e32 v23, 0x3fb8aa3b, v23
	v_add_f32_e32 v22, v55, v22
	v_exp_f32_e32 v46, v23
	v_sub_f32_e32 v23, v80, v150
	v_add_f32_e32 v22, v40, v22
	v_mul_f32_e32 v23, 0x3fb8aa3b, v23
	v_add_f32_e32 v22, v42, v22
	v_exp_f32_e32 v45, v23
	v_sub_f32_e32 v23, v81, v150
	v_add_f32_e32 v22, v41, v22
	v_mul_f32_e32 v23, 0x3fb8aa3b, v23
	v_add_f32_e32 v22, v44, v22
	v_exp_f32_e32 v47, v23
	v_add_f32_e32 v22, v43, v22
	v_add_f32_e32 v22, v46, v22
	v_add_f32_e32 v22, v45, v22
	v_add_f32_e32 v23, v47, v22
	v_sub_f32_e32 v22, v82, v150
	v_mul_f32_e32 v22, 0x3fb8aa3b, v22
	v_sub_f32_e32 v24, v83, v150
	v_exp_f32_e32 v22, v22
	v_mul_f32_e32 v24, 0x3fb8aa3b, v24
	v_exp_f32_e32 v24, v24
	v_sub_f32_e32 v28, v85, v150
	v_add_f32_e32 v23, v22, v23
	v_mul_f32_e32 v28, 0x3fb8aa3b, v28
	v_add_f32_e32 v25, v24, v23
	v_sub_f32_e32 v23, v84, v150
	v_mul_f32_e32 v23, 0x3fb8aa3b, v23
	v_exp_f32_e32 v23, v23
	v_exp_f32_e32 v36, v28
	v_sub_f32_e32 v29, v87, v150
	v_mul_f32_e32 v29, 0x3fb8aa3b, v29
	v_add_f32_e32 v25, v23, v25
	v_add_f32_e32 v28, v36, v25
	v_sub_f32_e32 v25, v86, v150
	v_mul_f32_e32 v25, 0x3fb8aa3b, v25
	v_exp_f32_e32 v38, v29
	v_sub_f32_e32 v29, v88, v150
	v_exp_f32_e32 v25, v25
	v_mul_f32_e32 v29, 0x3fb8aa3b, v29
	v_exp_f32_e32 v37, v29
	v_sub_f32_e32 v29, v89, v150
	v_mul_f32_e32 v29, 0x3fb8aa3b, v29
	v_exp_f32_e32 v39, v29
	v_add_f32_e32 v28, v25, v28
	v_add_f32_e32 v28, v38, v28
	v_add_f32_e32 v28, v37, v28
	v_add_f32_e32 v29, v39, v28
	v_sub_f32_e32 v28, v90, v150
	v_mul_f32_e32 v28, 0x3fb8aa3b, v28
	v_sub_f32_e32 v30, v91, v150
	v_exp_f32_e32 v28, v28
	v_mul_f32_e32 v30, 0x3fb8aa3b, v30
	v_exp_f32_e32 v30, v30
	v_sub_f32_e32 v32, v93, v150
	v_add_f32_e32 v29, v28, v29
	v_mul_f32_e32 v32, 0x3fb8aa3b, v32
	v_add_f32_e32 v31, v30, v29
	v_sub_f32_e32 v29, v92, v150
	v_mul_f32_e32 v29, 0x3fb8aa3b, v29
	v_exp_f32_e32 v29, v29
	v_exp_f32_e32 v32, v32
	v_sub_f32_e32 v18, v18, v150
	v_mul_f32_e32 v18, 0x3fb8aa3b, v18
	v_add_f32_e32 v31, v29, v31
	v_add_f32_e32 v33, v32, v31
	v_exp_f32_e32 v31, v18
	v_sub_f32_e32 v19, v19, v150
	v_mul_f32_e32 v19, 0x3fb8aa3b, v19
	v_exp_f32_e32 v34, v19
	v_sub_f32_e32 v19, v20, v150
	v_mul_f32_e32 v19, 0x3fb8aa3b, v19
	v_add_f32_e32 v18, v31, v33
	v_exp_f32_e32 v33, v19
	v_sub_f32_e32 v19, v21, v150
	v_mul_f32_e32 v19, 0x3fb8aa3b, v19
	v_exp_f32_e32 v35, v19
	v_add_f32_e32 v18, v34, v18
	v_add_f32_e32 v18, v33, v18
	v_bfe_u32 v20, v186, 16, 1
	v_add_f32_e32 v18, v35, v18
	ds_bpermute_b32 v19, v26, v18
	v_bfe_u32 v21, v185, 16, 1
	v_add3_u32 v64, v185, v21, s33
	v_add3_u32 v65, v186, v20, s33
	v_bfe_u32 v20, v183, 16, 1
	v_bfe_u32 v21, v184, 16, 1
	s_waitcnt lgkmcnt(0)
; #define LAS __attribute__((address_space(3)))
; __device__ __forceinline__ unsigned pk2(float lo, float hi) { return f2bf(lo) | (f2bf(hi) << 16); }
; #define MFMA16(a, b, c) __builtin_amdgcn_mfma_f32_16x16x32_bf16(a, b, c, 0, 0, 0)
; __device__ __forceinline__ v4i16_t vtr(const LAS unsigned char* p) { return __builtin_amdgcn_ds_read_tr16_b64_v4i16((LAS v4i16_t*)p); }
; __device__ __forceinline__ void memattn_group(const Params& p, LAS unsigned char* lds, int grp, const int tid) {
;     ...
;         sm += __shfl_xor(sm, 16); sm += __shfl_xor(sm, 32);
;         f32x4 ot[8];
; #pragma unroll
;         for (int dt = 0; dt < 8; ++dt) ot[dt] = (f32x4){0.f, 0.f, 0.f, 0.f};
; #pragma unroll
;         for (int ks = 0; ks < 8; ++ks) { v4u pw; pw.x = pk2(st[2 * ks][0], st[2 * ks][1]); pw.y = pk2(st[2 * ks][2], st[2 * ks][3]); pw.z = pk2(st[2 * ks + 1][0], st[2 * ks + 1][1]); pw.w = pk2(st[2 * ks + 1][2], st[2 * ks + 1][3]);
;             const bf16x8 pb = __builtin_bit_cast(bf16x8, pw);
; #pragma unroll
;             for (int dt = 0; dt < 8; ++dt) { const LAS unsigned char* vr = lds + MA_VT + (32 * ks + 4 * fq + (fr >> 2)) * 288 + (16 * dt + 4 * (fr & 3)) * 2;
;                 const v4i16_t lo = vtr(vr), hi = vtr(vr + 16 * 288);
;                 ot[dt] = MFMA16(__builtin_shufflevector(lo, hi, 0, 1, 2, 3, 4, 5, 6, 7), pb, ot[dt]); } }
	v_add_f32_e32 v26, v18, v19
	v_cvt_pk_bf16_f32 v21, v190, v191
	v_cvt_pk_bf16_f32 v20, v187, v188
	v_cvt_pk_bf16_f32 v19, v184, v186
	v_cvt_pk_bf16_f32 v18, v183, v185
	ds_read_b64_tr_b16 v[66:67], v128 offset:4608
	ds_read_b64_tr_b16 v[64:65], v128
	ds_read_b64_tr_b16 v[68:69], v128 offset:32
	ds_read_b64_tr_b16 v[70:71], v128 offset:4640
	ds_read_b64_tr_b16 v[72:73], v128 offset:64
	ds_read_b64_tr_b16 v[74:75], v128 offset:4672
	ds_read_b64_tr_b16 v[76:77], v128 offset:96
	ds_read_b64_tr_b16 v[78:79], v128 offset:4704
	ds_read_b64_tr_b16 v[80:81], v128 offset:128
	ds_read_b64_tr_b16 v[82:83], v128 offset:4736
	ds_read_b64_tr_b16 v[84:85], v128 offset:160
	ds_read_b64_tr_b16 v[86:87], v128 offset:4768
	ds_read_b64_tr_b16 v[88:89], v128 offset:192
	ds_read_b64_tr_b16 v[90:91], v128 offset:4800
	ds_read_b64_tr_b16 v[150:151], v128 offset:224
	ds_read_b64_tr_b16 v[152:153], v128 offset:4832
	s_waitcnt lgkmcnt(14)
	v_mfma_f32_16x16x32_bf16 v[64:67], v[64:67], v[18:21], 0
	v_bfe_u32 v92, v182, 16, 1
	v_bfe_u32 v93, v180, 16, 1
	v_add3_u32 v93, v180, v93, s33
	s_waitcnt lgkmcnt(12)
	v_mfma_f32_16x16x32_bf16 v[68:71], v[68:71], v[18:21], 0
	v_add3_u32 v92, v182, v92, s33
	ds_bpermute_b32 v27, v27, v26
	s_waitcnt lgkmcnt(0)
	v_add_f32_e32 v26, v26, v27
	v_mfma_f32_16x16x32_bf16 v[72:75], v[72:75], v[18:21], 0
	v_div_scale_f32 v27, s[0:1], v26, v26, 1.0
	v_mfma_f32_16x16x32_bf16 v[76:79], v[76:79], v[18:21], 0
	v_mfma_f32_16x16x32_bf16 v[80:83], v[80:83], v[18:21], 0
	v_mfma_f32_16x16x32_bf16 v[84:87], v[84:87], v[18:21], 0
	v_mfma_f32_16x16x32_bf16 v[88:91], v[88:91], v[18:21], 0
	v_mfma_f32_16x16x32_bf16 v[18:21], v[150:153], v[18:21], 0
	v_bfe_u32 v151, v176, 16, 1
	v_bfe_u32 v150, v178, 16, 1
	v_add3_u32 v176, v176, v151, s33
	v_bfe_u32 v151, v175, 16, 1
	v_bfe_u32 v152, v177, 16, 1
	v_add3_u32 v150, v178, v150, s33
	v_bfe_u32 v153, v179, 16, 1
	v_add3_u32 v152, v177, v152, s33
	v_add3_u32 v151, v175, v151, s33
	v_add3_u32 v153, v179, v153, s33
	v_lshrrev_b32_e32 v175, 16, v151
	v_lshrrev_b32_e32 v151, 16, v152
	v_lshrrev_b32_e32 v152, 16, v153
	v_and_or_b32 v151, v150, s11, v151
	v_and_or_b32 v150, v176, s11, v175
	ds_read_b64_tr_b16 v[176:177], v128 offset:9216
	ds_read_b64_tr_b16 v[178:179], v128 offset:13824
	v_cvt_pk_bf16_f32 v153, v181, v182
	v_and_or_b32 v152, v93, s11, v152
	v_bfe_u32 v93, v172, 16, 1
	v_add3_u32 v93, v172, v93, s33
	s_waitcnt lgkmcnt(0)
	v_mfma_f32_16x16x32_bf16 v[64:67], v[176:179], v[150:153], v[64:67]
	ds_read_b64_tr_b16 v[176:177], v128 offset:9248
	ds_read_b64_tr_b16 v[178:179], v128 offset:13856
	v_bfe_u32 v92, v174, 16, 1
	v_add3_u32 v92, v174, v92, s33
	s_waitcnt lgkmcnt(0)
	v_mfma_f32_16x16x32_bf16 v[68:71], v[176:179], v[150:153], v[68:71]
	ds_read_b64_tr_b16 v[176:177], v128 offset:9280
	ds_read_b64_tr_b16 v[178:179], v128 offset:13888
	s_waitcnt lgkmcnt(0)
	v_mfma_f32_16x16x32_bf16 v[72:75], v[176:179], v[150:153], v[72:75]
	ds_read_b64_tr_b16 v[176:177], v128 offset:9312
	ds_read_b64_tr_b16 v[178:179], v128 offset:13920
	s_waitcnt lgkmcnt(0)
	v_mfma_f32_16x16x32_bf16 v[76:79], v[176:179], v[150:153], v[76:79]
	ds_read_b64_tr_b16 v[176:177], v128 offset:9344
	ds_read_b64_tr_b16 v[178:179], v128 offset:13952
	s_waitcnt lgkmcnt(0)
	v_mfma_f32_16x16x32_bf16 v[80:83], v[176:179], v[150:153], v[80:83]
	ds_read_b64_tr_b16 v[176:177], v128 offset:9376
	ds_read_b64_tr_b16 v[178:179], v128 offset:13984
	s_waitcnt lgkmcnt(0)
	v_mfma_f32_16x16x32_bf16 v[84:87], v[176:179], v[150:153], v[84:87]
	ds_read_b64_tr_b16 v[176:177], v128 offset:9408
	ds_read_b64_tr_b16 v[178:179], v128 offset:14016
	s_waitcnt lgkmcnt(0)
	v_mfma_f32_16x16x32_bf16 v[88:91], v[176:179], v[150:153], v[88:91]
	ds_read_b64_tr_b16 v[176:177], v128 offset:9440
	ds_read_b64_tr_b16 v[178:179], v128 offset:14048
	s_waitcnt lgkmcnt(0)
	v_mfma_f32_16x16x32_bf16 v[18:21], v[176:179], v[150:153], v[18:21]
	v_bfe_u32 v150, v170, 16, 1
	v_add3_u32 v150, v170, v150, s33
	v_bfe_u32 v170, v173, 16, 1
	v_bfe_u32 v152, v123, 16, 1
	v_bfe_u32 v153, v171, 16, 1
	v_add3_u32 v170, v173, v170, s33
	v_add3_u32 v153, v171, v153, s33
	v_add3_u32 v123, v123, v152, s33
	v_lshrrev_b32_e32 v152, 16, v170
	ds_read_b64_tr_b16 v[170:171], v128 offset:18432
	ds_read_b64_tr_b16 v[172:173], v128 offset:23040
	v_lshrrev_b32_e32 v123, 16, v123
	v_lshrrev_b32_e32 v151, 16, v153
	v_and_or_b32 v153, v92, s11, v152
	v_and_or_b32 v152, v93, s11, v151
	v_and_or_b32 v151, v150, s11, v123
	v_cvt_pk_bf16_f32 v150, v115, v117
	v_bfe_u32 v92, v63, 16, 1
	v_bfe_u32 v93, v61, 16, 1
	s_waitcnt lgkmcnt(0)
	v_mfma_f32_16x16x32_bf16 v[64:67], v[170:173], v[150:153], v[64:67]
	ds_read_b64_tr_b16 v[170:171], v128 offset:18464
	ds_read_b64_tr_b16 v[172:173], v128 offset:23072
	v_bfe_u32 v115, v59, 16, 1
	v_bfe_u32 v117, v57, 16, 1
	s_waitcnt lgkmcnt(0)
	v_mfma_f32_16x16x32_bf16 v[68:71], v[170:173], v[150:153], v[68:71]
	ds_read_b64_tr_b16 v[170:171], v128 offset:18496
	ds_read_b64_tr_b16 v[172:173], v128 offset:23104
	v_add3_u32 v117, v57, v117, s33
	v_add3_u32 v57, v59, v115, s33
	s_waitcnt lgkmcnt(0)
	v_mfma_f32_16x16x32_bf16 v[72:75], v[170:173], v[150:153], v[72:75]
	ds_read_b64_tr_b16 v[170:171], v128 offset:18528
	ds_read_b64_tr_b16 v[172:173], v128 offset:23136
	v_add3_u32 v61, v61, v93, s33
	v_add3_u32 v59, v63, v92, s33
	s_waitcnt lgkmcnt(0)
	v_mfma_f32_16x16x32_bf16 v[76:79], v[170:173], v[150:153], v[76:79]
	ds_read_b64_tr_b16 v[170:171], v128 offset:18560
	ds_read_b64_tr_b16 v[172:173], v128 offset:23168
	v_bfe_u32 v92, v58, 16, 1
	v_bfe_u32 v93, v60, 16, 1
	s_waitcnt lgkmcnt(0)
; #define LAS __attribute__((address_space(3)))
; __device__ __forceinline__ unsigned pk2(float lo, float hi) { return f2bf(lo) | (f2bf(hi) << 16); }
; #define MFMA16(a, b, c) __builtin_amdgcn_mfma_f32_16x16x32_bf16(a, b, c, 0, 0, 0)
; __device__ __forceinline__ v4i16_t vtr(const LAS unsigned char* p) { return __builtin_amdgcn_ds_read_tr16_b64_v4i16((LAS v4i16_t*)p); }
; __device__ __forceinline__ void memattn_group(const Params& p, LAS unsigned char* lds, int grp, const int tid) {
;     ...
; #pragma unroll
;         for (int ks = 0; ks < 8; ++ks) { v4u pw; pw.x = pk2(st[2 * ks][0], st[2 * ks][1]); pw.y = pk2(st[2 * ks][2], st[2 * ks][3]); pw.z = pk2(st[2 * ks + 1][0], st[2 * ks + 1][1]); pw.w = pk2(st[2 * ks + 1][2], st[2 * ks + 1][3]);
;             const bf16x8 pb = __builtin_bit_cast(bf16x8, pw);
; #pragma unroll
;             for (int dt = 0; dt < 8; ++dt) { const LAS unsigned char* vr = lds + MA_VT + (32 * ks + 4 * fq + (fr >> 2)) * 288 + (16 * dt + 4 * (fr & 3)) * 2;
;                 const v4i16_t lo = vtr(vr), hi = vtr(vr + 16 * 288);
;                 ot[dt] = MFMA16(__builtin_shufflevector(lo, hi, 0, 1, 2, 3, 4, 5, 6, 7), pb, ot[dt]); } }
	v_mfma_f32_16x16x32_bf16 v[80:83], v[170:173], v[150:153], v[80:83]
	ds_read_b64_tr_b16 v[170:171], v128 offset:18592
	ds_read_b64_tr_b16 v[172:173], v128 offset:23200
	v_bfe_u32 v115, v62, 16, 1
	v_bfe_u32 v63, v56, 16, 1
	s_waitcnt lgkmcnt(0)
	v_mfma_f32_16x16x32_bf16 v[84:87], v[170:173], v[150:153], v[84:87]
	ds_read_b64_tr_b16 v[170:171], v128 offset:18624
	ds_read_b64_tr_b16 v[172:173], v128 offset:23232
	v_add3_u32 v62, v62, v115, s33
	v_add3_u32 v60, v60, v93, s33
	v_add3_u32 v58, v58, v92, s33
	v_add3_u32 v56, v56, v63, s33
	v_lshrrev_b32_e32 v63, 16, v58
	v_lshrrev_b32_e32 v58, 16, v60
	v_lshrrev_b32_e32 v60, 16, v62
	s_waitcnt lgkmcnt(0)
	v_mfma_f32_16x16x32_bf16 v[88:91], v[170:173], v[150:153], v[88:91]
	ds_read_b64_tr_b16 v[170:171], v128 offset:18656
	ds_read_b64_tr_b16 v[172:173], v128 offset:23264
	v_and_or_b32 v59, v59, s11, v60
	v_and_or_b32 v58, v61, s11, v58
	v_and_or_b32 v57, v57, s11, v63
	ds_read_b64_tr_b16 v[60:61], v128 offset:27648
	ds_read_b64_tr_b16 v[62:63], v128 offset:32256
	v_lshrrev_b32_e32 v56, 16, v56
	v_and_or_b32 v56, v117, s11, v56
	s_waitcnt lgkmcnt(2)
	v_mfma_f32_16x16x32_bf16 v[18:21], v[170:173], v[150:153], v[18:21]
	v_ashrrev_i32_e32 v123, 31, v122
	s_waitcnt lgkmcnt(0)
	v_mfma_f32_16x16x32_bf16 v[60:63], v[60:63], v[56:59], v[64:67]
	s_nop 2
	ds_read_b64_tr_b16 v[64:65], v128 offset:27680
	ds_read_b64_tr_b16 v[66:67], v128 offset:32288
	s_waitcnt lgkmcnt(0)
	v_mfma_f32_16x16x32_bf16 v[64:67], v[64:67], v[56:59], v[68:71]
	s_nop 2
	ds_read_b64_tr_b16 v[68:69], v128 offset:27712
	ds_read_b64_tr_b16 v[70:71], v128 offset:32320
	s_waitcnt lgkmcnt(0)
	v_mfma_f32_16x16x32_bf16 v[68:71], v[68:71], v[56:59], v[72:75]
	s_nop 2
	ds_read_b64_tr_b16 v[72:73], v128 offset:27744
	ds_read_b64_tr_b16 v[74:75], v128 offset:32352
	s_waitcnt lgkmcnt(0)
	v_mfma_f32_16x16x32_bf16 v[72:75], v[72:75], v[56:59], v[76:79]
	s_nop 2
	ds_read_b64_tr_b16 v[76:77], v128 offset:27776
	ds_read_b64_tr_b16 v[78:79], v128 offset:32384
	s_waitcnt lgkmcnt(0)
	v_mfma_f32_16x16x32_bf16 v[76:79], v[76:79], v[56:59], v[80:83]
	s_nop 2
	ds_read_b64_tr_b16 v[80:81], v128 offset:27808
	ds_read_b64_tr_b16 v[82:83], v128 offset:32416
	s_waitcnt lgkmcnt(0)
	v_mfma_f32_16x16x32_bf16 v[80:83], v[80:83], v[56:59], v[84:87]
	s_nop 2
	ds_read_b64_tr_b16 v[84:85], v128 offset:27840
	ds_read_b64_tr_b16 v[86:87], v128 offset:32448
	s_waitcnt lgkmcnt(0)
	v_mfma_f32_16x16x32_bf16 v[84:87], v[84:87], v[56:59], v[88:91]
	s_nop 2
	ds_read_b64_tr_b16 v[88:89], v128 offset:27872
	ds_read_b64_tr_b16 v[90:91], v128 offset:32480
	s_waitcnt lgkmcnt(0)
	v_mfma_f32_16x16x32_bf16 v[18:21], v[88:91], v[56:59], v[18:21]
	v_bfe_u32 v56, v55, 16, 1
	v_bfe_u32 v57, v54, 16, 1
	v_bfe_u32 v58, v52, 16, 1
	v_bfe_u32 v59, v49, 16, 1
	v_add3_u32 v59, v49, v59, s33
	v_add3_u32 v49, v52, v58, s33
	v_add3_u32 v52, v54, v57, s33
	v_add3_u32 v54, v55, v56, s33
	v_bfe_u32 v55, v48, 16, 1
	v_bfe_u32 v56, v50, 16, 1
	v_bfe_u32 v57, v51, 16, 1
	v_bfe_u32 v58, v53, 16, 1
	v_add3_u32 v53, v53, v58, s33
	v_add3_u32 v51, v51, v57, s33
	v_add3_u32 v50, v50, v56, s33
	v_add3_u32 v48, v48, v55, s33
	v_lshrrev_b32_e32 v48, 16, v48
	v_lshrrev_b32_e32 v55, 16, v50
	v_lshrrev_b32_e32 v50, 16, v51
	v_lshrrev_b32_e32 v51, 16, v53
	v_and_or_b32 v51, v54, s11, v51
	v_and_or_b32 v50, v52, s11, v50
	v_and_or_b32 v49, v49, s11, v55
	v_and_or_b32 v48, v59, s11, v48
	ds_read_b64_tr_b16 v[52:53], v128 offset:36864
	ds_read_b64_tr_b16 v[54:55], v128 offset:41472
	ds_read_b64_tr_b16 v[56:57], v128 offset:36896
	ds_read_b64_tr_b16 v[58:59], v128 offset:41504
	s_waitcnt lgkmcnt(2)
	v_mfma_f32_16x16x32_bf16 v[52:55], v[52:55], v[48:51], v[60:63]
	s_nop 2
	ds_read_b64_tr_b16 v[60:61], v128 offset:36928
	ds_read_b64_tr_b16 v[62:63], v128 offset:41536
	s_waitcnt lgkmcnt(2)
	v_mfma_f32_16x16x32_bf16 v[56:59], v[56:59], v[48:51], v[64:67]
	s_nop 2
	ds_read_b64_tr_b16 v[64:65], v128 offset:36960
	ds_read_b64_tr_b16 v[66:67], v128 offset:41568
	s_waitcnt lgkmcnt(2)
	v_mfma_f32_16x16x32_bf16 v[60:63], v[60:63], v[48:51], v[68:71]
	s_nop 2
	ds_read_b64_tr_b16 v[68:69], v128 offset:36992
	ds_read_b64_tr_b16 v[70:71], v128 offset:41600
	s_waitcnt lgkmcnt(2)
	v_mfma_f32_16x16x32_bf16 v[64:67], v[64:67], v[48:51], v[72:75]
	s_nop 2
	ds_read_b64_tr_b16 v[72:73], v128 offset:37024
	ds_read_b64_tr_b16 v[74:75], v128 offset:41632
	s_waitcnt lgkmcnt(2)
	v_mfma_f32_16x16x32_bf16 v[68:71], v[68:71], v[48:51], v[76:79]
	s_nop 2
	ds_read_b64_tr_b16 v[76:77], v128 offset:37056
	ds_read_b64_tr_b16 v[78:79], v128 offset:41664
	s_waitcnt lgkmcnt(2)
	v_mfma_f32_16x16x32_bf16 v[72:75], v[72:75], v[48:51], v[80:83]
	s_nop 2
	ds_read_b64_tr_b16 v[80:81], v128 offset:37088
	ds_read_b64_tr_b16 v[82:83], v128 offset:41696
	s_waitcnt lgkmcnt(2)
	v_mfma_f32_16x16x32_bf16 v[76:79], v[76:79], v[48:51], v[84:87]
	s_waitcnt lgkmcnt(0)
	v_mfma_f32_16x16x32_bf16 v[18:21], v[80:83], v[48:51], v[18:21]
	v_bfe_u32 v48, v47, 16, 1
	v_bfe_u32 v49, v46, 16, 1
	v_bfe_u32 v50, v44, 16, 1
	v_bfe_u32 v51, v42, 16, 1
	v_add3_u32 v51, v42, v51, s33
	v_add3_u32 v42, v46, v49, s33
	v_add3_u32 v46, v47, v48, s33
	v_bfe_u32 v47, v40, 16, 1
	v_bfe_u32 v49, v43, 16, 1
	v_bfe_u32 v50, v45, 16, 1
	v_add3_u32 v45, v45, v50, s33
	v_add3_u32 v43, v43, v49, s33
	v_add3_u32 v40, v40, v47, s33
	v_lshrrev_b32_e32 v40, 16, v40
	v_lshrrev_b32_e32 v47, 16, v43
	v_lshrrev_b32_e32 v43, 16, v45
	v_and_or_b32 v43, v46, s11, v43
	v_and_or_b32 v42, v42, s11, v47
	v_cvt_pk_bf16_f32 v41, v41, v44
	v_and_or_b32 v40, v51, s11, v40
	ds_read_b64_tr_b16 v[44:45], v128 offset:46080
	ds_read_b64_tr_b16 v[46:47], v128 offset:50688
	ds_read_b64_tr_b16 v[48:49], v128 offset:46112
	ds_read_b64_tr_b16 v[50:51], v128 offset:50720
	s_waitcnt lgkmcnt(2)
; #define LAS __attribute__((address_space(3)))
; __device__ __forceinline__ unsigned pk2(float lo, float hi) { return f2bf(lo) | (f2bf(hi) << 16); }
; #define MFMA16(a, b, c) __builtin_amdgcn_mfma_f32_16x16x32_bf16(a, b, c, 0, 0, 0)
; __device__ __forceinline__ v4i16_t vtr(const LAS unsigned char* p) { return __builtin_amdgcn_ds_read_tr16_b64_v4i16((LAS v4i16_t*)p); }
; __device__ __forceinline__ void memattn_group(const Params& p, LAS unsigned char* lds, int grp, const int tid) {
;     ...
; #pragma unroll
;         for (int ks = 0; ks < 8; ++ks) { v4u pw; pw.x = pk2(st[2 * ks][0], st[2 * ks][1]); pw.y = pk2(st[2 * ks][2], st[2 * ks][3]); pw.z = pk2(st[2 * ks + 1][0], st[2 * ks + 1][1]); pw.w = pk2(st[2 * ks + 1][2], st[2 * ks + 1][3]);
;             const bf16x8 pb = __builtin_bit_cast(bf16x8, pw);
; #pragma unroll
;             for (int dt = 0; dt < 8; ++dt) { const LAS unsigned char* vr = lds + MA_VT + (32 * ks + 4 * fq + (fr >> 2)) * 288 + (16 * dt + 4 * (fr & 3)) * 2;
;                 const v4i16_t lo = vtr(vr), hi = vtr(vr + 16 * 288);
;                 ot[dt] = MFMA16(__builtin_shufflevector(lo, hi, 0, 1, 2, 3, 4, 5, 6, 7), pb, ot[dt]); } }
	v_mfma_f32_16x16x32_bf16 v[44:47], v[44:47], v[40:43], v[52:55]
	s_nop 2
	ds_read_b64_tr_b16 v[52:53], v128 offset:46144
	ds_read_b64_tr_b16 v[54:55], v128 offset:50752
	s_waitcnt lgkmcnt(2)
	v_mfma_f32_16x16x32_bf16 v[48:51], v[48:51], v[40:43], v[56:59]
	s_nop 2
	ds_read_b64_tr_b16 v[56:57], v128 offset:46176
	ds_read_b64_tr_b16 v[58:59], v128 offset:50784
	s_waitcnt lgkmcnt(2)
	v_mfma_f32_16x16x32_bf16 v[52:55], v[52:55], v[40:43], v[60:63]
	s_nop 2
	ds_read_b64_tr_b16 v[60:61], v128 offset:46208
	ds_read_b64_tr_b16 v[62:63], v128 offset:50816
	s_waitcnt lgkmcnt(2)
	v_mfma_f32_16x16x32_bf16 v[56:59], v[56:59], v[40:43], v[64:67]
	s_nop 2
	ds_read_b64_tr_b16 v[64:65], v128 offset:46240
	ds_read_b64_tr_b16 v[66:67], v128 offset:50848
	s_waitcnt lgkmcnt(2)
	v_mfma_f32_16x16x32_bf16 v[60:63], v[60:63], v[40:43], v[68:71]
	s_nop 2
	ds_read_b64_tr_b16 v[68:69], v128 offset:46272
	ds_read_b64_tr_b16 v[70:71], v128 offset:50880
	s_waitcnt lgkmcnt(2)
	v_mfma_f32_16x16x32_bf16 v[64:67], v[64:67], v[40:43], v[72:75]
	s_nop 2
	ds_read_b64_tr_b16 v[72:73], v128 offset:46304
	ds_read_b64_tr_b16 v[74:75], v128 offset:50912
	s_waitcnt lgkmcnt(2)
	v_mfma_f32_16x16x32_bf16 v[68:71], v[68:71], v[40:43], v[76:79]
	s_waitcnt lgkmcnt(0)
	v_mfma_f32_16x16x32_bf16 v[40:43], v[72:75], v[40:43], v[18:21]
	s_nop 2
	v_bfe_u32 v18, v39, 16, 1
	v_bfe_u32 v19, v38, 16, 1
	v_bfe_u32 v20, v36, 16, 1
	v_bfe_u32 v21, v24, 16, 1
	v_add3_u32 v21, v24, v21, s33
	v_add3_u32 v20, v36, v20, s33
	v_add3_u32 v19, v38, v19, s33
	v_add3_u32 v18, v39, v18, s33
	v_bfe_u32 v24, v22, 16, 1
	v_bfe_u32 v36, v23, 16, 1
	v_bfe_u32 v38, v25, 16, 1
	v_bfe_u32 v39, v37, 16, 1
	v_add3_u32 v37, v37, v39, s33
	v_add3_u32 v25, v25, v38, s33
	v_add3_u32 v23, v23, v36, s33
	v_add3_u32 v22, v22, v24, s33
	v_lshrrev_b32_e32 v22, 16, v22
	v_lshrrev_b32_e32 v23, 16, v23
	v_lshrrev_b32_e32 v24, 16, v25
	v_lshrrev_b32_e32 v25, 16, v37
	v_and_or_b32 v39, v18, s11, v25
	v_and_or_b32 v38, v19, s11, v24
	v_and_or_b32 v37, v20, s11, v23
	v_and_or_b32 v36, v21, s11, v22
	ds_read_b64_tr_b16 v[18:19], v128 offset:55296
	ds_read_b64_tr_b16 v[20:21], v128 offset:59904
	s_waitcnt lgkmcnt(0)
	v_mfma_f32_16x16x32_bf16 v[44:47], v[18:21], v[36:39], v[44:47]
	ds_read_b64_tr_b16 v[18:19], v128 offset:55328
	ds_read_b64_tr_b16 v[20:21], v128 offset:59936
	s_waitcnt lgkmcnt(0)
	v_mfma_f32_16x16x32_bf16 v[48:51], v[18:21], v[36:39], v[48:51]
	ds_read_b64_tr_b16 v[18:19], v128 offset:55360
	ds_read_b64_tr_b16 v[20:21], v128 offset:59968
	s_waitcnt lgkmcnt(0)
	v_mfma_f32_16x16x32_bf16 v[52:55], v[18:21], v[36:39], v[52:55]
	ds_read_b64_tr_b16 v[18:19], v128 offset:55392
	ds_read_b64_tr_b16 v[20:21], v128 offset:60000
	s_waitcnt lgkmcnt(0)
	v_mfma_f32_16x16x32_bf16 v[56:59], v[18:21], v[36:39], v[56:59]
	ds_read_b64_tr_b16 v[18:19], v128 offset:55424
	ds_read_b64_tr_b16 v[20:21], v128 offset:60032
	ds_read_b64_tr_b16 v[22:23], v128 offset:55456
	ds_read_b64_tr_b16 v[24:25], v128 offset:60064
	s_waitcnt lgkmcnt(2)
	v_mfma_f32_16x16x32_bf16 v[18:21], v[18:21], v[36:39], v[60:63]
	s_waitcnt lgkmcnt(0)
	v_mfma_f32_16x16x32_bf16 v[60:63], v[22:25], v[36:39], v[64:67]
	ds_read_b64_tr_b16 v[22:23], v128 offset:55488
	ds_read_b64_tr_b16 v[24:25], v128 offset:60096
	s_nop 0
	ds_read_b64_tr_b16 v[64:65], v128 offset:55520
	ds_read_b64_tr_b16 v[66:67], v128 offset:60128
	s_waitcnt lgkmcnt(2)
	v_mfma_f32_16x16x32_bf16 v[22:25], v[22:25], v[36:39], v[68:71]
	s_waitcnt lgkmcnt(0)
	v_mfma_f32_16x16x32_bf16 v[36:39], v[64:67], v[36:39], v[40:43]
	s_nop 2
	v_bfe_u32 v40, v35, 16, 1
	v_bfe_u32 v41, v34, 16, 1
	v_bfe_u32 v42, v32, 16, 1
	v_bfe_u32 v43, v30, 16, 1
	v_add3_u32 v43, v30, v43, s33
	v_add3_u32 v30, v34, v41, s33
	v_add3_u32 v34, v35, v40, s33
	v_bfe_u32 v41, v31, 16, 1
	v_bfe_u32 v42, v33, 16, 1
	v_bfe_u32 v35, v28, 16, 1
	v_add3_u32 v33, v33, v42, s33
	v_add3_u32 v31, v31, v41, s33
	v_add3_u32 v28, v28, v35, s33
	v_lshrrev_b32_e32 v35, 16, v31
	v_lshrrev_b32_e32 v31, 16, v33
	v_and_or_b32 v31, v34, s11, v31
	v_and_or_b32 v30, v30, s11, v35
	v_cvt_pk_bf16_f32 v29, v29, v32
	ds_read_b64_tr_b16 v[32:33], v128 offset:64512
	ds_read_b64_tr_b16 v[34:35], v129
	v_lshrrev_b32_e32 v28, 16, v28
	v_and_or_b32 v28, v43, s11, v28
	ds_read_b64_tr_b16 v[40:41], v128 offset:64544
	ds_read_b64_tr_b16 v[42:43], v130
	s_waitcnt lgkmcnt(2)
; #define LAS __attribute__((address_space(3)))
; __device__ __forceinline__ unsigned pk2(float lo, float hi) { return f2bf(lo) | (f2bf(hi) << 16); }
; #define MFMA16(a, b, c) __builtin_amdgcn_mfma_f32_16x16x32_bf16(a, b, c, 0, 0, 0)
; __device__ __forceinline__ v4i16_t vtr(const LAS unsigned char* p) { return __builtin_amdgcn_ds_read_tr16_b64_v4i16((LAS v4i16_t*)p); }
; __device__ __forceinline__ void memattn_group(const Params& p, LAS unsigned char* lds, int grp, const int tid) {
;     ...
;         for (int ks = 0; ks < 4; ++ks) qa[ks] = qn[ks];
;         if (j < 3) { const bf16* qp = QM + (size_t)(m0 + 128 + 16 * w + fr) * 512 + h * 128 + 8 * fq;
; #pragma unroll
;             for (int ks = 0; ks < 4; ++ks) qn[ks] = *(const bf16x8*)(qp + 32 * ks); }
;     ...
;             for (int dt = 0; dt < 8; ++dt) { const LAS unsigned char* vr = lds + MA_VT + (32 * ks + 4 * fq + (fr >> 2)) * 288 + (16 * dt + 4 * (fr & 3)) * 2;
;                 const v4i16_t lo = vtr(vr), hi = vtr(vr + 16 * 288);
;                 ot[dt] = MFMA16(__builtin_shufflevector(lo, hi, 0, 1, 2, 3, 4, 5, 6, 7), pb, ot[dt]); } }
;         { const size_t m = (size_t)(m0 + 16 * w + fr); const float inv = 1.f / sm;
; #pragma unroll
;           for (int dt = 0; dt < 8; ++dt) { unsigned long long wv = (unsigned long long)pk2(ot[dt][0] * inv, ot[dt][1] * inv) | ((unsigned long long)pk2(ot[dt][2] * inv, ot[dt][3] * inv) << 32);
;               *(unsigned long long*)(QM + m * 512 + h * 128 + 16 * dt + 4 * fq) = wv; } }
	v_mfma_f32_16x16x32_bf16 v[32:35], v[32:35], v[28:31], v[44:47]
	s_nop 2
	ds_read_b64_tr_b16 v[44:45], v128 offset:64576
	ds_read_b64_tr_b16 v[46:47], v131
	s_waitcnt lgkmcnt(2)
	v_mfma_f32_16x16x32_bf16 v[40:43], v[40:43], v[28:31], v[48:51]
	s_nop 2
	ds_read_b64_tr_b16 v[48:49], v128 offset:64608
	ds_read_b64_tr_b16 v[50:51], v132
	s_waitcnt lgkmcnt(2)
	v_mfma_f32_16x16x32_bf16 v[44:47], v[44:47], v[28:31], v[52:55]
	s_nop 2
	ds_read_b64_tr_b16 v[52:53], v128 offset:64640
	ds_read_b64_tr_b16 v[54:55], v133
	s_waitcnt lgkmcnt(2)
	v_mfma_f32_16x16x32_bf16 v[48:51], v[48:51], v[28:31], v[56:59]
	s_waitcnt lgkmcnt(0)
	v_mfma_f32_16x16x32_bf16 v[18:21], v[52:55], v[28:31], v[18:21]
	ds_read_b64_tr_b16 v[52:53], v128 offset:64672
	ds_read_b64_tr_b16 v[54:55], v134
	ds_read_b64_tr_b16 v[56:57], v128 offset:64704
	ds_read_b64_tr_b16 v[58:59], v135
	s_waitcnt lgkmcnt(0)
	v_mfma_f32_16x16x32_bf16 v[22:25], v[56:59], v[28:31], v[22:25]
	ds_read_b64_tr_b16 v[56:57], v128 offset:64736
	ds_read_b64_tr_b16 v[58:59], v136
	v_mfma_f32_16x16x32_bf16 v[52:55], v[52:55], v[28:31], v[60:63]
	s_waitcnt lgkmcnt(0)
	v_mfma_f32_16x16x32_bf16 v[28:31], v[56:59], v[28:31], v[36:39]
	s_nop 2
	v_rcp_f32_e32 v36, v27
	s_nop 0
	v_fma_f32 v37, -v27, v36, 1.0
	v_fmac_f32_e32 v36, v37, v36
	v_div_scale_f32 v37, vcc, 1.0, v26, 1.0
	v_mul_f32_e32 v38, v37, v36
	v_fma_f32 v39, -v27, v38, v37
	v_fmac_f32_e32 v38, v39, v36
	v_fma_f32 v27, -v27, v38, v37
	v_div_fmas_f32 v27, v27, v36, v38
	v_div_fixup_f32 v36, v27, v26, 1.0
	v_mul_f32_e32 v32, v36, v32
	v_mul_f32_e32 v33, v36, v33
	v_bfe_u32 v37, v32, 16, 1
	v_add3_u32 v32, v32, v37, s33
	v_bfe_u32 v37, v33, 16, 1
	v_lshrrev_b32_e32 v32, 16, v32
	v_add3_u32 v33, v33, v37, s33
	v_and_or_b32 v32, v33, s11, v32
	v_mul_f32_e32 v33, v36, v34
	v_mul_f32_e32 v34, v36, v35
	v_lshlrev_b64 v[26:27], 10, v[122:123]
	v_lshl_add_u64 v[26:27], v[120:121], 0, v[26:27]
	v_cvt_pk_bf16_f32 v33, v33, v34
	global_store_dwordx2 v[26:27], v[32:33], off
	v_mul_f32_e32 v32, v36, v40
	v_mul_f32_e32 v33, v36, v41
	v_cvt_pk_bf16_f32 v32, v32, v33
	v_mul_f32_e32 v33, v36, v42
	v_mul_f32_e32 v34, v36, v43
	v_cvt_pk_bf16_f32 v33, v33, v34
	global_store_dwordx2 v[26:27], v[32:33], off offset:32
	v_mul_f32_e32 v32, v36, v44
	v_mul_f32_e32 v33, v36, v45
	v_cvt_pk_bf16_f32 v32, v32, v33
	v_mul_f32_e32 v33, v36, v46
	v_mul_f32_e32 v34, v36, v47
	v_cvt_pk_bf16_f32 v33, v33, v34
	global_store_dwordx2 v[26:27], v[32:33], off offset:64
	v_mul_f32_e32 v32, v36, v48
	v_mul_f32_e32 v33, v36, v49
	v_cvt_pk_bf16_f32 v32, v32, v33
	v_mul_f32_e32 v33, v36, v50
	v_mul_f32_e32 v34, v36, v51
	v_bfe_u32 v35, v33, 16, 1
	v_add3_u32 v33, v33, v35, s33
	v_bfe_u32 v35, v34, 16, 1
	v_lshrrev_b32_e32 v33, 16, v33
	v_add3_u32 v34, v34, v35, s33
	v_and_or_b32 v33, v34, s11, v33
	v_mul_f32_e32 v18, v36, v18
	global_store_dwordx2 v[26:27], v[32:33], off offset:96
	v_mul_f32_e32 v19, v36, v19
	v_cvt_pk_bf16_f32 v18, v18, v19
	v_mul_f32_e32 v19, v36, v20
	v_mul_f32_e32 v20, v36, v21
	v_cvt_pk_bf16_f32 v19, v19, v20
	global_store_dwordx2 v[26:27], v[18:19], off offset:128
	v_mul_f32_e32 v18, v36, v52
	v_mul_f32_e32 v19, v36, v53
	v_cvt_pk_bf16_f32 v18, v18, v19
	v_mul_f32_e32 v19, v36, v54
	v_mul_f32_e32 v20, v36, v55
	v_cvt_pk_bf16_f32 v19, v19, v20
	global_store_dwordx2 v[26:27], v[18:19], off offset:160
	v_mul_f32_e32 v18, v36, v22
	v_mul_f32_e32 v19, v36, v23
	v_cvt_pk_bf16_f32 v18, v18, v19
	v_mul_f32_e32 v19, v36, v24
	v_mul_f32_e32 v20, v36, v25
	v_cvt_pk_bf16_f32 v19, v19, v20
	global_store_dwordx2 v[26:27], v[18:19], off offset:192
	v_mul_f32_e32 v18, v36, v28
	v_mul_f32_e32 v19, v36, v29
	v_cvt_pk_bf16_f32 v18, v18, v19
	v_mul_f32_e32 v19, v36, v30
	v_mul_f32_e32 v20, v36, v31
	v_cvt_pk_bf16_f32 v19, v19, v20
	global_store_dwordx2 v[26:27], v[18:19], off offset:224
	s_waitcnt vmcnt(8)
	v_mov_b64_e32 v[32:33], v[8:9]
	v_mov_b64_e32 v[28:29], v[12:13]
	v_mov_b64_e32 v[24:25], v[16:17]
	v_mov_b64_e32 v[20:21], v[4:5]
	v_mov_b64_e32 v[30:31], v[6:7]
	v_mov_b64_e32 v[26:27], v[10:11]
	v_mov_b64_e32 v[22:23], v[14:15]
	v_mov_b64_e32 v[18:19], v[2:3]
	s_cbranch_scc0 .LBB0_494

; __device__ __forceinline__ void memattn_group(const Params& p, LAS unsigned char* lds, int grp, const int tid) {
;     ...
;         for (int ks = 0; ks < 4; ++ks) qa[ks] = qn[ks];
;         if (j < 3) { const bf16* qp = QM + (size_t)(m0 + 128 + 16 * w + fr) * 512 + h * 128 + 8 * fq;
; #pragma unroll
;             for (int ks = 0; ks < 4; ++ks) qn[ks] = *(const bf16x8*)(qp + 32 * ks); }
.LBB0_503:
	s_andn2_b64 vcc, exec, s[0:1]
	s_cbranch_vccnz .LBB0_500
	v_mov_b64_e32 v[6:7], v[30:31]
	v_mov_b64_e32 v[10:11], v[26:27]
	v_mov_b64_e32 v[14:15], v[22:23]
	v_mov_b64_e32 v[2:3], v[18:19]
	v_mov_b32_e32 v122, v34
	v_mov_b64_e32 v[8:9], v[32:33]
	v_mov_b64_e32 v[12:13], v[28:29]
	v_mov_b64_e32 v[16:17], v[24:25]
	v_mov_b64_e32 v[4:5], v[20:21]
	s_branch .LBB0_500

; template <int NR>
; __device__ __forceinline__ void ln_rows(const _Float16* z, bf16* xb, float* st, float* outf, int m0, int stride, const float* g, const float* b, int lane, bool final_out) {
;     ...
;     for (int r = 0; r < NR; ++r) { const h16x4* zr = (const h16x4*)(z + (size_t)(m0 + r * stride) * D) + lane; s[r] = 0.f;
; #pragma unroll
;         for (int j = 0; j < 4; ++j) v[r][j] = __builtin_convertvector(zr[64 * j], f32x4); }
; #pragma unroll
;     for (int r = 0; r < NR; ++r)
; #pragma unroll
;         for (int j = 0; j < 4; ++j) s[r] += (v[r][j].x + v[r][j].y) + (v[r][j].z + v[r][j].w);
; #pragma unroll
;     for (int o = 1; o < 64; o <<= 1)
; #pragma unroll
;         for (int r = 0; r < NR; ++r) s[r] += __shfl_xor(s[r], o);
.LBB0_631:
	s_ashr_i32 s5, s4, 31
	s_lshl_b64 s[54:55], s[4:5], 11
	v_lshl_add_u64 v[2:3], v[8:9], 0, s[54:55]
	flat_load_dwordx2 v[44:45], v[2:3]
	flat_load_dwordx2 v[42:43], v[2:3] offset:512
	flat_load_dwordx2 v[40:41], v[2:3] offset:1024
	flat_load_dwordx2 v[38:39], v[2:3] offset:1536
	s_add_i32 s42, s4, s14
	s_ashr_i32 s43, s42, 31
	s_lshl_b64 s[52:53], s[42:43], 11
	v_lshl_add_u64 v[2:3], v[8:9], 0, s[52:53]
	flat_load_dwordx2 v[36:37], v[2:3]
	flat_load_dwordx2 v[34:35], v[2:3] offset:512
	flat_load_dwordx2 v[32:33], v[2:3] offset:1024
	flat_load_dwordx2 v[30:31], v[2:3] offset:1536
	s_add_i32 s48, s58, s4
	s_ashr_i32 s49, s48, 31
	s_lshl_b64 s[50:51], s[48:49], 11
	v_lshl_add_u64 v[2:3], v[8:9], 0, s[50:51]
	flat_load_dwordx2 v[28:29], v[2:3]
	flat_load_dwordx2 v[26:27], v[2:3] offset:512
	flat_load_dwordx2 v[24:25], v[2:3] offset:1024
	flat_load_dwordx2 v[22:23], v[2:3] offset:1536
	s_add_i32 s44, s15, s4
	s_ashr_i32 s45, s44, 31
	s_lshl_b64 s[46:47], s[44:45], 11
	v_lshl_add_u64 v[2:3], v[8:9], 0, s[46:47]
	flat_load_dwordx2 v[20:21], v[2:3]
	flat_load_dwordx2 v[18:19], v[2:3] offset:512
	flat_load_dwordx2 v[4:5], v[2:3] offset:1024
	s_nop 0
	flat_load_dwordx2 v[2:3], v[2:3] offset:1536
	s_waitcnt vmcnt(0) lgkmcnt(0)
	v_cvt_f32_f16_e32 v46, v44
	v_cvt_f32_f16_sdwa v47, v45 dst_sel:DWORD dst_unused:UNUSED_PAD src0_sel:WORD_1
	v_cvt_f32_f16_e32 v49, v45
	v_cvt_f32_f16_sdwa v48, v44 dst_sel:DWORD dst_unused:UNUSED_PAD src0_sel:WORD_1
	v_cvt_f32_f16_e32 v50, v42
	v_cvt_f32_f16_sdwa v51, v43 dst_sel:DWORD dst_unused:UNUSED_PAD src0_sel:WORD_1
	v_cvt_f32_f16_e32 v53, v43
	v_cvt_f32_f16_sdwa v52, v42 dst_sel:DWORD dst_unused:UNUSED_PAD src0_sel:WORD_1
	v_cvt_f32_f16_e32 v7, v41
	v_cvt_f32_f16_sdwa v54, v41 dst_sel:DWORD dst_unused:UNUSED_PAD src0_sel:WORD_1
	v_cvt_f32_f16_e32 v56, v40
	v_cvt_f32_f16_sdwa v68, v40 dst_sel:DWORD dst_unused:UNUSED_PAD src0_sel:WORD_1
	v_cvt_f32_f16_sdwa v70, v38 dst_sel:DWORD dst_unused:UNUSED_PAD src0_sel:WORD_1
	v_pk_add_f32 v[46:47], v[48:49], v[46:47]
	v_cvt_f32_f16_sdwa v55, v39 dst_sel:DWORD dst_unused:UNUSED_PAD src0_sel:WORD_1
	v_cvt_f32_f16_e32 v57, v39
	v_cvt_f32_f16_e32 v59, v38
	v_add_f32_e32 v46, v46, v47
	v_add_f32_e32 v58, 0, v46
	v_pk_add_f32 v[46:47], v[52:53], v[50:51]
	v_cvt_f32_f16_e32 v60, v36
	v_cvt_f32_f16_sdwa v61, v37 dst_sel:DWORD dst_unused:UNUSED_PAD src0_sel:WORD_1
	v_cvt_f32_f16_e32 v63, v37
	v_cvt_f32_f16_sdwa v62, v36 dst_sel:DWORD dst_unused:UNUSED_PAD src0_sel:WORD_1
	v_pk_add_f32 v[46:47], v[46:47], v[46:47] op_sel:[0,1] op_sel_hi:[1,0]
	v_add_f32_e32 v56, v56, v68
	v_add_f32_e32 v54, v7, v54
	v_mov_b32_e32 v47, v70
	v_cvt_f32_f16_e32 v64, v34
	v_cvt_f32_f16_sdwa v65, v35 dst_sel:DWORD dst_unused:UNUSED_PAD src0_sel:WORD_1
	v_cvt_f32_f16_e32 v67, v35
	v_cvt_f32_f16_sdwa v66, v34 dst_sel:DWORD dst_unused:UNUSED_PAD src0_sel:WORD_1
	v_pk_add_f32 v[46:47], v[58:59], v[46:47]
	v_pk_add_f32 v[48:49], v[56:57], v[54:55]
	v_cvt_f32_f16_e32 v82, v33
	v_pk_add_f32 v[46:47], v[46:47], v[48:49]
	v_cvt_f32_f16_sdwa v84, v33 dst_sel:DWORD dst_unused:UNUSED_PAD src0_sel:WORD_1
	v_cvt_f32_f16_e32 v91, v32
	v_cvt_f32_f16_sdwa v92, v32 dst_sel:DWORD dst_unused:UNUSED_PAD src0_sel:WORD_1
	v_cvt_f32_f16_sdwa v102, v30 dst_sel:DWORD dst_unused:UNUSED_PAD src0_sel:WORD_1
	v_add_f32_e32 v7, v46, v47
	v_pk_add_f32 v[46:47], v[62:63], v[60:61]
	v_cvt_f32_f16_sdwa v69, v31 dst_sel:DWORD dst_unused:UNUSED_PAD src0_sel:WORD_1
	v_cvt_f32_f16_e32 v71, v31
	v_cvt_f32_f16_e32 v73, v30
	v_add_f32_e32 v46, v46, v47
	v_add_f32_e32 v72, 0, v46
	v_pk_add_f32 v[46:47], v[66:67], v[64:65]
	v_cvt_f32_f16_e32 v74, v28
	v_cvt_f32_f16_sdwa v75, v29 dst_sel:DWORD dst_unused:UNUSED_PAD src0_sel:WORD_1
	v_cvt_f32_f16_e32 v77, v29
	v_cvt_f32_f16_sdwa v76, v28 dst_sel:DWORD dst_unused:UNUSED_PAD src0_sel:WORD_1
	v_pk_add_f32 v[46:47], v[46:47], v[46:47] op_sel:[0,1] op_sel_hi:[1,0]
	v_add_f32_e32 v70, v91, v92
	v_add_f32_e32 v68, v82, v84
	v_mov_b32_e32 v47, v102
	v_cvt_f32_f16_e32 v78, v26
	v_cvt_f32_f16_sdwa v79, v27 dst_sel:DWORD dst_unused:UNUSED_PAD src0_sel:WORD_1
	v_cvt_f32_f16_e32 v81, v27
	v_cvt_f32_f16_sdwa v80, v26 dst_sel:DWORD dst_unused:UNUSED_PAD src0_sel:WORD_1
	v_pk_add_f32 v[46:47], v[72:73], v[46:47]
	v_pk_add_f32 v[48:49], v[70:71], v[68:69]
	v_cvt_f32_f16_e32 v104, v25
	v_pk_add_f32 v[46:47], v[46:47], v[48:49]
	v_cvt_f32_f16_sdwa v106, v25 dst_sel:DWORD dst_unused:UNUSED_PAD src0_sel:WORD_1
	v_cvt_f32_f16_e32 v108, v24
	v_cvt_f32_f16_sdwa v109, v24 dst_sel:DWORD dst_unused:UNUSED_PAD src0_sel:WORD_1
	v_cvt_f32_f16_sdwa v110, v22 dst_sel:DWORD dst_unused:UNUSED_PAD src0_sel:WORD_1
	v_add_f32_e32 v50, v46, v47
	v_pk_add_f32 v[46:47], v[76:77], v[74:75]
	v_cvt_f32_f16_sdwa v83, v23 dst_sel:DWORD dst_unused:UNUSED_PAD src0_sel:WORD_1
	v_cvt_f32_f16_e32 v85, v23
	v_cvt_f32_f16_e32 v93, v22
	v_add_f32_e32 v46, v46, v47
	v_add_f32_e32 v92, 0, v46
	v_pk_add_f32 v[46:47], v[80:81], v[78:79]
	v_cvt_f32_f16_e32 v94, v20
	v_cvt_f32_f16_sdwa v95, v21 dst_sel:DWORD dst_unused:UNUSED_PAD src0_sel:WORD_1
	v_cvt_f32_f16_e32 v97, v21
	v_cvt_f32_f16_sdwa v96, v20 dst_sel:DWORD dst_unused:UNUSED_PAD src0_sel:WORD_1
	v_pk_add_f32 v[46:47], v[46:47], v[46:47] op_sel:[0,1] op_sel_hi:[1,0]
	v_add_f32_e32 v84, v108, v109
	v_add_f32_e32 v82, v104, v106
	v_mov_b32_e32 v47, v110
	v_cvt_f32_f16_e32 v98, v18
	v_cvt_f32_f16_sdwa v99, v19 dst_sel:DWORD dst_unused:UNUSED_PAD src0_sel:WORD_1
	v_cvt_f32_f16_e32 v101, v19
	v_cvt_f32_f16_sdwa v100, v18 dst_sel:DWORD dst_unused:UNUSED_PAD src0_sel:WORD_1
	v_pk_add_f32 v[46:47], v[92:93], v[46:47]
	v_pk_add_f32 v[48:49], v[84:85], v[82:83]
	v_cvt_f32_f16_e32 v111, v5
	v_pk_add_f32 v[46:47], v[46:47], v[48:49]
	v_cvt_f32_f16_sdwa v112, v5 dst_sel:DWORD dst_unused:UNUSED_PAD src0_sel:WORD_1
	v_cvt_f32_f16_e32 v113, v4
	v_cvt_f32_f16_sdwa v114, v4 dst_sel:DWORD dst_unused:UNUSED_PAD src0_sel:WORD_1
	v_cvt_f32_f16_sdwa v115, v2 dst_sel:DWORD dst_unused:UNUSED_PAD src0_sel:WORD_1
	v_add_f32_e32 v51, v46, v47
	v_pk_add_f32 v[46:47], v[96:97], v[94:95]
	v_cvt_f32_f16_sdwa v103, v3 dst_sel:DWORD dst_unused:UNUSED_PAD src0_sel:WORD_1
	v_cvt_f32_f16_e32 v105, v3
	v_cvt_f32_f16_e32 v107, v2
	v_add_f32_e32 v46, v46, v47
	v_add_f32_e32 v106, 0, v46
	v_pk_add_f32 v[46:47], v[100:101], v[98:99]
	v_add_f32_e32 v104, v113, v114
	v_pk_add_f32 v[46:47], v[46:47], v[46:47] op_sel:[0,1] op_sel_hi:[1,0]
	v_add_f32_e32 v102, v111, v112
	v_mov_b32_e32 v47, v115
	v_pk_add_f32 v[46:47], v[106:107], v[46:47]
	v_pk_add_f32 v[48:49], v[104:105], v[102:103]
	s_nop 0
	v_pk_add_f32 v[46:47], v[46:47], v[48:49]
	v_mov_b32_dpp v48, v50 quad_perm:[1,0,3,2] row_mask:0xf bank_mask:0xf
	v_add_f32_e32 v46, v46, v47
	v_mov_b32_dpp v47, v7 quad_perm:[1,0,3,2] row_mask:0xf bank_mask:0xf
	v_mov_b32_dpp v49, v51 quad_perm:[1,0,3,2] row_mask:0xf bank_mask:0xf
	v_mov_b32_dpp v52, v46 quad_perm:[1,0,3,2] row_mask:0xf bank_mask:0xf
	s_waitcnt lgkmcnt(0)
; template <int NR>
; __device__ __forceinline__ void ln_rows(const _Float16* z, bf16* xb, float* st, float* outf, int m0, int stride, const float* g, const float* b, int lane, bool final_out) {
;     ...
;     for (int o = 1; o < 64; o <<= 1)
; #pragma unroll
;         for (int r = 0; r < NR; ++r) s[r] += __shfl_xor(s[r], o);
;     float mean[NR], s2[NR];
; #pragma unroll
;     for (int r = 0; r < NR; ++r) { mean[r] = s[r] * (1.f / D); s2[r] = 0.f;
; #pragma unroll
;         for (int j = 0; j < 4; ++j) { v[r][j] = v[r][j] - mean[r]; s2[r] += (v[r][j].x * v[r][j].x + v[r][j].y * v[r][j].y) + (v[r][j].z * v[r][j].z + v[r][j].w * v[r][j].w); } }
; #pragma unroll
;     for (int o = 1; o < 64; o <<= 1)
; #pragma unroll
;         for (int r = 0; r < NR; ++r) s2[r] += __shfl_xor(s2[r], o);
	v_add_f32_e32 v7, v7, v47
	v_add_f32_e32 v47, v50, v48
	s_waitcnt lgkmcnt(0)
	v_add_f32_e32 v48, v51, v49
	v_mov_b32_dpp v49, v7 quad_perm:[2,3,0,1] row_mask:0xf bank_mask:0xf
	v_mov_b32_dpp v50, v47 quad_perm:[2,3,0,1] row_mask:0xf bank_mask:0xf
	v_mov_b32_dpp v51, v48 quad_perm:[2,3,0,1] row_mask:0xf bank_mask:0xf
	s_waitcnt lgkmcnt(0)
	v_add_f32_e32 v46, v46, v52
	s_nop 1
	v_mov_b32_dpp v52, v46 quad_perm:[2,3,0,1] row_mask:0xf bank_mask:0xf
	s_waitcnt lgkmcnt(0)
	v_add_f32_e32 v7, v7, v49
	s_nop 1
	v_mov_b32_dpp v49, v7 row_half_mirror row_mask:0xf bank_mask:0xf
	s_waitcnt lgkmcnt(0)
	v_add_f32_e32 v47, v47, v50
	s_nop 1
	v_mov_b32_dpp v50, v47 row_half_mirror row_mask:0xf bank_mask:0xf
	s_waitcnt lgkmcnt(0)
	v_add_f32_e32 v48, v48, v51
	s_nop 1
	v_mov_b32_dpp v51, v48 row_half_mirror row_mask:0xf bank_mask:0xf
	s_waitcnt lgkmcnt(0)
	v_add_f32_e32 v46, v46, v52
	s_waitcnt lgkmcnt(0)
	v_add_f32_e32 v7, v7, v49
	v_mov_b32_dpp v52, v46 row_half_mirror row_mask:0xf bank_mask:0xf
	s_nop 0
	v_mov_b32_dpp v49, v7 row_mirror row_mask:0xf bank_mask:0xf
	s_waitcnt lgkmcnt(0)
	v_add_f32_e32 v47, v47, v50
	s_nop 1
	v_mov_b32_dpp v50, v47 row_mirror row_mask:0xf bank_mask:0xf
	s_waitcnt lgkmcnt(0)
	v_add_f32_e32 v48, v48, v51
	s_nop 1
	v_mov_b32_dpp v51, v48 row_mirror row_mask:0xf bank_mask:0xf
	s_waitcnt lgkmcnt(0)
	v_add_f32_e32 v46, v46, v52
	s_waitcnt lgkmcnt(0)
	v_add_f32_e32 v7, v7, v49
	v_mov_b32_dpp v52, v46 row_mirror row_mask:0xf bank_mask:0xf
	ds_bpermute_b32 v49, v89, v7
	s_waitcnt lgkmcnt(0)
	v_add_f32_e32 v47, v47, v50
	ds_bpermute_b32 v50, v89, v47
	s_waitcnt lgkmcnt(0)
	v_add_f32_e32 v48, v48, v51
	ds_bpermute_b32 v51, v89, v48
	s_waitcnt lgkmcnt(0)
	v_add_f32_e32 v46, v46, v52
	s_waitcnt lgkmcnt(0)
	v_add_f32_e32 v7, v7, v49
	ds_bpermute_b32 v52, v89, v46
	ds_bpermute_b32 v49, v90, v7
	s_waitcnt lgkmcnt(0)
	v_add_f32_e32 v47, v47, v50
	ds_bpermute_b32 v50, v90, v47
	s_waitcnt lgkmcnt(0)
	v_add_f32_e32 v48, v48, v51
	ds_bpermute_b32 v51, v90, v48
	s_waitcnt lgkmcnt(0)
	v_add_f32_e32 v46, v46, v52
	s_waitcnt lgkmcnt(0)
	v_add_f32_e32 v82, v7, v49
	ds_bpermute_b32 v52, v90, v46
	v_fma_mix_f32 v79, v82, s92, v45 op_sel:[0,0,1] op_sel_hi:[0,0,1]
	v_fma_mix_f32 v81, v82, s92, v44 op_sel:[0,0,1] op_sel_hi:[0,0,1]
	v_fma_mix_f32 v75, v82, s92, v43 op_sel:[0,0,1] op_sel_hi:[0,0,1]
	v_fma_mix_f32 v77, v82, s92, v42 op_sel:[0,0,1] op_sel_hi:[0,0,1]
	s_waitcnt lgkmcnt(0)
	v_add_f32_e32 v94, v47, v50
	v_fma_mix_f32 v78, v82, s92, v45 op_sel_hi:[0,0,1]
	v_fma_mix_f32 v80, v82, s92, v44 op_sel_hi:[0,0,1]
	v_mul_f32_e32 v44, v81, v81
	v_mul_f32_e32 v45, v79, v79
	v_fma_mix_f32 v74, v82, s92, v43 op_sel_hi:[0,0,1]
	v_fma_mix_f32 v76, v82, s92, v42 op_sel_hi:[0,0,1]
	v_mul_f32_e32 v42, v77, v77
	v_mul_f32_e32 v43, v75, v75
	v_fma_mix_f32 v71, v82, s92, v41 op_sel:[0,0,1] op_sel_hi:[0,0,1]
	v_fma_mix_f32 v73, v82, s92, v40 op_sel:[0,0,1] op_sel_hi:[0,0,1]
	v_fmac_f32_e32 v44, v80, v80
	v_fmac_f32_e32 v45, v78, v78
	v_fmac_f32_e32 v42, v76, v76
	v_fmac_f32_e32 v43, v74, v74
	v_fma_mix_f32 v70, v82, s92, v41 op_sel_hi:[0,0,1]
	v_fma_mix_f32 v72, v82, s92, v40 op_sel_hi:[0,0,1]
	v_mul_f32_e32 v40, v73, v73
	v_mul_f32_e32 v41, v71, v71
	v_fma_mix_f32 v67, v82, s92, v39 op_sel:[0,0,1] op_sel_hi:[0,0,1]
	v_fma_mix_f32 v69, v82, s92, v38 op_sel:[0,0,1] op_sel_hi:[0,0,1]
	v_fma_mix_f32 v63, v94, s92, v37 op_sel:[0,0,1] op_sel_hi:[0,0,1]
	v_fma_mix_f32 v65, v94, s92, v36 op_sel:[0,0,1] op_sel_hi:[0,0,1]
	v_fma_mix_f32 v59, v94, s92, v35 op_sel:[0,0,1] op_sel_hi:[0,0,1]
	v_fma_mix_f32 v61, v94, s92, v34 op_sel:[0,0,1] op_sel_hi:[0,0,1]
	s_waitcnt lgkmcnt(0)
	v_add_f32_e32 v91, v48, v51
	v_add_f32_e32 v44, v44, v45
	v_add_f32_e32 v42, v42, v43
	v_fmac_f32_e32 v40, v72, v72
	v_fmac_f32_e32 v41, v70, v70
	v_fma_mix_f32 v66, v82, s92, v39 op_sel_hi:[0,0,1]
	v_fma_mix_f32 v68, v82, s92, v38 op_sel_hi:[0,0,1]
	v_mul_f32_e32 v38, v69, v69
	v_mul_f32_e32 v39, v67, v67
	v_fma_mix_f32 v62, v94, s92, v37 op_sel_hi:[0,0,1]
	v_fma_mix_f32 v64, v94, s92, v36 op_sel_hi:[0,0,1]
	v_mul_f32_e32 v36, v65, v65
	v_mul_f32_e32 v37, v63, v63
	v_fma_mix_f32 v58, v94, s92, v35 op_sel_hi:[0,0,1]
	v_fma_mix_f32 v60, v94, s92, v34 op_sel_hi:[0,0,1]
	v_mul_f32_e32 v34, v61, v61
	v_mul_f32_e32 v35, v59, v59
	v_fma_mix_f32 v55, v94, s92, v33 op_sel:[0,0,1] op_sel_hi:[0,0,1]
	v_fma_mix_f32 v57, v94, s92, v32 op_sel:[0,0,1] op_sel_hi:[0,0,1]
	v_add_f32_e32 v42, v44, v42
	v_add_f32_e32 v40, v40, v41
	v_fmac_f32_e32 v38, v68, v68
	v_fmac_f32_e32 v39, v66, v66
	v_fmac_f32_e32 v36, v64, v64
	v_fmac_f32_e32 v37, v62, v62
	v_fmac_f32_e32 v34, v60, v60
	v_fmac_f32_e32 v35, v58, v58
	v_fma_mix_f32 v54, v94, s92, v33 op_sel_hi:[0,0,1]
	v_fma_mix_f32 v56, v94, s92, v32 op_sel_hi:[0,0,1]
	v_mul_f32_e32 v32, v57, v57
	v_mul_f32_e32 v33, v55, v55
	v_fma_mix_f32 v47, v91, s92, v29 op_sel:[0,0,1] op_sel_hi:[0,0,1]
	v_fma_mix_f32 v49, v91, s92, v28 op_sel:[0,0,1] op_sel_hi:[0,0,1]
	v_fma_mix_f32 v43, v91, s92, v27 op_sel:[0,0,1] op_sel_hi:[0,0,1]
	v_fma_mix_f32 v45, v91, s92, v26 op_sel:[0,0,1] op_sel_hi:[0,0,1]
	s_waitcnt lgkmcnt(0)
; template <int NR>
; __device__ __forceinline__ void ln_rows(const _Float16* z, bf16* xb, float* st, float* outf, int m0, int stride, const float* g, const float* b, int lane, bool final_out) {
;     ...
; #pragma unroll
;     for (int o = 1; o < 64; o <<= 1)
; #pragma unroll
;         for (int r = 0; r < NR; ++r) s2[r] += __shfl_xor(s2[r], o);
; #pragma unroll
;     for (int r = 0; r < NR; ++r) { const int m = m0 + r * stride; const float rstd = 1.f / sqrtf(s2[r] * (1.f / D) + LN_EPS);
;         if (!final_out && lane == 0) *(f32x2*)(st + 2 * (size_t)m) = (f32x2){mean[r], rstd};
	v_add_f32_e32 v7, v46, v52
	v_add_f32_e32 v40, v40, v42
	v_add_f32_e32 v38, v38, v39
	v_add_f32_e32 v36, v36, v37
	v_add_f32_e32 v34, v34, v35
	v_fmac_f32_e32 v32, v56, v56
	v_fmac_f32_e32 v33, v54, v54
	v_fma_mix_f32 v46, v91, s92, v29 op_sel_hi:[0,0,1]
	v_fma_mix_f32 v48, v91, s92, v28 op_sel_hi:[0,0,1]
	v_mul_f32_e32 v28, v49, v49
	v_mul_f32_e32 v29, v47, v47
	v_fma_mix_f32 v42, v91, s92, v27 op_sel_hi:[0,0,1]
	v_fma_mix_f32 v44, v91, s92, v26 op_sel_hi:[0,0,1]
	v_mul_f32_e32 v26, v45, v45
	v_mul_f32_e32 v27, v43, v43
	v_fma_mix_f32 v39, v91, s92, v25 op_sel:[0,0,1] op_sel_hi:[0,0,1]
	v_fma_mix_f32 v41, v91, s92, v24 op_sel:[0,0,1] op_sel_hi:[0,0,1]
	v_add_f32_e32 v83, v38, v40
	v_add_f32_e32 v34, v36, v34
	v_add_f32_e32 v32, v32, v33
	v_fmac_f32_e32 v28, v48, v48
	v_fmac_f32_e32 v29, v46, v46
	v_fmac_f32_e32 v26, v44, v44
	v_fmac_f32_e32 v27, v42, v42
	v_fma_mix_f32 v38, v91, s92, v25 op_sel_hi:[0,0,1]
	v_fma_mix_f32 v40, v91, s92, v24 op_sel_hi:[0,0,1]
	v_mul_f32_e32 v24, v41, v41
	v_mul_f32_e32 v25, v39, v39
	v_fma_mix_f32 v35, v91, s92, v23 op_sel:[0,0,1] op_sel_hi:[0,0,1]
	v_fma_mix_f32 v37, v91, s92, v22 op_sel:[0,0,1] op_sel_hi:[0,0,1]
	v_add_f32_e32 v32, v32, v34
	v_fma_mix_f32 v51, v94, s92, v31 op_sel:[0,0,1] op_sel_hi:[0,0,1]
	v_fma_mix_f32 v53, v94, s92, v30 op_sel:[0,0,1] op_sel_hi:[0,0,1]
	v_add_f32_e32 v28, v28, v29
	v_add_f32_e32 v26, v26, v27
	v_fmac_f32_e32 v24, v40, v40
	v_fmac_f32_e32 v25, v38, v38
	v_fma_mix_f32 v34, v91, s92, v23 op_sel_hi:[0,0,1]
	v_fma_mix_f32 v36, v91, s92, v22 op_sel_hi:[0,0,1]
	v_mul_f32_e32 v22, v37, v37
	v_mul_f32_e32 v23, v35, v35
	v_fma_mix_f32 v50, v94, s92, v31 op_sel_hi:[0,0,1]
	v_fma_mix_f32 v52, v94, s92, v30 op_sel_hi:[0,0,1]
	v_mul_f32_e32 v30, v53, v53
	v_mul_f32_e32 v31, v51, v51
	v_add_f32_e32 v26, v28, v26
	v_add_f32_e32 v24, v24, v25
	v_fmac_f32_e32 v22, v36, v36
	v_fmac_f32_e32 v23, v34, v34
	v_fmac_f32_e32 v30, v52, v52
	v_fmac_f32_e32 v31, v50, v50
	v_add_f32_e32 v24, v24, v26
	v_add_f32_e32 v22, v22, v23
	v_fma_mix_f32 v23, v7, s92, v5 op_sel:[0,0,1] op_sel_hi:[0,0,1]
	v_fma_mix_f32 v25, v7, s92, v4 op_sel:[0,0,1] op_sel_hi:[0,0,1]
	v_add_f32_e32 v30, v30, v31
	v_add_f32_e32 v85, v22, v24
	v_fma_mix_f32 v31, v7, s92, v21 op_sel:[0,0,1] op_sel_hi:[0,0,1]
	v_fma_mix_f32 v33, v7, s92, v20 op_sel:[0,0,1] op_sel_hi:[0,0,1]
	v_fma_mix_f32 v27, v7, s92, v19 op_sel:[0,0,1] op_sel_hi:[0,0,1]
	v_fma_mix_f32 v29, v7, s92, v18 op_sel:[0,0,1] op_sel_hi:[0,0,1]
	v_fma_mix_f32 v22, v7, s92, v5 op_sel_hi:[0,0,1]
	v_fma_mix_f32 v24, v7, s92, v4 op_sel_hi:[0,0,1]
	v_mul_f32_e32 v4, v25, v25
	v_mul_f32_e32 v5, v23, v23
	v_add_f32_e32 v84, v30, v32
	v_fma_mix_f32 v30, v7, s92, v21 op_sel_hi:[0,0,1]
	v_fma_mix_f32 v32, v7, s92, v20 op_sel_hi:[0,0,1]
	v_mul_f32_e32 v20, v33, v33
	v_mul_f32_e32 v21, v31, v31
	v_fma_mix_f32 v26, v7, s92, v19 op_sel_hi:[0,0,1]
	v_fma_mix_f32 v28, v7, s92, v18 op_sel_hi:[0,0,1]
	v_mul_f32_e32 v18, v29, v29
	v_mul_f32_e32 v19, v27, v27
	v_fmac_f32_e32 v4, v24, v24
	v_fmac_f32_e32 v5, v22, v22
	v_fmac_f32_e32 v20, v32, v32
	v_fmac_f32_e32 v21, v30, v30
	v_fmac_f32_e32 v18, v28, v28
	v_fmac_f32_e32 v19, v26, v26
	v_add_f32_e32 v4, v4, v5
	v_mov_b32_dpp v5, v83 quad_perm:[1,0,3,2] row_mask:0xf bank_mask:0xf
	v_add_f32_e32 v20, v20, v21
	v_add_f32_e32 v18, v18, v19
	v_mov_b32_dpp v92, v84 quad_perm:[1,0,3,2] row_mask:0xf bank_mask:0xf
	v_add_f32_e32 v18, v20, v18
	v_fma_mix_f32 v19, v7, s92, v3 op_sel:[0,0,1] op_sel_hi:[0,0,1]
	v_fma_mix_f32 v21, v7, s92, v2 op_sel:[0,0,1] op_sel_hi:[0,0,1]
	v_add_f32_e32 v4, v4, v18
	v_fma_mix_f32 v18, v7, s92, v3 op_sel_hi:[0,0,1]
	v_fma_mix_f32 v20, v7, s92, v2 op_sel_hi:[0,0,1]
	v_mul_f32_e32 v2, v21, v21
	v_mul_f32_e32 v3, v19, v19
	v_fmac_f32_e32 v2, v20, v20
	v_fmac_f32_e32 v3, v18, v18
	v_add_f32_e32 v2, v2, v3
	s_waitcnt lgkmcnt(0)
	v_add_f32_e32 v3, v83, v5
	v_add_f32_e32 v2, v2, v4
	s_waitcnt lgkmcnt(0)
	v_add_f32_e32 v5, v84, v92
	v_mov_b32_dpp v84, v3 quad_perm:[2,3,0,1] row_mask:0xf bank_mask:0xf
	v_mov_b32_dpp v4, v85 quad_perm:[1,0,3,2] row_mask:0xf bank_mask:0xf
	v_mov_b32_dpp v83, v2 quad_perm:[1,0,3,2] row_mask:0xf bank_mask:0xf
	v_mov_b32_dpp v92, v5 quad_perm:[2,3,0,1] row_mask:0xf bank_mask:0xf
	s_waitcnt lgkmcnt(0)
	v_add_f32_e32 v3, v3, v84
	s_waitcnt lgkmcnt(0)
	v_add_f32_e32 v4, v85, v4
	s_waitcnt lgkmcnt(0)
	v_add_f32_e32 v2, v2, v83
	v_mov_b32_dpp v83, v3 row_half_mirror row_mask:0xf bank_mask:0xf
	v_mov_b32_dpp v85, v4 quad_perm:[2,3,0,1] row_mask:0xf bank_mask:0xf
	s_waitcnt lgkmcnt(0)
	v_add_f32_e32 v5, v5, v92
	v_mov_b32_dpp v84, v2 quad_perm:[2,3,0,1] row_mask:0xf bank_mask:0xf
	s_waitcnt lgkmcnt(0)
	v_add_f32_e32 v3, v3, v83
	s_waitcnt lgkmcnt(0)
	v_add_f32_e32 v4, v4, v85
	v_mov_b32_dpp v83, v3 row_mirror row_mask:0xf bank_mask:0xf
	v_mov_b32_dpp v85, v5 row_half_mirror row_mask:0xf bank_mask:0xf
	v_mov_b32_dpp v92, v4 row_half_mirror row_mask:0xf bank_mask:0xf
	s_waitcnt lgkmcnt(0)
	v_add_f32_e32 v2, v2, v84
	s_nop 1
	v_mov_b32_dpp v84, v2 row_half_mirror row_mask:0xf bank_mask:0xf
	s_waitcnt lgkmcnt(0)
	v_add_f32_e32 v3, v3, v83
	s_waitcnt lgkmcnt(0)
	v_add_f32_e32 v5, v5, v85
	s_waitcnt lgkmcnt(0)
	v_add_f32_e32 v4, v4, v92
	ds_bpermute_b32 v92, v89, v3
	v_mov_b32_dpp v83, v5 row_mirror row_mask:0xf bank_mask:0xf
	s_waitcnt lgkmcnt(0)
	v_add_f32_e32 v2, v2, v84
	s_nop 1
	v_mov_b32_dpp v84, v2 row_mirror row_mask:0xf bank_mask:0xf
	v_mov_b32_dpp v85, v4 row_mirror row_mask:0xf bank_mask:0xf
	s_waitcnt lgkmcnt(0)
	v_add_f32_e32 v3, v3, v92
	s_waitcnt lgkmcnt(0)
	v_add_f32_e32 v5, v5, v83
	ds_bpermute_b32 v83, v90, v3
	s_waitcnt lgkmcnt(0)
	v_add_f32_e32 v2, v2, v84
	s_waitcnt lgkmcnt(0)
	v_add_f32_e32 v4, v4, v85
	ds_bpermute_b32 v92, v89, v2
	ds_bpermute_b32 v85, v89, v4
	s_waitcnt lgkmcnt(0)
	v_add_f32_e32 v3, v3, v83
	v_fmamk_f32 v3, v3, 0x3a800000, v193
	v_mul_f32_e32 v83, 0x4f800000, v3
	v_cmp_gt_f32_e32 vcc, s2, v3
	ds_bpermute_b32 v84, v89, v5
	s_waitcnt lgkmcnt(0)
	v_add_f32_e32 v92, v2, v92
	v_cndmask_b32_e32 v3, v3, v83, vcc
	v_sqrt_f32_e32 v83, v3
	s_waitcnt lgkmcnt(0)
	v_add_f32_e32 v95, v4, v85
	s_waitcnt lgkmcnt(0)
	v_add_f32_e32 v97, v5, v84
	ds_bpermute_b32 v98, v90, v97
	v_add_u32_e32 v2, -1, v83
	v_fma_f32 v4, -v2, v83, v3
	v_cmp_ge_f32_e64 s[0:1], 0, v4
	v_add_u32_e32 v4, 1, v83
	v_fma_f32 v5, -v4, v83, v3
	v_cndmask_b32_e64 v2, v83, v2, s[0:1]
	v_cmp_lt_f32_e64 s[0:1], 0, v5
	ds_bpermute_b32 v96, v90, v95
	ds_bpermute_b32 v93, v90, v92
	v_cndmask_b32_e64 v2, v2, v4, s[0:1]
	v_mul_f32_e32 v4, 0x37800000, v2
	v_cndmask_b32_e32 v2, v2, v4, vcc
	v_cmp_class_f32_e32 vcc, v3, v197
	s_nop 1
	v_cndmask_b32_e32 v2, v2, v3, vcc
	v_div_scale_f32 v3, s[0:1], v2, v2, 1.0
	v_rcp_f32_e32 v4, v3
	s_nop 0
	v_fma_f32 v5, -v3, v4, 1.0
	v_fmac_f32_e32 v4, v5, v4
	v_div_scale_f32 v5, vcc, 1.0, v2, 1.0
	v_mul_f32_e32 v83, v5, v4
	v_fma_f32 v84, -v3, v83, v5
	v_fmac_f32_e32 v83, v84, v4
	v_fma_f32 v3, -v3, v83, v5
	v_div_fmas_f32 v3, v3, v4, v83
	v_div_fixup_f32 v84, v3, v2, 1.0
	s_and_saveexec_b64 s[0:1], s[40:41]
	s_cbranch_execz .LBB0_633
; template <int NR>
; __device__ __forceinline__ void ln_rows(const _Float16* z, bf16* xb, float* st, float* outf, int m0, int stride, const float* g, const float* b, int lane, bool final_out) {
;     ...
;         if (!final_out && lane == 0) *(f32x2*)(st + 2 * (size_t)m) = (f32x2){mean[r], rstd};
	s_lshl_b64 s[60:61], s[4:5], 3
	s_add_u32 s60, s56, s60
	s_addc_u32 s61, s57, s61
	v_mul_f32_e32 v2, 0x3a800000, v82
	v_mov_b32_e32 v3, v84
	v_mov_b64_e32 v[4:5], s[60:61]
	flat_store_dwordx2 v[4:5], v[2:3]
